# v14: + nt (non-temporal) on once-read prologue f32 weight loads and compression partial-sum loads
# speedup vs baseline: 1.0330x; 1.0064x over previous
.LBB0_49:
	v_and_b32_e32 v1, 31, v0
	v_add_u32_e32 v4, s23, v1
	v_bfe_u32 v104, v0, 5, 1
	v_ashrrev_i32_e32 v5, 31, v4
	v_cmp_le_i32_e32 vcc, s5, v4
	v_cmp_gt_i32_e64 s[6:7], s5, v4
	v_add_u32_e32 v100, s12, v104
	v_lshl_add_u64 v[98:99], v[4:5], 2, v[2:3]
	v_mov_b32_e32 v35, 0
	v_mov_b32_e32 v34, 0
	s_and_saveexec_b64 s[18:19], s[6:7]
	s_cbranch_execz .LBB0_51
	v_mad_u64_u32 v[2:3], s[6:7], v100, s5, 0
	v_ashrrev_i32_e32 v5, 31, v100
	v_mov_b32_e32 v4, v3
	v_mad_u64_u32 v[4:5], s[6:7], v5, s5, v[4:5]
	v_mov_b32_e32 v3, v4
	v_add_u32_e32 v4, 2, v100
	v_ashrrev_i32_e32 v7, 31, v4
	v_mad_u64_u32 v[4:5], s[6:7], v4, s5, 0
	v_mov_b32_e32 v6, v5
	v_mad_u64_u32 v[6:7], s[6:7], v7, s5, v[6:7]
	v_lshl_add_u64 v[2:3], v[2:3], 2, v[98:99]
	v_mov_b32_e32 v5, v6
	v_lshl_add_u64 v[4:5], v[4:5], 2, v[98:99]
	global_load_dword v34, v[2:3], off nt
	global_load_dword v35, v[4:5], off nt

.LBB0_54:
	v_add_u32_e32 v2, 4, v100
	v_ashrrev_i32_e32 v5, 31, v2
	v_mad_u64_u32 v[2:3], s[18:19], v2, s5, 0
	v_mov_b32_e32 v4, v3
	v_mad_u64_u32 v[4:5], s[18:19], v5, s5, v[4:5]
	v_mov_b32_e32 v3, v4
	v_add_u32_e32 v4, 6, v100
	v_ashrrev_i32_e32 v7, 31, v4
	v_mad_u64_u32 v[4:5], s[18:19], v4, s5, 0
	v_mov_b32_e32 v6, v5
	v_mad_u64_u32 v[6:7], s[18:19], v7, s5, v[6:7]
	v_lshl_add_u64 v[2:3], v[2:3], 2, v[98:99]
	v_mov_b32_e32 v5, v6
	v_lshl_add_u64 v[4:5], v[4:5], 2, v[98:99]
	global_load_dword v36, v[2:3], off nt
	global_load_dword v66, v[4:5], off nt
	s_waitcnt vmcnt(1)
	v_mov_b64_e32 v[2:3], v[34:35]
	v_mov_b64_e32 v[4:5], v[36:37]
	v_mov_b64_e32 v[6:7], v[38:39]
	v_mov_b64_e32 v[8:9], v[40:41]
	v_mov_b64_e32 v[10:11], v[42:43]
	v_mov_b64_e32 v[12:13], v[44:45]
	v_mov_b64_e32 v[14:15], v[46:47]
	v_mov_b64_e32 v[16:17], v[48:49]
	v_mov_b64_e32 v[18:19], v[50:51]
	v_mov_b64_e32 v[20:21], v[52:53]
	v_mov_b64_e32 v[22:23], v[54:55]
	v_mov_b64_e32 v[24:25], v[56:57]
	v_mov_b64_e32 v[26:27], v[58:59]
	v_mov_b64_e32 v[28:29], v[60:61]
	v_mov_b64_e32 v[30:31], v[62:63]
	v_mov_b64_e32 v[32:33], v[64:65]
	s_waitcnt vmcnt(0)
	v_mov_b32_e32 v5, v66

.LBB0_58:
	v_add_u32_e32 v6, 8, v100
	s_waitcnt vmcnt(0)
	v_mad_u64_u32 v[34:35], s[18:19], v6, s5, 0
	v_ashrrev_i32_e32 v36, 31, v6
	v_mov_b32_e32 v6, v35
	v_mad_u64_u32 v[36:37], s[18:19], v36, s5, v[6:7]
	v_add_u32_e32 v6, 10, v100
	v_mov_b32_e32 v35, v36
	v_mad_u64_u32 v[36:37], s[18:19], v6, s5, 0
	v_ashrrev_i32_e32 v38, 31, v6
	v_mov_b32_e32 v6, v37
	v_mad_u64_u32 v[38:39], s[18:19], v38, s5, v[6:7]
	v_lshl_add_u64 v[34:35], v[34:35], 2, v[98:99]
	v_mov_b32_e32 v37, v38
	v_lshl_add_u64 v[36:37], v[36:37], 2, v[98:99]
	global_load_dword v6, v[34:35], off nt
	global_load_dword v66, v[36:37], off nt
	s_waitcnt vmcnt(1)
	v_mov_b64_e32 v[64:65], v[32:33]
	v_mov_b64_e32 v[38:39], v[6:7]
	v_mov_b64_e32 v[62:63], v[30:31]
	v_mov_b64_e32 v[60:61], v[28:29]
	v_mov_b64_e32 v[58:59], v[26:27]
	v_mov_b64_e32 v[56:57], v[24:25]
	v_mov_b64_e32 v[54:55], v[22:23]
	v_mov_b64_e32 v[52:53], v[20:21]
	v_mov_b64_e32 v[50:51], v[18:19]
	v_mov_b64_e32 v[48:49], v[16:17]
	v_mov_b64_e32 v[46:47], v[14:15]
	v_mov_b64_e32 v[44:45], v[12:13]
	v_mov_b64_e32 v[42:43], v[10:11]
	v_mov_b64_e32 v[40:41], v[8:9]
	v_mov_b64_e32 v[36:37], v[4:5]
	v_mov_b64_e32 v[34:35], v[2:3]
	s_waitcnt vmcnt(0)
	v_mov_b32_e32 v39, v66

.LBB0_62:
	v_add_u32_e32 v2, 12, v100
	v_ashrrev_i32_e32 v5, 31, v2
	v_mad_u64_u32 v[2:3], s[18:19], v2, s5, 0
	v_mov_b32_e32 v4, v3
	v_mad_u64_u32 v[4:5], s[18:19], v5, s5, v[4:5]
	v_mov_b32_e32 v3, v4
	v_add_u32_e32 v4, 14, v100
	v_ashrrev_i32_e32 v7, 31, v4
	v_mad_u64_u32 v[4:5], s[18:19], v4, s5, 0
	v_mov_b32_e32 v6, v5
	v_mad_u64_u32 v[6:7], s[18:19], v7, s5, v[6:7]
	v_lshl_add_u64 v[2:3], v[2:3], 2, v[98:99]
	v_mov_b32_e32 v5, v6
	v_lshl_add_u64 v[4:5], v[4:5], 2, v[98:99]
	global_load_dword v40, v[2:3], off nt
	global_load_dword v66, v[4:5], off nt
	s_waitcnt vmcnt(1)
	v_mov_b64_e32 v[2:3], v[34:35]
	v_mov_b64_e32 v[8:9], v[40:41]
	v_mov_b64_e32 v[4:5], v[36:37]
	v_mov_b64_e32 v[6:7], v[38:39]
	v_mov_b64_e32 v[10:11], v[42:43]
	v_mov_b64_e32 v[12:13], v[44:45]
	v_mov_b64_e32 v[14:15], v[46:47]
	v_mov_b64_e32 v[16:17], v[48:49]
	v_mov_b64_e32 v[18:19], v[50:51]
	v_mov_b64_e32 v[20:21], v[52:53]
	v_mov_b64_e32 v[22:23], v[54:55]
	v_mov_b64_e32 v[24:25], v[56:57]
	v_mov_b64_e32 v[26:27], v[58:59]
	v_mov_b64_e32 v[28:29], v[60:61]
	v_mov_b64_e32 v[30:31], v[62:63]
	v_mov_b64_e32 v[32:33], v[64:65]
	s_waitcnt vmcnt(0)
	v_mov_b32_e32 v9, v66

.LBB0_66:
	v_add_u32_e32 v10, 16, v100
	s_waitcnt vmcnt(0)
	v_mad_u64_u32 v[34:35], s[18:19], v10, s5, 0
	v_ashrrev_i32_e32 v36, 31, v10
	v_mov_b32_e32 v10, v35
	v_mad_u64_u32 v[36:37], s[18:19], v36, s5, v[10:11]
	v_add_u32_e32 v10, 18, v100
	v_mov_b32_e32 v35, v36
	v_mad_u64_u32 v[36:37], s[18:19], v10, s5, 0
	v_ashrrev_i32_e32 v38, 31, v10
	v_mov_b32_e32 v10, v37
	v_mad_u64_u32 v[38:39], s[18:19], v38, s5, v[10:11]
	v_lshl_add_u64 v[34:35], v[34:35], 2, v[98:99]
	v_mov_b32_e32 v37, v38
	v_lshl_add_u64 v[36:37], v[36:37], 2, v[98:99]
	global_load_dword v10, v[34:35], off nt
	global_load_dword v66, v[36:37], off nt
	s_waitcnt vmcnt(1)
	v_mov_b64_e32 v[64:65], v[32:33]
	v_mov_b64_e32 v[42:43], v[10:11]
	v_mov_b64_e32 v[62:63], v[30:31]
	v_mov_b64_e32 v[60:61], v[28:29]
	v_mov_b64_e32 v[58:59], v[26:27]
	v_mov_b64_e32 v[56:57], v[24:25]
	v_mov_b64_e32 v[54:55], v[22:23]
	v_mov_b64_e32 v[52:53], v[20:21]
	v_mov_b64_e32 v[50:51], v[18:19]
	v_mov_b64_e32 v[48:49], v[16:17]
	v_mov_b64_e32 v[46:47], v[14:15]
	v_mov_b64_e32 v[44:45], v[12:13]
	v_mov_b64_e32 v[40:41], v[8:9]
	v_mov_b64_e32 v[38:39], v[6:7]
	v_mov_b64_e32 v[36:37], v[4:5]
	v_mov_b64_e32 v[34:35], v[2:3]
	s_waitcnt vmcnt(0)
	v_mov_b32_e32 v43, v66

.LBB0_70:
	v_add_u32_e32 v2, 20, v100
	v_ashrrev_i32_e32 v5, 31, v2
	v_mad_u64_u32 v[2:3], s[18:19], v2, s5, 0
	v_mov_b32_e32 v4, v3
	v_mad_u64_u32 v[4:5], s[18:19], v5, s5, v[4:5]
	v_mov_b32_e32 v3, v4
	v_add_u32_e32 v4, 22, v100
	v_ashrrev_i32_e32 v7, 31, v4
	v_mad_u64_u32 v[4:5], s[18:19], v4, s5, 0
	v_mov_b32_e32 v6, v5
	v_mad_u64_u32 v[6:7], s[18:19], v7, s5, v[6:7]
	v_lshl_add_u64 v[2:3], v[2:3], 2, v[98:99]
	v_mov_b32_e32 v5, v6
	v_lshl_add_u64 v[4:5], v[4:5], 2, v[98:99]
	global_load_dword v44, v[2:3], off nt
	global_load_dword v66, v[4:5], off nt
	s_waitcnt vmcnt(1)
	v_mov_b64_e32 v[2:3], v[34:35]
	v_mov_b64_e32 v[12:13], v[44:45]
	v_mov_b64_e32 v[4:5], v[36:37]
	v_mov_b64_e32 v[6:7], v[38:39]
	v_mov_b64_e32 v[8:9], v[40:41]
	v_mov_b64_e32 v[10:11], v[42:43]
	v_mov_b64_e32 v[14:15], v[46:47]
	v_mov_b64_e32 v[16:17], v[48:49]
	v_mov_b64_e32 v[18:19], v[50:51]
	v_mov_b64_e32 v[20:21], v[52:53]
	v_mov_b64_e32 v[22:23], v[54:55]
	v_mov_b64_e32 v[24:25], v[56:57]
	v_mov_b64_e32 v[26:27], v[58:59]
	v_mov_b64_e32 v[28:29], v[60:61]
	v_mov_b64_e32 v[30:31], v[62:63]
	v_mov_b64_e32 v[32:33], v[64:65]
	s_waitcnt vmcnt(0)
	v_mov_b32_e32 v13, v66

.LBB0_74:
	v_add_u32_e32 v14, 24, v100
	s_waitcnt vmcnt(0)
	v_mad_u64_u32 v[34:35], s[18:19], v14, s5, 0
	v_ashrrev_i32_e32 v36, 31, v14
	v_mov_b32_e32 v14, v35
	v_mad_u64_u32 v[36:37], s[18:19], v36, s5, v[14:15]
	v_add_u32_e32 v14, 26, v100
	v_mov_b32_e32 v35, v36
	v_mad_u64_u32 v[36:37], s[18:19], v14, s5, 0
	v_ashrrev_i32_e32 v38, 31, v14
	v_mov_b32_e32 v14, v37
	v_mad_u64_u32 v[38:39], s[18:19], v38, s5, v[14:15]
	v_lshl_add_u64 v[34:35], v[34:35], 2, v[98:99]
	v_mov_b32_e32 v37, v38
	v_lshl_add_u64 v[36:37], v[36:37], 2, v[98:99]
	global_load_dword v14, v[34:35], off nt
	global_load_dword v66, v[36:37], off nt
	s_waitcnt vmcnt(1)
	v_mov_b64_e32 v[64:65], v[32:33]
	v_mov_b64_e32 v[46:47], v[14:15]
	v_mov_b64_e32 v[62:63], v[30:31]
	v_mov_b64_e32 v[60:61], v[28:29]
	v_mov_b64_e32 v[58:59], v[26:27]
	v_mov_b64_e32 v[56:57], v[24:25]
	v_mov_b64_e32 v[54:55], v[22:23]
	v_mov_b64_e32 v[52:53], v[20:21]
	v_mov_b64_e32 v[50:51], v[18:19]
	v_mov_b64_e32 v[48:49], v[16:17]
	v_mov_b64_e32 v[44:45], v[12:13]
	v_mov_b64_e32 v[42:43], v[10:11]
	v_mov_b64_e32 v[40:41], v[8:9]
	v_mov_b64_e32 v[38:39], v[6:7]
	v_mov_b64_e32 v[36:37], v[4:5]
	v_mov_b64_e32 v[34:35], v[2:3]
	s_waitcnt vmcnt(0)
	v_mov_b32_e32 v47, v66

.LBB0_78:
	v_add_u32_e32 v2, 28, v100
	v_ashrrev_i32_e32 v5, 31, v2
	v_mad_u64_u32 v[2:3], s[18:19], v2, s5, 0
	v_mov_b32_e32 v4, v3
	v_mad_u64_u32 v[4:5], s[18:19], v5, s5, v[4:5]
	v_mov_b32_e32 v3, v4
	v_add_u32_e32 v4, 30, v100
	v_ashrrev_i32_e32 v7, 31, v4
	v_mad_u64_u32 v[4:5], s[18:19], v4, s5, 0
	v_mov_b32_e32 v6, v5
	v_mad_u64_u32 v[6:7], s[18:19], v7, s5, v[6:7]
	v_lshl_add_u64 v[2:3], v[2:3], 2, v[98:99]
	v_mov_b32_e32 v5, v6
	v_lshl_add_u64 v[4:5], v[4:5], 2, v[98:99]
	global_load_dword v48, v[2:3], off nt
	global_load_dword v66, v[4:5], off nt
	s_waitcnt vmcnt(1)
	v_mov_b64_e32 v[2:3], v[34:35]
	v_mov_b64_e32 v[16:17], v[48:49]
	v_mov_b64_e32 v[4:5], v[36:37]
	v_mov_b64_e32 v[6:7], v[38:39]
	v_mov_b64_e32 v[8:9], v[40:41]
	v_mov_b64_e32 v[10:11], v[42:43]
	v_mov_b64_e32 v[12:13], v[44:45]
	v_mov_b64_e32 v[14:15], v[46:47]
	v_mov_b64_e32 v[18:19], v[50:51]
	v_mov_b64_e32 v[20:21], v[52:53]
	v_mov_b64_e32 v[22:23], v[54:55]
	v_mov_b64_e32 v[24:25], v[56:57]
	v_mov_b64_e32 v[26:27], v[58:59]
	v_mov_b64_e32 v[28:29], v[60:61]
	v_mov_b64_e32 v[30:31], v[62:63]
	v_mov_b64_e32 v[32:33], v[64:65]
	s_waitcnt vmcnt(0)
	v_mov_b32_e32 v17, v66

.LBB0_82:
	v_add_u32_e32 v18, 32, v100
	s_waitcnt vmcnt(0)
	v_mad_u64_u32 v[34:35], s[18:19], v18, s5, 0
	v_ashrrev_i32_e32 v36, 31, v18
	v_mov_b32_e32 v18, v35
	v_mad_u64_u32 v[36:37], s[18:19], v36, s5, v[18:19]
	v_add_u32_e32 v18, 34, v100
	v_mov_b32_e32 v35, v36
	v_mad_u64_u32 v[36:37], s[18:19], v18, s5, 0
	v_ashrrev_i32_e32 v38, 31, v18
	v_mov_b32_e32 v18, v37
	v_mad_u64_u32 v[38:39], s[18:19], v38, s5, v[18:19]
	v_lshl_add_u64 v[34:35], v[34:35], 2, v[98:99]
	v_mov_b32_e32 v37, v38
	v_lshl_add_u64 v[36:37], v[36:37], 2, v[98:99]
	global_load_dword v18, v[34:35], off nt
	global_load_dword v66, v[36:37], off nt
	s_waitcnt vmcnt(1)
	v_mov_b64_e32 v[64:65], v[32:33]
	v_mov_b64_e32 v[50:51], v[18:19]
	v_mov_b64_e32 v[62:63], v[30:31]
	v_mov_b64_e32 v[60:61], v[28:29]
	v_mov_b64_e32 v[58:59], v[26:27]
	v_mov_b64_e32 v[56:57], v[24:25]
	v_mov_b64_e32 v[54:55], v[22:23]
	v_mov_b64_e32 v[52:53], v[20:21]
	v_mov_b64_e32 v[48:49], v[16:17]
	v_mov_b64_e32 v[46:47], v[14:15]
	v_mov_b64_e32 v[44:45], v[12:13]
	v_mov_b64_e32 v[42:43], v[10:11]
	v_mov_b64_e32 v[40:41], v[8:9]
	v_mov_b64_e32 v[38:39], v[6:7]
	v_mov_b64_e32 v[36:37], v[4:5]
	v_mov_b64_e32 v[34:35], v[2:3]
	s_waitcnt vmcnt(0)
	v_mov_b32_e32 v51, v66

.LBB0_86:
	v_add_u32_e32 v2, 36, v100
	v_ashrrev_i32_e32 v5, 31, v2
	v_mad_u64_u32 v[2:3], s[18:19], v2, s5, 0
	v_mov_b32_e32 v4, v3
	v_mad_u64_u32 v[4:5], s[18:19], v5, s5, v[4:5]
	v_mov_b32_e32 v3, v4
	v_add_u32_e32 v4, 38, v100
	v_ashrrev_i32_e32 v7, 31, v4
	v_mad_u64_u32 v[4:5], s[18:19], v4, s5, 0
	v_mov_b32_e32 v6, v5
	v_mad_u64_u32 v[6:7], s[18:19], v7, s5, v[6:7]
	v_lshl_add_u64 v[2:3], v[2:3], 2, v[98:99]
	v_mov_b32_e32 v5, v6
	v_lshl_add_u64 v[4:5], v[4:5], 2, v[98:99]
	global_load_dword v52, v[2:3], off nt
	global_load_dword v66, v[4:5], off nt
	s_waitcnt vmcnt(1)
	v_mov_b64_e32 v[2:3], v[34:35]
	v_mov_b64_e32 v[20:21], v[52:53]
	v_mov_b64_e32 v[4:5], v[36:37]
	v_mov_b64_e32 v[6:7], v[38:39]
	v_mov_b64_e32 v[8:9], v[40:41]
	v_mov_b64_e32 v[10:11], v[42:43]
	v_mov_b64_e32 v[12:13], v[44:45]
	v_mov_b64_e32 v[14:15], v[46:47]
	v_mov_b64_e32 v[16:17], v[48:49]
	v_mov_b64_e32 v[18:19], v[50:51]
	v_mov_b64_e32 v[22:23], v[54:55]
	v_mov_b64_e32 v[24:25], v[56:57]
	v_mov_b64_e32 v[26:27], v[58:59]
	v_mov_b64_e32 v[28:29], v[60:61]
	v_mov_b64_e32 v[30:31], v[62:63]
	v_mov_b64_e32 v[32:33], v[64:65]
	s_waitcnt vmcnt(0)
	v_mov_b32_e32 v21, v66

.LBB0_90:
	v_add_u32_e32 v22, 40, v100
	s_waitcnt vmcnt(0)
	v_mad_u64_u32 v[34:35], s[18:19], v22, s5, 0
	v_ashrrev_i32_e32 v36, 31, v22
	v_mov_b32_e32 v22, v35
	v_mad_u64_u32 v[36:37], s[18:19], v36, s5, v[22:23]
	v_add_u32_e32 v22, 42, v100
	v_mov_b32_e32 v35, v36
	v_mad_u64_u32 v[36:37], s[18:19], v22, s5, 0
	v_ashrrev_i32_e32 v38, 31, v22
	v_mov_b32_e32 v22, v37
	v_mad_u64_u32 v[38:39], s[18:19], v38, s5, v[22:23]
	v_lshl_add_u64 v[34:35], v[34:35], 2, v[98:99]
	v_mov_b32_e32 v37, v38
	v_lshl_add_u64 v[36:37], v[36:37], 2, v[98:99]
	global_load_dword v22, v[34:35], off nt
	global_load_dword v66, v[36:37], off nt
	s_waitcnt vmcnt(1)
	v_mov_b64_e32 v[64:65], v[32:33]
	v_mov_b64_e32 v[54:55], v[22:23]
	v_mov_b64_e32 v[62:63], v[30:31]
	v_mov_b64_e32 v[60:61], v[28:29]
	v_mov_b64_e32 v[58:59], v[26:27]
	v_mov_b64_e32 v[56:57], v[24:25]
	v_mov_b64_e32 v[52:53], v[20:21]
	v_mov_b64_e32 v[50:51], v[18:19]
	v_mov_b64_e32 v[48:49], v[16:17]
	v_mov_b64_e32 v[46:47], v[14:15]
	v_mov_b64_e32 v[44:45], v[12:13]
	v_mov_b64_e32 v[42:43], v[10:11]
	v_mov_b64_e32 v[40:41], v[8:9]
	v_mov_b64_e32 v[38:39], v[6:7]
	v_mov_b64_e32 v[36:37], v[4:5]
	v_mov_b64_e32 v[34:35], v[2:3]
	s_waitcnt vmcnt(0)
	v_mov_b32_e32 v55, v66

.LBB0_94:
	v_add_u32_e32 v2, 44, v100
	v_ashrrev_i32_e32 v5, 31, v2
	v_mad_u64_u32 v[2:3], s[18:19], v2, s5, 0
	v_mov_b32_e32 v4, v3
	v_mad_u64_u32 v[4:5], s[18:19], v5, s5, v[4:5]
	v_mov_b32_e32 v3, v4
	v_add_u32_e32 v4, 46, v100
	v_ashrrev_i32_e32 v7, 31, v4
	v_mad_u64_u32 v[4:5], s[18:19], v4, s5, 0
	v_mov_b32_e32 v6, v5
	v_mad_u64_u32 v[6:7], s[18:19], v7, s5, v[6:7]
	v_lshl_add_u64 v[2:3], v[2:3], 2, v[98:99]
	v_mov_b32_e32 v5, v6
	v_lshl_add_u64 v[4:5], v[4:5], 2, v[98:99]
	global_load_dword v56, v[2:3], off nt
	global_load_dword v66, v[4:5], off nt
	s_waitcnt vmcnt(1)
	v_mov_b64_e32 v[2:3], v[34:35]
	v_mov_b64_e32 v[24:25], v[56:57]
	v_mov_b64_e32 v[4:5], v[36:37]
	v_mov_b64_e32 v[6:7], v[38:39]
	v_mov_b64_e32 v[8:9], v[40:41]
	v_mov_b64_e32 v[10:11], v[42:43]
	v_mov_b64_e32 v[12:13], v[44:45]
	v_mov_b64_e32 v[14:15], v[46:47]
	v_mov_b64_e32 v[16:17], v[48:49]
	v_mov_b64_e32 v[18:19], v[50:51]
	v_mov_b64_e32 v[20:21], v[52:53]
	v_mov_b64_e32 v[22:23], v[54:55]
	v_mov_b64_e32 v[26:27], v[58:59]
	v_mov_b64_e32 v[28:29], v[60:61]
	v_mov_b64_e32 v[30:31], v[62:63]
	v_mov_b64_e32 v[32:33], v[64:65]
	s_waitcnt vmcnt(0)
	v_mov_b32_e32 v25, v66

.LBB0_98:
	v_add_u32_e32 v26, 48, v100
	s_waitcnt vmcnt(0)
	v_mad_u64_u32 v[34:35], s[18:19], v26, s5, 0
	v_ashrrev_i32_e32 v36, 31, v26
	v_mov_b32_e32 v26, v35
	v_mad_u64_u32 v[36:37], s[18:19], v36, s5, v[26:27]
	v_add_u32_e32 v26, 50, v100
	v_mov_b32_e32 v35, v36
	v_mad_u64_u32 v[36:37], s[18:19], v26, s5, 0
	v_ashrrev_i32_e32 v38, 31, v26
	v_mov_b32_e32 v26, v37
	v_mad_u64_u32 v[38:39], s[18:19], v38, s5, v[26:27]
	v_lshl_add_u64 v[34:35], v[34:35], 2, v[98:99]
	v_mov_b32_e32 v37, v38
	v_lshl_add_u64 v[36:37], v[36:37], 2, v[98:99]
	global_load_dword v26, v[34:35], off nt
	global_load_dword v66, v[36:37], off nt
	s_waitcnt vmcnt(1)
	v_mov_b64_e32 v[64:65], v[32:33]
	v_mov_b64_e32 v[58:59], v[26:27]
	v_mov_b64_e32 v[62:63], v[30:31]
	v_mov_b64_e32 v[60:61], v[28:29]
	v_mov_b64_e32 v[56:57], v[24:25]
	v_mov_b64_e32 v[54:55], v[22:23]
	v_mov_b64_e32 v[52:53], v[20:21]
	v_mov_b64_e32 v[50:51], v[18:19]
	v_mov_b64_e32 v[48:49], v[16:17]
	v_mov_b64_e32 v[46:47], v[14:15]
	v_mov_b64_e32 v[44:45], v[12:13]
	v_mov_b64_e32 v[42:43], v[10:11]
	v_mov_b64_e32 v[40:41], v[8:9]
	v_mov_b64_e32 v[38:39], v[6:7]
	v_mov_b64_e32 v[36:37], v[4:5]
	v_mov_b64_e32 v[34:35], v[2:3]
	s_waitcnt vmcnt(0)
	v_mov_b32_e32 v59, v66

.LBB0_102:
	v_add_u32_e32 v2, 52, v100
	v_ashrrev_i32_e32 v5, 31, v2
	v_mad_u64_u32 v[2:3], s[18:19], v2, s5, 0
	v_mov_b32_e32 v4, v3
	v_mad_u64_u32 v[4:5], s[18:19], v5, s5, v[4:5]
	v_mov_b32_e32 v3, v4
	v_add_u32_e32 v4, 54, v100
	v_ashrrev_i32_e32 v7, 31, v4
	v_mad_u64_u32 v[4:5], s[18:19], v4, s5, 0
	v_mov_b32_e32 v6, v5
	v_mad_u64_u32 v[6:7], s[18:19], v7, s5, v[6:7]
	v_lshl_add_u64 v[2:3], v[2:3], 2, v[98:99]
	v_mov_b32_e32 v5, v6
	v_lshl_add_u64 v[4:5], v[4:5], 2, v[98:99]
	global_load_dword v60, v[2:3], off nt
	global_load_dword v6, v[4:5], off nt
	s_waitcnt vmcnt(1)
	v_mov_b64_e32 v[96:97], v[64:65]
	v_mov_b64_e32 v[92:93], v[60:61]
	v_mov_b64_e32 v[94:95], v[62:63]
	v_mov_b64_e32 v[90:91], v[58:59]
	v_mov_b64_e32 v[88:89], v[56:57]
	v_mov_b64_e32 v[86:87], v[54:55]
	v_mov_b64_e32 v[84:85], v[52:53]
	v_mov_b64_e32 v[82:83], v[50:51]
	v_mov_b64_e32 v[80:81], v[48:49]
	v_mov_b64_e32 v[78:79], v[46:47]
	v_mov_b64_e32 v[76:77], v[44:45]
	v_mov_b64_e32 v[74:75], v[42:43]
	v_mov_b64_e32 v[72:73], v[40:41]
	v_mov_b64_e32 v[70:71], v[38:39]
	v_mov_b64_e32 v[68:69], v[36:37]
	v_mov_b64_e32 v[66:67], v[34:35]
	s_waitcnt vmcnt(0)
	v_mov_b32_e32 v93, v6

.LBB0_108:
	v_add_u32_e32 v2, 56, v100
	v_ashrrev_i32_e32 v5, 31, v2
	v_mad_u64_u32 v[2:3], s[18:19], v2, s5, 0
	v_mov_b32_e32 v4, v3
	v_mad_u64_u32 v[4:5], s[18:19], v5, s5, v[4:5]
	v_mov_b32_e32 v3, v4
	v_add_u32_e32 v4, 58, v100
	v_ashrrev_i32_e32 v7, 31, v4
	v_mad_u64_u32 v[4:5], s[18:19], v4, s5, 0
	v_mov_b32_e32 v6, v5
	v_mad_u64_u32 v[6:7], s[18:19], v7, s5, v[6:7]
	v_lshl_add_u64 v[2:3], v[2:3], 2, v[98:99]
	v_mov_b32_e32 v5, v6
	v_lshl_add_u64 v[4:5], v[4:5], 2, v[98:99]
	global_load_dword v94, v[2:3], off nt
	global_load_dword v34, v[4:5], off nt
	s_waitcnt vmcnt(1)
	v_mov_b64_e32 v[2:3], v[66:67]
	v_mov_b64_e32 v[30:31], v[94:95]
	v_mov_b64_e32 v[4:5], v[68:69]
	v_mov_b64_e32 v[6:7], v[70:71]
	v_mov_b64_e32 v[8:9], v[72:73]
	v_mov_b64_e32 v[10:11], v[74:75]
	v_mov_b64_e32 v[12:13], v[76:77]
	v_mov_b64_e32 v[14:15], v[78:79]
	v_mov_b64_e32 v[16:17], v[80:81]
	v_mov_b64_e32 v[18:19], v[82:83]
	v_mov_b64_e32 v[20:21], v[84:85]
	v_mov_b64_e32 v[22:23], v[86:87]
	v_mov_b64_e32 v[24:25], v[88:89]
	v_mov_b64_e32 v[26:27], v[90:91]
	v_mov_b64_e32 v[28:29], v[92:93]
	v_mov_b64_e32 v[32:33], v[96:97]
	s_waitcnt vmcnt(0)
	v_mov_b32_e32 v31, v34
	s_or_b64 exec, exec, s[6:7]
	s_and_saveexec_b64 s[6:7], vcc
	s_xor_b64 s[6:7], exec, s[6:7]
	s_cbranch_execnz .LBB0_106

.LBB0_110:
	v_add_u32_e32 v32, 60, v100
	s_waitcnt vmcnt(0)
	v_ashrrev_i32_e32 v35, 31, v32
	v_mad_u64_u32 v[32:33], s[18:19], v32, s5, 0
	v_mov_b32_e32 v34, v33
	v_mad_u64_u32 v[34:35], s[18:19], v35, s5, v[34:35]
	v_mov_b32_e32 v33, v34
	v_lshl_add_u64 v[34:35], v[32:33], 2, v[98:99]
	v_add_u32_e32 v32, 62, v100
	v_ashrrev_i32_e32 v37, 31, v32
	v_mad_u64_u32 v[32:33], s[18:19], v32, s5, 0
	v_mov_b32_e32 v36, v33
	v_mad_u64_u32 v[36:37], s[18:19], v37, s5, v[36:37]
	v_mov_b32_e32 v33, v36
	v_lshl_add_u64 v[36:37], v[32:33], 2, v[98:99]
	global_load_dword v32, v[34:35], off nt
	global_load_dword v33, v[36:37], off nt

.LBB0_145:
	v_add_u32_e32 v38, s37, v1
	v_ashrrev_i32_e32 v39, 31, v38
	v_cmp_gt_i32_e32 vcc, s27, v38
	v_add_u32_e32 v36, s26, v104
	v_lshl_add_u64 v[34:35], v[38:39], 2, v[34:35]
	s_waitcnt vmcnt(5)
	v_mov_b32_e32 v114, 0
	v_mov_b32_e32 v115, 0
	s_waitcnt vmcnt(4)
	v_mov_b32_e32 v116, 0
	s_and_saveexec_b64 s[38:39], vcc
	s_cbranch_execz .LBB0_147
	v_mad_u64_u32 v[38:39], s[36:37], v36, s27, 0
	v_ashrrev_i32_e32 v37, 31, v36
	v_mov_b32_e32 v40, v39
	v_mad_u64_u32 v[40:41], s[36:37], v37, s27, v[40:41]
	v_add_u32_e32 v37, 2, v36
	v_mov_b32_e32 v39, v40
	v_mad_u64_u32 v[40:41], s[36:37], v37, s27, 0
	v_ashrrev_i32_e32 v43, 31, v37
	v_mov_b32_e32 v42, v41
	v_mad_u64_u32 v[42:43], s[36:37], v43, s27, v[42:43]
	v_lshl_add_u64 v[38:39], v[38:39], 2, v[34:35]
	v_mov_b32_e32 v41, v42
	v_lshl_add_u64 v[40:41], v[40:41], 2, v[34:35]
	global_load_dword v115, v[38:39], off nt
	global_load_dword v116, v[40:41], off nt
.LBB0_147:
	s_or_b64 exec, exec, s[38:39]
	v_mov_b32_e32 v117, 0
	s_and_saveexec_b64 s[38:39], vcc
	s_cbranch_execz .LBB0_149
	v_add_u32_e32 v37, 4, v36
	v_mad_u64_u32 v[38:39], s[36:37], v37, s27, 0
	v_ashrrev_i32_e32 v41, 31, v37
	v_mov_b32_e32 v40, v39
	v_mad_u64_u32 v[40:41], s[36:37], v41, s27, v[40:41]
	v_add_u32_e32 v37, 6, v36
	v_mov_b32_e32 v39, v40
	v_mad_u64_u32 v[40:41], s[36:37], v37, s27, 0
	v_ashrrev_i32_e32 v43, 31, v37
	v_mov_b32_e32 v42, v41
	v_mad_u64_u32 v[42:43], s[36:37], v43, s27, v[42:43]
	v_lshl_add_u64 v[38:39], v[38:39], 2, v[34:35]
	v_mov_b32_e32 v41, v42
	v_lshl_add_u64 v[40:41], v[40:41], 2, v[34:35]
	global_load_dword v114, v[38:39], off nt
	global_load_dword v117, v[40:41], off nt
.LBB0_149:
	s_or_b64 exec, exec, s[38:39]
	v_mov_b32_e32 v118, 0
	v_mov_b32_e32 v119, 0
	v_mov_b32_e32 v120, 0
	s_and_saveexec_b64 s[38:39], vcc
	s_cbranch_execz .LBB0_151
	v_add_u32_e32 v37, 8, v36
	v_mad_u64_u32 v[38:39], s[36:37], v37, s27, 0
	v_ashrrev_i32_e32 v41, 31, v37
	v_mov_b32_e32 v40, v39
	v_mad_u64_u32 v[40:41], s[36:37], v41, s27, v[40:41]
	v_add_u32_e32 v37, 10, v36
	v_mov_b32_e32 v39, v40
	v_mad_u64_u32 v[40:41], s[36:37], v37, s27, 0
	v_ashrrev_i32_e32 v43, 31, v37
	v_mov_b32_e32 v42, v41
	v_mad_u64_u32 v[42:43], s[36:37], v43, s27, v[42:43]
	v_lshl_add_u64 v[38:39], v[38:39], 2, v[34:35]
	v_mov_b32_e32 v41, v42
	v_lshl_add_u64 v[40:41], v[40:41], 2, v[34:35]
	global_load_dword v119, v[38:39], off nt
	global_load_dword v120, v[40:41], off nt
.LBB0_151:
	s_or_b64 exec, exec, s[38:39]
	v_mov_b32_e32 v121, 0
	s_and_saveexec_b64 s[38:39], vcc
	s_cbranch_execz .LBB0_153
	v_add_u32_e32 v37, 12, v36
	v_mad_u64_u32 v[38:39], s[36:37], v37, s27, 0
	v_ashrrev_i32_e32 v41, 31, v37
	v_mov_b32_e32 v40, v39
	v_mad_u64_u32 v[40:41], s[36:37], v41, s27, v[40:41]
	v_add_u32_e32 v37, 14, v36
	v_mov_b32_e32 v39, v40
	v_mad_u64_u32 v[40:41], s[36:37], v37, s27, 0
	v_ashrrev_i32_e32 v43, 31, v37
	v_mov_b32_e32 v42, v41
	v_mad_u64_u32 v[42:43], s[36:37], v43, s27, v[42:43]
	v_lshl_add_u64 v[38:39], v[38:39], 2, v[34:35]
	v_mov_b32_e32 v41, v42
	v_lshl_add_u64 v[40:41], v[40:41], 2, v[34:35]
	global_load_dword v118, v[38:39], off nt
	global_load_dword v121, v[40:41], off nt
.LBB0_153:
	s_or_b64 exec, exec, s[38:39]
	v_mov_b32_e32 v122, 0
	v_mov_b32_e32 v123, 0
	v_mov_b32_e32 v124, 0
	s_and_saveexec_b64 s[38:39], vcc
	s_cbranch_execz .LBB0_155
	v_add_u32_e32 v37, 16, v36
	v_mad_u64_u32 v[38:39], s[36:37], v37, s27, 0
	v_ashrrev_i32_e32 v41, 31, v37
	v_mov_b32_e32 v40, v39
	v_mad_u64_u32 v[40:41], s[36:37], v41, s27, v[40:41]
	v_add_u32_e32 v37, 18, v36
	v_mov_b32_e32 v39, v40
	v_mad_u64_u32 v[40:41], s[36:37], v37, s27, 0
	v_ashrrev_i32_e32 v43, 31, v37
	v_mov_b32_e32 v42, v41
	v_mad_u64_u32 v[42:43], s[36:37], v43, s27, v[42:43]
	v_lshl_add_u64 v[38:39], v[38:39], 2, v[34:35]
	v_mov_b32_e32 v41, v42
	v_lshl_add_u64 v[40:41], v[40:41], 2, v[34:35]
	global_load_dword v123, v[38:39], off nt
	global_load_dword v124, v[40:41], off nt
.LBB0_155:
	s_or_b64 exec, exec, s[38:39]
	v_mov_b32_e32 v125, 0
	s_and_saveexec_b64 s[38:39], vcc
	s_cbranch_execz .LBB0_157
	v_add_u32_e32 v37, 20, v36
	v_mad_u64_u32 v[38:39], s[36:37], v37, s27, 0
	v_ashrrev_i32_e32 v41, 31, v37
	v_mov_b32_e32 v40, v39
	v_mad_u64_u32 v[40:41], s[36:37], v41, s27, v[40:41]
	v_add_u32_e32 v37, 22, v36
	v_mov_b32_e32 v39, v40
	v_mad_u64_u32 v[40:41], s[36:37], v37, s27, 0
	v_ashrrev_i32_e32 v43, 31, v37
	v_mov_b32_e32 v42, v41
	v_mad_u64_u32 v[42:43], s[36:37], v43, s27, v[42:43]
	v_lshl_add_u64 v[38:39], v[38:39], 2, v[34:35]
	v_mov_b32_e32 v41, v42
	v_lshl_add_u64 v[40:41], v[40:41], 2, v[34:35]
	global_load_dword v122, v[38:39], off nt
	global_load_dword v125, v[40:41], off nt
.LBB0_157:
	s_or_b64 exec, exec, s[38:39]
	v_mov_b32_e32 v126, 0
	v_mov_b32_e32 v127, 0
	v_mov_b32_e32 v128, 0
	s_and_saveexec_b64 s[38:39], vcc
	s_cbranch_execz .LBB0_159
	v_add_u32_e32 v37, 24, v36
	v_mad_u64_u32 v[38:39], s[36:37], v37, s27, 0
	v_ashrrev_i32_e32 v41, 31, v37
	v_mov_b32_e32 v40, v39
	v_mad_u64_u32 v[40:41], s[36:37], v41, s27, v[40:41]
	v_add_u32_e32 v37, 26, v36
	v_mov_b32_e32 v39, v40
	v_mad_u64_u32 v[40:41], s[36:37], v37, s27, 0
	v_ashrrev_i32_e32 v43, 31, v37
	v_mov_b32_e32 v42, v41
	v_mad_u64_u32 v[42:43], s[36:37], v43, s27, v[42:43]
	v_lshl_add_u64 v[38:39], v[38:39], 2, v[34:35]
	v_mov_b32_e32 v41, v42
	v_lshl_add_u64 v[40:41], v[40:41], 2, v[34:35]
	global_load_dword v127, v[38:39], off nt
	global_load_dword v128, v[40:41], off nt
.LBB0_159:
	s_or_b64 exec, exec, s[38:39]
	v_mov_b32_e32 v129, 0
	s_and_saveexec_b64 s[38:39], vcc
	s_cbranch_execz .LBB0_161
	v_add_u32_e32 v37, 28, v36
	v_mad_u64_u32 v[38:39], s[36:37], v37, s27, 0
	v_ashrrev_i32_e32 v41, 31, v37
	v_mov_b32_e32 v40, v39
	v_mad_u64_u32 v[40:41], s[36:37], v41, s27, v[40:41]
	v_add_u32_e32 v37, 30, v36
	v_mov_b32_e32 v39, v40
	v_mad_u64_u32 v[40:41], s[36:37], v37, s27, 0
	v_ashrrev_i32_e32 v43, 31, v37
	v_mov_b32_e32 v42, v41
	v_mad_u64_u32 v[42:43], s[36:37], v43, s27, v[42:43]
	v_lshl_add_u64 v[38:39], v[38:39], 2, v[34:35]
	v_mov_b32_e32 v41, v42
	v_lshl_add_u64 v[40:41], v[40:41], 2, v[34:35]
	global_load_dword v126, v[38:39], off nt
	global_load_dword v129, v[40:41], off nt
.LBB0_161:
	s_or_b64 exec, exec, s[38:39]
	v_mov_b32_e32 v130, 0
	v_mov_b32_e32 v131, 0
	v_mov_b32_e32 v132, 0
	s_and_saveexec_b64 s[38:39], vcc
	s_cbranch_execz .LBB0_163
	v_add_u32_e32 v37, 32, v36
	v_mad_u64_u32 v[38:39], s[36:37], v37, s27, 0
	v_ashrrev_i32_e32 v41, 31, v37
	v_mov_b32_e32 v40, v39
	v_mad_u64_u32 v[40:41], s[36:37], v41, s27, v[40:41]
	v_add_u32_e32 v37, 34, v36
	v_mov_b32_e32 v39, v40
	v_mad_u64_u32 v[40:41], s[36:37], v37, s27, 0
	v_ashrrev_i32_e32 v43, 31, v37
	v_mov_b32_e32 v42, v41
	v_mad_u64_u32 v[42:43], s[36:37], v43, s27, v[42:43]
	v_lshl_add_u64 v[38:39], v[38:39], 2, v[34:35]
	v_mov_b32_e32 v41, v42
	v_lshl_add_u64 v[40:41], v[40:41], 2, v[34:35]
	global_load_dword v131, v[38:39], off nt
	global_load_dword v132, v[40:41], off nt
.LBB0_163:
	s_or_b64 exec, exec, s[38:39]
	v_mov_b32_e32 v133, 0
	s_and_saveexec_b64 s[38:39], vcc
	s_cbranch_execz .LBB0_165
	v_add_u32_e32 v37, 36, v36
	v_mad_u64_u32 v[38:39], s[36:37], v37, s27, 0
	v_ashrrev_i32_e32 v41, 31, v37
	v_mov_b32_e32 v40, v39
	v_mad_u64_u32 v[40:41], s[36:37], v41, s27, v[40:41]
	v_add_u32_e32 v37, 38, v36
	v_mov_b32_e32 v39, v40
	v_mad_u64_u32 v[40:41], s[36:37], v37, s27, 0
	v_ashrrev_i32_e32 v43, 31, v37
	v_mov_b32_e32 v42, v41
	v_mad_u64_u32 v[42:43], s[36:37], v43, s27, v[42:43]
	v_lshl_add_u64 v[38:39], v[38:39], 2, v[34:35]
	v_mov_b32_e32 v41, v42
	v_lshl_add_u64 v[40:41], v[40:41], 2, v[34:35]
	global_load_dword v130, v[38:39], off nt
	global_load_dword v133, v[40:41], off nt
.LBB0_165:
	s_or_b64 exec, exec, s[38:39]
	v_mov_b32_e32 v134, 0
	v_mov_b32_e32 v135, 0
	v_mov_b32_e32 v136, 0
	s_and_saveexec_b64 s[38:39], vcc
	s_cbranch_execz .LBB0_167
	v_add_u32_e32 v37, 40, v36
	v_mad_u64_u32 v[38:39], s[36:37], v37, s27, 0
	v_ashrrev_i32_e32 v41, 31, v37
	v_mov_b32_e32 v40, v39
	v_mad_u64_u32 v[40:41], s[36:37], v41, s27, v[40:41]
	v_add_u32_e32 v37, 42, v36
	v_mov_b32_e32 v39, v40
	v_mad_u64_u32 v[40:41], s[36:37], v37, s27, 0
	v_ashrrev_i32_e32 v43, 31, v37
	v_mov_b32_e32 v42, v41
	v_mad_u64_u32 v[42:43], s[36:37], v43, s27, v[42:43]
	v_lshl_add_u64 v[38:39], v[38:39], 2, v[34:35]
	v_mov_b32_e32 v41, v42
	v_lshl_add_u64 v[40:41], v[40:41], 2, v[34:35]
	global_load_dword v135, v[38:39], off nt
	global_load_dword v136, v[40:41], off nt
.LBB0_167:
	s_or_b64 exec, exec, s[38:39]
	v_mov_b32_e32 v137, 0
	s_and_saveexec_b64 s[38:39], vcc
	s_cbranch_execz .LBB0_169
	v_add_u32_e32 v37, 44, v36
	v_mad_u64_u32 v[38:39], s[36:37], v37, s27, 0
	v_ashrrev_i32_e32 v41, 31, v37
	v_mov_b32_e32 v40, v39
	v_mad_u64_u32 v[40:41], s[36:37], v41, s27, v[40:41]
	v_add_u32_e32 v37, 46, v36
	v_mov_b32_e32 v39, v40
	v_mad_u64_u32 v[40:41], s[36:37], v37, s27, 0
	v_ashrrev_i32_e32 v43, 31, v37
	v_mov_b32_e32 v42, v41
	v_mad_u64_u32 v[42:43], s[36:37], v43, s27, v[42:43]
	v_lshl_add_u64 v[38:39], v[38:39], 2, v[34:35]
	v_mov_b32_e32 v41, v42
	v_lshl_add_u64 v[40:41], v[40:41], 2, v[34:35]
	global_load_dword v134, v[38:39], off nt
	global_load_dword v137, v[40:41], off nt
.LBB0_169:
	s_or_b64 exec, exec, s[38:39]
	v_mov_b32_e32 v138, 0
	v_mov_b32_e32 v139, 0
	v_mov_b32_e32 v140, 0
	s_and_saveexec_b64 s[38:39], vcc
	s_cbranch_execz .LBB0_171
	v_add_u32_e32 v37, 48, v36
	v_mad_u64_u32 v[38:39], s[36:37], v37, s27, 0
	v_ashrrev_i32_e32 v41, 31, v37
	v_mov_b32_e32 v40, v39
	v_mad_u64_u32 v[40:41], s[36:37], v41, s27, v[40:41]
	v_add_u32_e32 v37, 50, v36
	v_mov_b32_e32 v39, v40
	v_mad_u64_u32 v[40:41], s[36:37], v37, s27, 0
	v_ashrrev_i32_e32 v43, 31, v37
	v_mov_b32_e32 v42, v41
	v_mad_u64_u32 v[42:43], s[36:37], v43, s27, v[42:43]
	v_lshl_add_u64 v[38:39], v[38:39], 2, v[34:35]
	v_mov_b32_e32 v41, v42
	v_lshl_add_u64 v[40:41], v[40:41], 2, v[34:35]
	global_load_dword v139, v[38:39], off nt
	global_load_dword v140, v[40:41], off nt
.LBB0_171:
	s_or_b64 exec, exec, s[38:39]
	v_mov_b32_e32 v141, 0
	s_and_saveexec_b64 s[38:39], vcc
	s_cbranch_execz .LBB0_173
	v_add_u32_e32 v37, 52, v36
	v_mad_u64_u32 v[38:39], s[36:37], v37, s27, 0
	v_ashrrev_i32_e32 v41, 31, v37
	v_mov_b32_e32 v40, v39
	v_mad_u64_u32 v[40:41], s[36:37], v41, s27, v[40:41]
	v_add_u32_e32 v37, 54, v36
	v_mov_b32_e32 v39, v40
	v_mad_u64_u32 v[40:41], s[36:37], v37, s27, 0
	v_ashrrev_i32_e32 v43, 31, v37
	v_mov_b32_e32 v42, v41
	v_mad_u64_u32 v[42:43], s[36:37], v43, s27, v[42:43]
	v_lshl_add_u64 v[38:39], v[38:39], 2, v[34:35]
	v_mov_b32_e32 v41, v42
	v_lshl_add_u64 v[40:41], v[40:41], 2, v[34:35]
	global_load_dword v138, v[38:39], off nt
	global_load_dword v141, v[40:41], off nt
.LBB0_173:
	s_or_b64 exec, exec, s[38:39]
	v_mov_b32_e32 v142, 0
	v_mov_b32_e32 v143, 0
	v_mov_b32_e32 v144, 0
	s_and_saveexec_b64 s[38:39], vcc
	s_cbranch_execz .LBB0_175
	v_add_u32_e32 v37, 56, v36
	v_mad_u64_u32 v[38:39], s[36:37], v37, s27, 0
	v_ashrrev_i32_e32 v41, 31, v37
	v_mov_b32_e32 v40, v39
	v_mad_u64_u32 v[40:41], s[36:37], v41, s27, v[40:41]
	v_add_u32_e32 v37, 58, v36
	v_mov_b32_e32 v39, v40
	v_mad_u64_u32 v[40:41], s[36:37], v37, s27, 0
	v_ashrrev_i32_e32 v43, 31, v37
	v_mov_b32_e32 v42, v41
	v_mad_u64_u32 v[42:43], s[36:37], v43, s27, v[42:43]
	v_lshl_add_u64 v[38:39], v[38:39], 2, v[34:35]
	v_mov_b32_e32 v41, v42
	v_lshl_add_u64 v[40:41], v[40:41], 2, v[34:35]
	global_load_dword v143, v[38:39], off nt
	global_load_dword v144, v[40:41], off nt
.LBB0_175:
	s_or_b64 exec, exec, s[38:39]
	v_mov_b32_e32 v145, 0
	s_and_saveexec_b64 s[38:39], vcc
	s_cbranch_execz .LBB0_177
	v_add_u32_e32 v37, 60, v36
	v_mad_u64_u32 v[38:39], s[36:37], v37, s27, 0
	v_ashrrev_i32_e32 v41, 31, v37
	v_mov_b32_e32 v40, v39
	v_mad_u64_u32 v[40:41], s[36:37], v41, s27, v[40:41]
	v_add_u32_e32 v36, 62, v36
	v_ashrrev_i32_e32 v41, 31, v36
	v_mad_u64_u32 v[36:37], s[36:37], v36, s27, 0
	v_mov_b32_e32 v39, v40
	v_mov_b32_e32 v40, v37
	v_mad_u64_u32 v[40:41], s[36:37], v41, s27, v[40:41]
	v_lshl_add_u64 v[38:39], v[38:39], 2, v[34:35]
	v_mov_b32_e32 v37, v40
	v_lshl_add_u64 v[34:35], v[36:37], 2, v[34:35]
	global_load_dword v142, v[38:39], off nt
	global_load_dword v145, v[34:35], off nt

.LBB0_208:
	v_add_u32_e32 v36, s36, v1
	v_cmp_le_i32_e32 vcc, s13, v36
	s_and_saveexec_b64 s[36:37], vcc
	s_xor_b64 s[38:39], exec, s[36:37]
	v_mov_b32_e32 v2, s19
	s_or_saveexec_b64 s[38:39], s[38:39]
	v_ashrrev_i32_e32 v37, 31, v36
	v_add_u32_e32 v153, s12, v104
	v_lshl_add_u64 v[102:103], v[36:37], 2, v[34:35]
	v_mov_b32_e32 v3, 0
	s_xor_b64 exec, exec, s[38:39]
	s_cbranch_execz .LBB0_212
	v_mad_u64_u32 v[2:3], s[36:37], v153, s13, 0
	v_ashrrev_i32_e32 v5, 31, v153
	v_mov_b32_e32 v4, v3
	v_mad_u64_u32 v[4:5], s[36:37], v5, s13, v[4:5]
	v_mov_b32_e32 v3, v4
	v_add_u32_e32 v4, 2, v153
	v_ashrrev_i32_e32 v7, 31, v4
	v_mad_u64_u32 v[4:5], s[36:37], v4, s13, 0
	v_mov_b32_e32 v6, v5
	v_mad_u64_u32 v[6:7], s[36:37], v7, s13, v[6:7]
	v_lshl_add_u64 v[2:3], v[2:3], 2, v[102:103]
	v_mov_b32_e32 v5, v6
	v_lshl_add_u64 v[4:5], v[4:5], 2, v[102:103]
	global_load_dword v2, v[2:3], off nt
	s_nop 0
	global_load_dword v3, v[4:5], off nt

.LBB0_215:
	v_add_u32_e32 v4, 4, v153
	v_mad_u64_u32 v[34:35], s[36:37], v4, s13, 0
	v_ashrrev_i32_e32 v36, 31, v4
	v_mov_b32_e32 v4, v35
	v_mad_u64_u32 v[36:37], s[36:37], v36, s13, v[4:5]
	v_add_u32_e32 v4, 6, v153
	v_mov_b32_e32 v35, v36
	v_mad_u64_u32 v[36:37], s[36:37], v4, s13, 0
	v_ashrrev_i32_e32 v38, 31, v4
	v_mov_b32_e32 v4, v37
	v_mad_u64_u32 v[38:39], s[36:37], v38, s13, v[4:5]
	v_lshl_add_u64 v[34:35], v[34:35], 2, v[102:103]
	v_mov_b32_e32 v37, v38
	v_lshl_add_u64 v[36:37], v[36:37], 2, v[102:103]
	global_load_dword v4, v[34:35], off nt
	global_load_dword v66, v[36:37], off nt
	s_waitcnt vmcnt(1)
	v_mov_b64_e32 v[64:65], v[32:33]
	v_mov_b64_e32 v[36:37], v[4:5]
	v_mov_b64_e32 v[62:63], v[30:31]
	v_mov_b64_e32 v[60:61], v[28:29]
	v_mov_b64_e32 v[58:59], v[26:27]
	v_mov_b64_e32 v[56:57], v[24:25]
	v_mov_b64_e32 v[54:55], v[22:23]
	v_mov_b64_e32 v[52:53], v[20:21]
	v_mov_b64_e32 v[50:51], v[18:19]
	v_mov_b64_e32 v[48:49], v[16:17]
	v_mov_b64_e32 v[46:47], v[14:15]
	v_mov_b64_e32 v[44:45], v[12:13]
	v_mov_b64_e32 v[42:43], v[10:11]
	v_mov_b64_e32 v[40:41], v[8:9]
	v_mov_b64_e32 v[38:39], v[6:7]
	v_mov_b64_e32 v[34:35], v[2:3]
	s_waitcnt vmcnt(0)
	v_mov_b32_e32 v37, v66

.LBB0_219:
	s_waitcnt vmcnt(1)
	v_add_u32_e32 v2, 8, v153
	v_ashrrev_i32_e32 v5, 31, v2
	s_waitcnt vmcnt(0)
	v_mad_u64_u32 v[2:3], s[36:37], v2, s13, 0
	v_mov_b32_e32 v4, v3
	v_mad_u64_u32 v[4:5], s[36:37], v5, s13, v[4:5]
	v_mov_b32_e32 v3, v4
	v_add_u32_e32 v4, 10, v153
	v_ashrrev_i32_e32 v7, 31, v4
	v_mad_u64_u32 v[4:5], s[36:37], v4, s13, 0
	v_mov_b32_e32 v6, v5
	v_mad_u64_u32 v[6:7], s[36:37], v7, s13, v[6:7]
	v_lshl_add_u64 v[2:3], v[2:3], 2, v[102:103]
	v_mov_b32_e32 v5, v6
	v_lshl_add_u64 v[4:5], v[4:5], 2, v[102:103]
	global_load_dword v38, v[2:3], off nt
	global_load_dword v66, v[4:5], off nt
	s_waitcnt vmcnt(1)
	v_mov_b64_e32 v[2:3], v[34:35]
	v_mov_b64_e32 v[6:7], v[38:39]
	v_mov_b64_e32 v[4:5], v[36:37]
	v_mov_b64_e32 v[8:9], v[40:41]
	v_mov_b64_e32 v[10:11], v[42:43]
	v_mov_b64_e32 v[12:13], v[44:45]
	v_mov_b64_e32 v[14:15], v[46:47]
	v_mov_b64_e32 v[16:17], v[48:49]
	v_mov_b64_e32 v[18:19], v[50:51]
	v_mov_b64_e32 v[20:21], v[52:53]
	v_mov_b64_e32 v[22:23], v[54:55]
	v_mov_b64_e32 v[24:25], v[56:57]
	v_mov_b64_e32 v[26:27], v[58:59]
	v_mov_b64_e32 v[28:29], v[60:61]
	v_mov_b64_e32 v[30:31], v[62:63]
	v_mov_b64_e32 v[32:33], v[64:65]
	s_waitcnt vmcnt(0)
	v_mov_b32_e32 v7, v66

.LBB0_223:
	v_add_u32_e32 v8, 12, v153
	v_mad_u64_u32 v[34:35], s[36:37], v8, s13, 0
	v_ashrrev_i32_e32 v36, 31, v8
	v_mov_b32_e32 v8, v35
	v_mad_u64_u32 v[36:37], s[36:37], v36, s13, v[8:9]
	v_add_u32_e32 v8, 14, v153
	v_mov_b32_e32 v35, v36
	v_mad_u64_u32 v[36:37], s[36:37], v8, s13, 0
	v_ashrrev_i32_e32 v38, 31, v8
	v_mov_b32_e32 v8, v37
	v_mad_u64_u32 v[38:39], s[36:37], v38, s13, v[8:9]
	v_lshl_add_u64 v[34:35], v[34:35], 2, v[102:103]
	v_mov_b32_e32 v37, v38
	v_lshl_add_u64 v[36:37], v[36:37], 2, v[102:103]
	global_load_dword v8, v[34:35], off nt
	global_load_dword v66, v[36:37], off nt
	s_waitcnt vmcnt(1)
	v_mov_b64_e32 v[64:65], v[32:33]
	v_mov_b64_e32 v[40:41], v[8:9]
	v_mov_b64_e32 v[62:63], v[30:31]
	v_mov_b64_e32 v[60:61], v[28:29]
	v_mov_b64_e32 v[58:59], v[26:27]
	v_mov_b64_e32 v[56:57], v[24:25]
	v_mov_b64_e32 v[54:55], v[22:23]
	v_mov_b64_e32 v[52:53], v[20:21]
	v_mov_b64_e32 v[50:51], v[18:19]
	v_mov_b64_e32 v[48:49], v[16:17]
	v_mov_b64_e32 v[46:47], v[14:15]
	v_mov_b64_e32 v[44:45], v[12:13]
	v_mov_b64_e32 v[42:43], v[10:11]
	v_mov_b64_e32 v[38:39], v[6:7]
	v_mov_b64_e32 v[36:37], v[4:5]
	v_mov_b64_e32 v[34:35], v[2:3]
	s_waitcnt vmcnt(0)
	v_mov_b32_e32 v41, v66

.LBB0_227:
	s_waitcnt vmcnt(1)
	v_add_u32_e32 v2, 16, v153
	v_ashrrev_i32_e32 v5, 31, v2
	s_waitcnt vmcnt(0)
	v_mad_u64_u32 v[2:3], s[36:37], v2, s13, 0
	v_mov_b32_e32 v4, v3
	v_mad_u64_u32 v[4:5], s[36:37], v5, s13, v[4:5]
	v_mov_b32_e32 v3, v4
	v_add_u32_e32 v4, 18, v153
	v_ashrrev_i32_e32 v7, 31, v4
	v_mad_u64_u32 v[4:5], s[36:37], v4, s13, 0
	v_mov_b32_e32 v6, v5
	v_mad_u64_u32 v[6:7], s[36:37], v7, s13, v[6:7]
	v_lshl_add_u64 v[2:3], v[2:3], 2, v[102:103]
	v_mov_b32_e32 v5, v6
	v_lshl_add_u64 v[4:5], v[4:5], 2, v[102:103]
	global_load_dword v42, v[2:3], off nt
	global_load_dword v66, v[4:5], off nt
	s_waitcnt vmcnt(1)
	v_mov_b64_e32 v[2:3], v[34:35]
	v_mov_b64_e32 v[10:11], v[42:43]
	v_mov_b64_e32 v[4:5], v[36:37]
	v_mov_b64_e32 v[6:7], v[38:39]
	v_mov_b64_e32 v[8:9], v[40:41]
	v_mov_b64_e32 v[12:13], v[44:45]
	v_mov_b64_e32 v[14:15], v[46:47]
	v_mov_b64_e32 v[16:17], v[48:49]
	v_mov_b64_e32 v[18:19], v[50:51]
	v_mov_b64_e32 v[20:21], v[52:53]
	v_mov_b64_e32 v[22:23], v[54:55]
	v_mov_b64_e32 v[24:25], v[56:57]
	v_mov_b64_e32 v[26:27], v[58:59]
	v_mov_b64_e32 v[28:29], v[60:61]
	v_mov_b64_e32 v[30:31], v[62:63]
	v_mov_b64_e32 v[32:33], v[64:65]
	s_waitcnt vmcnt(0)
	v_mov_b32_e32 v11, v66

.LBB0_231:
	v_add_u32_e32 v12, 20, v153
	v_mad_u64_u32 v[34:35], s[36:37], v12, s13, 0
	v_ashrrev_i32_e32 v36, 31, v12
	v_mov_b32_e32 v12, v35
	v_mad_u64_u32 v[36:37], s[36:37], v36, s13, v[12:13]
	v_add_u32_e32 v12, 22, v153
	v_mov_b32_e32 v35, v36
	v_mad_u64_u32 v[36:37], s[36:37], v12, s13, 0
	v_ashrrev_i32_e32 v38, 31, v12
	v_mov_b32_e32 v12, v37
	v_mad_u64_u32 v[38:39], s[36:37], v38, s13, v[12:13]
	v_lshl_add_u64 v[34:35], v[34:35], 2, v[102:103]
	v_mov_b32_e32 v37, v38
	v_lshl_add_u64 v[36:37], v[36:37], 2, v[102:103]
	global_load_dword v12, v[34:35], off nt
	global_load_dword v66, v[36:37], off nt
	s_waitcnt vmcnt(1)
	v_mov_b64_e32 v[64:65], v[32:33]
	v_mov_b64_e32 v[44:45], v[12:13]
	v_mov_b64_e32 v[62:63], v[30:31]
	v_mov_b64_e32 v[60:61], v[28:29]
	v_mov_b64_e32 v[58:59], v[26:27]
	v_mov_b64_e32 v[56:57], v[24:25]
	v_mov_b64_e32 v[54:55], v[22:23]
	v_mov_b64_e32 v[52:53], v[20:21]
	v_mov_b64_e32 v[50:51], v[18:19]
	v_mov_b64_e32 v[48:49], v[16:17]
	v_mov_b64_e32 v[46:47], v[14:15]
	v_mov_b64_e32 v[42:43], v[10:11]
	v_mov_b64_e32 v[40:41], v[8:9]
	v_mov_b64_e32 v[38:39], v[6:7]
	v_mov_b64_e32 v[36:37], v[4:5]
	v_mov_b64_e32 v[34:35], v[2:3]
	s_waitcnt vmcnt(0)
	v_mov_b32_e32 v45, v66

.LBB0_235:
	s_waitcnt vmcnt(1)
	v_add_u32_e32 v2, 24, v153
	v_ashrrev_i32_e32 v5, 31, v2
	s_waitcnt vmcnt(0)
	v_mad_u64_u32 v[2:3], s[36:37], v2, s13, 0
	v_mov_b32_e32 v4, v3
	v_mad_u64_u32 v[4:5], s[36:37], v5, s13, v[4:5]
	v_mov_b32_e32 v3, v4
	v_add_u32_e32 v4, 26, v153
	v_ashrrev_i32_e32 v7, 31, v4
	v_mad_u64_u32 v[4:5], s[36:37], v4, s13, 0
	v_mov_b32_e32 v6, v5
	v_mad_u64_u32 v[6:7], s[36:37], v7, s13, v[6:7]
	v_lshl_add_u64 v[2:3], v[2:3], 2, v[102:103]
	v_mov_b32_e32 v5, v6
	v_lshl_add_u64 v[4:5], v[4:5], 2, v[102:103]
	global_load_dword v46, v[2:3], off nt
	global_load_dword v66, v[4:5], off nt
	s_waitcnt vmcnt(1)
	v_mov_b64_e32 v[2:3], v[34:35]
	v_mov_b64_e32 v[14:15], v[46:47]
	v_mov_b64_e32 v[4:5], v[36:37]
	v_mov_b64_e32 v[6:7], v[38:39]
	v_mov_b64_e32 v[8:9], v[40:41]
	v_mov_b64_e32 v[10:11], v[42:43]
	v_mov_b64_e32 v[12:13], v[44:45]
	v_mov_b64_e32 v[16:17], v[48:49]
	v_mov_b64_e32 v[18:19], v[50:51]
	v_mov_b64_e32 v[20:21], v[52:53]
	v_mov_b64_e32 v[22:23], v[54:55]
	v_mov_b64_e32 v[24:25], v[56:57]
	v_mov_b64_e32 v[26:27], v[58:59]
	v_mov_b64_e32 v[28:29], v[60:61]
	v_mov_b64_e32 v[30:31], v[62:63]
	v_mov_b64_e32 v[32:33], v[64:65]
	s_waitcnt vmcnt(0)
	v_mov_b32_e32 v15, v66

.LBB0_239:
	v_add_u32_e32 v16, 28, v153
	v_mad_u64_u32 v[34:35], s[36:37], v16, s13, 0
	v_ashrrev_i32_e32 v36, 31, v16
	v_mov_b32_e32 v16, v35
	v_mad_u64_u32 v[36:37], s[36:37], v36, s13, v[16:17]
	v_add_u32_e32 v16, 30, v153
	v_mov_b32_e32 v35, v36
	v_mad_u64_u32 v[36:37], s[36:37], v16, s13, 0
	v_ashrrev_i32_e32 v38, 31, v16
	v_mov_b32_e32 v16, v37
	v_mad_u64_u32 v[38:39], s[36:37], v38, s13, v[16:17]
	v_lshl_add_u64 v[34:35], v[34:35], 2, v[102:103]
	v_mov_b32_e32 v37, v38
	v_lshl_add_u64 v[36:37], v[36:37], 2, v[102:103]
	global_load_dword v16, v[34:35], off nt
	global_load_dword v66, v[36:37], off nt
	s_waitcnt vmcnt(1)
	v_mov_b64_e32 v[64:65], v[32:33]
	v_mov_b64_e32 v[48:49], v[16:17]
	v_mov_b64_e32 v[62:63], v[30:31]
	v_mov_b64_e32 v[60:61], v[28:29]
	v_mov_b64_e32 v[58:59], v[26:27]
	v_mov_b64_e32 v[56:57], v[24:25]
	v_mov_b64_e32 v[54:55], v[22:23]
	v_mov_b64_e32 v[52:53], v[20:21]
	v_mov_b64_e32 v[50:51], v[18:19]
	v_mov_b64_e32 v[46:47], v[14:15]
	v_mov_b64_e32 v[44:45], v[12:13]
	v_mov_b64_e32 v[42:43], v[10:11]
	v_mov_b64_e32 v[40:41], v[8:9]
	v_mov_b64_e32 v[38:39], v[6:7]
	v_mov_b64_e32 v[36:37], v[4:5]
	v_mov_b64_e32 v[34:35], v[2:3]
	s_waitcnt vmcnt(0)
	v_mov_b32_e32 v49, v66

.LBB0_243:
	s_waitcnt vmcnt(1)
	v_add_u32_e32 v2, 32, v153
	v_ashrrev_i32_e32 v5, 31, v2
	s_waitcnt vmcnt(0)
	v_mad_u64_u32 v[2:3], s[36:37], v2, s13, 0
	v_mov_b32_e32 v4, v3
	v_mad_u64_u32 v[4:5], s[36:37], v5, s13, v[4:5]
	v_mov_b32_e32 v3, v4
	v_add_u32_e32 v4, 34, v153
	v_ashrrev_i32_e32 v7, 31, v4
	v_mad_u64_u32 v[4:5], s[36:37], v4, s13, 0
	v_mov_b32_e32 v6, v5
	v_mad_u64_u32 v[6:7], s[36:37], v7, s13, v[6:7]
	v_lshl_add_u64 v[2:3], v[2:3], 2, v[102:103]
	v_mov_b32_e32 v5, v6
	v_lshl_add_u64 v[4:5], v[4:5], 2, v[102:103]
	global_load_dword v50, v[2:3], off nt
	global_load_dword v66, v[4:5], off nt
	s_waitcnt vmcnt(1)
	v_mov_b64_e32 v[2:3], v[34:35]
	v_mov_b64_e32 v[18:19], v[50:51]
	v_mov_b64_e32 v[4:5], v[36:37]
	v_mov_b64_e32 v[6:7], v[38:39]
	v_mov_b64_e32 v[8:9], v[40:41]
	v_mov_b64_e32 v[10:11], v[42:43]
	v_mov_b64_e32 v[12:13], v[44:45]
	v_mov_b64_e32 v[14:15], v[46:47]
	v_mov_b64_e32 v[16:17], v[48:49]
	v_mov_b64_e32 v[20:21], v[52:53]
	v_mov_b64_e32 v[22:23], v[54:55]
	v_mov_b64_e32 v[24:25], v[56:57]
	v_mov_b64_e32 v[26:27], v[58:59]
	v_mov_b64_e32 v[28:29], v[60:61]
	v_mov_b64_e32 v[30:31], v[62:63]
	v_mov_b64_e32 v[32:33], v[64:65]
	s_waitcnt vmcnt(0)
	v_mov_b32_e32 v19, v66

.LBB0_247:
	v_add_u32_e32 v20, 36, v153
	v_mad_u64_u32 v[34:35], s[36:37], v20, s13, 0
	v_ashrrev_i32_e32 v36, 31, v20
	v_mov_b32_e32 v20, v35
	v_mad_u64_u32 v[36:37], s[36:37], v36, s13, v[20:21]
	v_add_u32_e32 v20, 38, v153
	v_mov_b32_e32 v35, v36
	v_mad_u64_u32 v[36:37], s[36:37], v20, s13, 0
	v_ashrrev_i32_e32 v38, 31, v20
	v_mov_b32_e32 v20, v37
	v_mad_u64_u32 v[38:39], s[36:37], v38, s13, v[20:21]
	v_lshl_add_u64 v[34:35], v[34:35], 2, v[102:103]
	v_mov_b32_e32 v37, v38
	v_lshl_add_u64 v[36:37], v[36:37], 2, v[102:103]
	global_load_dword v20, v[34:35], off nt
	global_load_dword v66, v[36:37], off nt
	s_waitcnt vmcnt(1)
	v_mov_b64_e32 v[64:65], v[32:33]
	v_mov_b64_e32 v[52:53], v[20:21]
	v_mov_b64_e32 v[62:63], v[30:31]
	v_mov_b64_e32 v[60:61], v[28:29]
	v_mov_b64_e32 v[58:59], v[26:27]
	v_mov_b64_e32 v[56:57], v[24:25]
	v_mov_b64_e32 v[54:55], v[22:23]
	v_mov_b64_e32 v[50:51], v[18:19]
	v_mov_b64_e32 v[48:49], v[16:17]
	v_mov_b64_e32 v[46:47], v[14:15]
	v_mov_b64_e32 v[44:45], v[12:13]
	v_mov_b64_e32 v[42:43], v[10:11]
	v_mov_b64_e32 v[40:41], v[8:9]
	v_mov_b64_e32 v[38:39], v[6:7]
	v_mov_b64_e32 v[36:37], v[4:5]
	v_mov_b64_e32 v[34:35], v[2:3]
	s_waitcnt vmcnt(0)
	v_mov_b32_e32 v53, v66

.LBB0_251:
	s_waitcnt vmcnt(1)
	v_add_u32_e32 v2, 40, v153
	v_ashrrev_i32_e32 v5, 31, v2
	s_waitcnt vmcnt(0)
	v_mad_u64_u32 v[2:3], s[36:37], v2, s13, 0
	v_mov_b32_e32 v4, v3
	v_mad_u64_u32 v[4:5], s[36:37], v5, s13, v[4:5]
	v_mov_b32_e32 v3, v4
	v_add_u32_e32 v4, 42, v153
	v_ashrrev_i32_e32 v7, 31, v4
	v_mad_u64_u32 v[4:5], s[36:37], v4, s13, 0
	v_mov_b32_e32 v6, v5
	v_mad_u64_u32 v[6:7], s[36:37], v7, s13, v[6:7]
	v_lshl_add_u64 v[2:3], v[2:3], 2, v[102:103]
	v_mov_b32_e32 v5, v6
	v_lshl_add_u64 v[4:5], v[4:5], 2, v[102:103]
	global_load_dword v54, v[2:3], off nt
	global_load_dword v66, v[4:5], off nt
	s_waitcnt vmcnt(1)
	v_mov_b64_e32 v[2:3], v[34:35]
	v_mov_b64_e32 v[22:23], v[54:55]
	v_mov_b64_e32 v[4:5], v[36:37]
	v_mov_b64_e32 v[6:7], v[38:39]
	v_mov_b64_e32 v[8:9], v[40:41]
	v_mov_b64_e32 v[10:11], v[42:43]
	v_mov_b64_e32 v[12:13], v[44:45]
	v_mov_b64_e32 v[14:15], v[46:47]
	v_mov_b64_e32 v[16:17], v[48:49]
	v_mov_b64_e32 v[18:19], v[50:51]
	v_mov_b64_e32 v[20:21], v[52:53]
	v_mov_b64_e32 v[24:25], v[56:57]
	v_mov_b64_e32 v[26:27], v[58:59]
	v_mov_b64_e32 v[28:29], v[60:61]
	v_mov_b64_e32 v[30:31], v[62:63]
	v_mov_b64_e32 v[32:33], v[64:65]
	s_waitcnt vmcnt(0)
	v_mov_b32_e32 v23, v66

.LBB0_255:
	v_add_u32_e32 v24, 44, v153
	v_mad_u64_u32 v[34:35], s[36:37], v24, s13, 0
	v_ashrrev_i32_e32 v36, 31, v24
	v_mov_b32_e32 v24, v35
	v_mad_u64_u32 v[36:37], s[36:37], v36, s13, v[24:25]
	v_add_u32_e32 v24, 46, v153
	v_mov_b32_e32 v35, v36
	v_mad_u64_u32 v[36:37], s[36:37], v24, s13, 0
	v_ashrrev_i32_e32 v38, 31, v24
	v_mov_b32_e32 v24, v37
	v_mad_u64_u32 v[38:39], s[36:37], v38, s13, v[24:25]
	v_lshl_add_u64 v[34:35], v[34:35], 2, v[102:103]
	v_mov_b32_e32 v37, v38
	v_lshl_add_u64 v[36:37], v[36:37], 2, v[102:103]
	global_load_dword v24, v[34:35], off nt
	global_load_dword v66, v[36:37], off nt
	s_waitcnt vmcnt(1)
	v_mov_b64_e32 v[64:65], v[32:33]
	v_mov_b64_e32 v[56:57], v[24:25]
	v_mov_b64_e32 v[62:63], v[30:31]
	v_mov_b64_e32 v[60:61], v[28:29]
	v_mov_b64_e32 v[58:59], v[26:27]
	v_mov_b64_e32 v[54:55], v[22:23]
	v_mov_b64_e32 v[52:53], v[20:21]
	v_mov_b64_e32 v[50:51], v[18:19]
	v_mov_b64_e32 v[48:49], v[16:17]
	v_mov_b64_e32 v[46:47], v[14:15]
	v_mov_b64_e32 v[44:45], v[12:13]
	v_mov_b64_e32 v[42:43], v[10:11]
	v_mov_b64_e32 v[40:41], v[8:9]
	v_mov_b64_e32 v[38:39], v[6:7]
	v_mov_b64_e32 v[36:37], v[4:5]
	v_mov_b64_e32 v[34:35], v[2:3]
	s_waitcnt vmcnt(0)
	v_mov_b32_e32 v57, v66

.LBB0_259:
	s_waitcnt vmcnt(1)
	v_add_u32_e32 v2, 48, v153
	v_ashrrev_i32_e32 v5, 31, v2
	s_waitcnt vmcnt(0)
	v_mad_u64_u32 v[2:3], s[36:37], v2, s13, 0
	v_mov_b32_e32 v4, v3
	v_mad_u64_u32 v[4:5], s[36:37], v5, s13, v[4:5]
	v_mov_b32_e32 v3, v4
	v_add_u32_e32 v4, 50, v153
	v_ashrrev_i32_e32 v7, 31, v4
	v_mad_u64_u32 v[4:5], s[36:37], v4, s13, 0
	v_mov_b32_e32 v6, v5
	v_mad_u64_u32 v[6:7], s[36:37], v7, s13, v[6:7]
	v_lshl_add_u64 v[2:3], v[2:3], 2, v[102:103]
	v_mov_b32_e32 v5, v6
	v_lshl_add_u64 v[4:5], v[4:5], 2, v[102:103]
	global_load_dword v58, v[2:3], off nt
	global_load_dword v66, v[4:5], off nt
	s_waitcnt vmcnt(1)
	v_mov_b64_e32 v[2:3], v[34:35]
	v_mov_b64_e32 v[26:27], v[58:59]
	v_mov_b64_e32 v[4:5], v[36:37]
	v_mov_b64_e32 v[6:7], v[38:39]
	v_mov_b64_e32 v[8:9], v[40:41]
	v_mov_b64_e32 v[10:11], v[42:43]
	v_mov_b64_e32 v[12:13], v[44:45]
	v_mov_b64_e32 v[14:15], v[46:47]
	v_mov_b64_e32 v[16:17], v[48:49]
	v_mov_b64_e32 v[18:19], v[50:51]
	v_mov_b64_e32 v[20:21], v[52:53]
	v_mov_b64_e32 v[22:23], v[54:55]
	v_mov_b64_e32 v[24:25], v[56:57]
	v_mov_b64_e32 v[28:29], v[60:61]
	v_mov_b64_e32 v[30:31], v[62:63]
	v_mov_b64_e32 v[32:33], v[64:65]
	s_waitcnt vmcnt(0)
	v_mov_b32_e32 v27, v66

.LBB0_263:
	v_add_u32_e32 v28, 52, v153
	v_mad_u64_u32 v[34:35], s[36:37], v28, s13, 0
	v_ashrrev_i32_e32 v36, 31, v28
	v_mov_b32_e32 v28, v35
	v_mad_u64_u32 v[36:37], s[36:37], v36, s13, v[28:29]
	v_add_u32_e32 v28, 54, v153
	v_mov_b32_e32 v35, v36
	v_mad_u64_u32 v[36:37], s[36:37], v28, s13, 0
	v_ashrrev_i32_e32 v38, 31, v28
	v_mov_b32_e32 v28, v37
	v_mad_u64_u32 v[38:39], s[36:37], v38, s13, v[28:29]
	v_lshl_add_u64 v[34:35], v[34:35], 2, v[102:103]
	v_mov_b32_e32 v37, v38
	v_lshl_add_u64 v[36:37], v[36:37], 2, v[102:103]
	global_load_dword v28, v[34:35], off nt
	s_nop 0
	global_load_dword v34, v[36:37], off nt
	s_waitcnt vmcnt(1)
	v_mov_b64_e32 v[96:97], v[32:33]
	v_mov_b64_e32 v[92:93], v[28:29]
	v_mov_b64_e32 v[94:95], v[30:31]
	v_mov_b64_e32 v[90:91], v[26:27]
	v_mov_b64_e32 v[88:89], v[24:25]
	v_mov_b64_e32 v[86:87], v[22:23]
	v_mov_b64_e32 v[84:85], v[20:21]
	v_mov_b64_e32 v[82:83], v[18:19]
	v_mov_b64_e32 v[80:81], v[16:17]
	v_mov_b64_e32 v[78:79], v[14:15]
	v_mov_b64_e32 v[76:77], v[12:13]
	v_mov_b64_e32 v[74:75], v[10:11]
	v_mov_b64_e32 v[72:73], v[8:9]
	v_mov_b64_e32 v[70:71], v[6:7]
	v_mov_b64_e32 v[68:69], v[4:5]
	v_mov_b64_e32 v[66:67], v[2:3]
	s_waitcnt vmcnt(0)
	v_mov_b32_e32 v93, v34

.LBB0_267:
	s_waitcnt vmcnt(1)
	v_add_u32_e32 v2, 56, v153
	v_ashrrev_i32_e32 v5, 31, v2
	s_waitcnt vmcnt(0)
	v_mad_u64_u32 v[2:3], s[36:37], v2, s13, 0
	v_mov_b32_e32 v4, v3
	v_mad_u64_u32 v[4:5], s[36:37], v5, s13, v[4:5]
	v_mov_b32_e32 v3, v4
	v_add_u32_e32 v4, 58, v153
	v_ashrrev_i32_e32 v7, 31, v4
	v_mad_u64_u32 v[4:5], s[36:37], v4, s13, 0
	v_mov_b32_e32 v6, v5
	v_mad_u64_u32 v[6:7], s[36:37], v7, s13, v[6:7]
	v_lshl_add_u64 v[2:3], v[2:3], 2, v[102:103]
	v_mov_b32_e32 v5, v6
	v_lshl_add_u64 v[4:5], v[4:5], 2, v[102:103]
	global_load_dword v94, v[2:3], off nt
	s_nop 0
	global_load_dword v2, v[4:5], off nt
	s_waitcnt vmcnt(1)
	v_mov_b64_e32 v[34:35], v[66:67]
	v_mov_b64_e32 v[62:63], v[94:95]
	v_mov_b64_e32 v[36:37], v[68:69]
	v_mov_b64_e32 v[38:39], v[70:71]
	v_mov_b64_e32 v[40:41], v[72:73]
	v_mov_b64_e32 v[42:43], v[74:75]
	v_mov_b64_e32 v[44:45], v[76:77]
	v_mov_b64_e32 v[46:47], v[78:79]
	v_mov_b64_e32 v[48:49], v[80:81]
	v_mov_b64_e32 v[50:51], v[82:83]
	v_mov_b64_e32 v[52:53], v[84:85]
	v_mov_b64_e32 v[54:55], v[86:87]
	v_mov_b64_e32 v[56:57], v[88:89]
	v_mov_b64_e32 v[58:59], v[90:91]
	v_mov_b64_e32 v[60:61], v[92:93]
	v_mov_b64_e32 v[64:65], v[96:97]
	s_waitcnt vmcnt(0)
	v_mov_b32_e32 v63, v2

.LBB0_272:
	s_waitcnt vmcnt(1)
	v_add_u32_e32 v2, 60, v153
	v_ashrrev_i32_e32 v5, 31, v2
	s_waitcnt vmcnt(0)
	v_mad_u64_u32 v[2:3], s[36:37], v2, s13, 0
	v_mov_b32_e32 v4, v3
	v_mad_u64_u32 v[4:5], s[36:37], v5, s13, v[4:5]
	v_mov_b32_e32 v3, v4
	v_add_u32_e32 v4, 62, v153
	v_ashrrev_i32_e32 v7, 31, v4
	v_mad_u64_u32 v[4:5], s[36:37], v4, s13, 0
	v_mov_b32_e32 v6, v5
	v_mad_u64_u32 v[6:7], s[36:37], v7, s13, v[6:7]
	v_lshl_add_u64 v[2:3], v[2:3], 2, v[102:103]
	v_mov_b32_e32 v5, v6
	v_lshl_add_u64 v[4:5], v[4:5], 2, v[102:103]
	global_load_dword v64, v[2:3], off nt
	global_load_dword v66, v[4:5], off nt
	s_waitcnt vmcnt(1)
	v_mov_b64_e32 v[2:3], v[34:35]
	v_mov_b64_e32 v[32:33], v[64:65]
	v_mov_b64_e32 v[4:5], v[36:37]
	v_mov_b64_e32 v[6:7], v[38:39]
	v_mov_b64_e32 v[8:9], v[40:41]
	v_mov_b64_e32 v[10:11], v[42:43]
	v_mov_b64_e32 v[12:13], v[44:45]
	v_mov_b64_e32 v[14:15], v[46:47]
	v_mov_b64_e32 v[16:17], v[48:49]
	v_mov_b64_e32 v[18:19], v[50:51]
	v_mov_b64_e32 v[20:21], v[52:53]
	v_mov_b64_e32 v[22:23], v[54:55]
	v_mov_b64_e32 v[24:25], v[56:57]
	v_mov_b64_e32 v[26:27], v[58:59]
	v_mov_b64_e32 v[28:29], v[60:61]
	v_mov_b64_e32 v[30:31], v[62:63]
	s_waitcnt vmcnt(0)
	v_mov_b32_e32 v33, v66
	s_or_b64 exec, exec, s[38:39]
	s_andn2_b64 vcc, exec, s[20:21]
	s_cbranch_vccnz .LBB0_113

.LBB0_281:
	global_load_dword v27, v[6:7], off nt
	global_load_dword v26, v[6:7], off offset:256 nt
	global_load_dword v29, v[6:7], off offset:512 nt
	global_load_dword v28, v[6:7], off offset:768 nt
	global_load_dword v31, v[6:7], off offset:1024
	global_load_dword v30, v[6:7], off offset:1280
	global_load_dword v33, v[6:7], off offset:1536
	global_load_dword v32, v[6:7], off offset:1792
	global_load_dword v35, v[6:7], off offset:2048
	global_load_dword v34, v[6:7], off offset:2304
	global_load_dword v37, v[6:7], off offset:2560
	global_load_dword v36, v[6:7], off offset:2816
	global_load_dword v39, v[6:7], off offset:3072
	global_load_dword v38, v[6:7], off offset:3328
	global_load_dword v41, v[6:7], off offset:3584
	global_load_dword v40, v[6:7], off offset:3840
	v_lshl_add_u64 v[24:25], v[4:5], 0, s[8:9]
	v_add_co_u32_e32 v42, vcc, s2, v6
	s_add_u32 s8, s8, 64
	s_nop 0
	v_addc_co_u32_e32 v43, vcc, 0, v7, vcc
	global_load_dwordx4 v[8:11], v[24:25], off
	global_load_dwordx4 v[12:15], v[24:25], off offset:16
	global_load_dwordx4 v[16:19], v[24:25], off offset:48
	global_load_dwordx4 v[20:23], v[24:25], off offset:32
	global_load_dword v45, v[42:43], off nt
	global_load_dword v44, v[42:43], off offset:256 nt
	global_load_dword v47, v[42:43], off offset:512 nt
	global_load_dword v46, v[42:43], off offset:768 nt
	global_load_dword v49, v[42:43], off offset:1024
	global_load_dword v48, v[42:43], off offset:1280
	global_load_dword v51, v[42:43], off offset:1536
	global_load_dword v50, v[42:43], off offset:1792
	global_load_dword v53, v[42:43], off offset:2048
	global_load_dword v52, v[42:43], off offset:2304
	global_load_dword v55, v[42:43], off offset:2560
	global_load_dword v54, v[42:43], off offset:2816
	global_load_dword v25, v[42:43], off offset:3072
	global_load_dword v24, v[42:43], off offset:3328
	global_load_dword v57, v[42:43], off offset:3584
	global_load_dword v56, v[42:43], off offset:3840
	s_addc_u32 s9, s9, 0
	v_lshl_add_u64 v[6:7], v[6:7], 0, s[10:11]
	s_cmpk_eq_i32 s8, 0x100
	s_waitcnt vmcnt(19)
	v_pk_fma_f32 v[2:3], v[8:9], v[26:27], v[2:3] op_sel_hi:[0,1,1]
	v_pk_fma_f32 v[2:3], v[8:9], v[28:29], v[2:3] op_sel:[1,0,0]
	v_mov_b32_e32 v26, v11
	v_pk_fma_f32 v[2:3], v[10:11], v[30:31], v[2:3] op_sel_hi:[0,1,1]
	s_waitcnt vmcnt(18)
	v_mov_b32_e32 v42, v15
	v_pk_fma_f32 v[2:3], v[26:27], v[32:33], v[2:3] op_sel_hi:[0,1,1]
	s_waitcnt vmcnt(16)
	v_mov_b32_e32 v58, v23
	v_pk_fma_f32 v[2:3], v[12:13], v[34:35], v[2:3] op_sel_hi:[0,1,1]
	v_mov_b32_e32 v60, v19
	v_pk_fma_f32 v[2:3], v[12:13], v[36:37], v[2:3] op_sel:[1,0,0]
	s_nop 0
	v_pk_fma_f32 v[2:3], v[14:15], v[38:39], v[2:3] op_sel_hi:[0,1,1]
	v_pk_fma_f32 v[2:3], v[42:43], v[40:41], v[2:3] op_sel_hi:[0,1,1]
	s_waitcnt vmcnt(14)
	v_pk_fma_f32 v[2:3], v[20:21], v[44:45], v[2:3] op_sel_hi:[0,1,1]
	s_waitcnt vmcnt(12)
	v_pk_fma_f32 v[2:3], v[20:21], v[46:47], v[2:3] op_sel:[1,0,0]
	s_waitcnt vmcnt(10)
	v_pk_fma_f32 v[2:3], v[22:23], v[48:49], v[2:3] op_sel_hi:[0,1,1]
	s_waitcnt vmcnt(8)
	v_pk_fma_f32 v[2:3], v[58:59], v[50:51], v[2:3] op_sel_hi:[0,1,1]
	s_waitcnt vmcnt(6)
	v_pk_fma_f32 v[2:3], v[16:17], v[52:53], v[2:3] op_sel_hi:[0,1,1]
	s_waitcnt vmcnt(4)
	v_pk_fma_f32 v[2:3], v[16:17], v[54:55], v[2:3] op_sel:[1,0,0]
	s_waitcnt vmcnt(2)
	v_pk_fma_f32 v[2:3], v[18:19], v[24:25], v[2:3] op_sel_hi:[0,1,1]
	s_waitcnt vmcnt(0)
	v_pk_fma_f32 v[2:3], v[60:61], v[56:57], v[2:3] op_sel_hi:[0,1,1]
	s_cbranch_scc0 .LBB0_281
	s_lshl_b32 s2, s4, 9
	s_lshl_b32 s4, s6, 7
	s_add_i32 s4, s2, s4
	s_ashr_i32 s5, s4, 31
	s_lshl_b64 s[4:5], s[4:5], 2
	s_add_u32 s4, s94, s4
	s_addc_u32 s5, s95, s5
	v_lshlrev_b32_e32 v4, 2, v98
	v_mov_b32_e32 v5, 0
	v_lshl_add_u64 v[4:5], s[4:5], 0, v[4:5]
	s_mov_b64 s[4:5], 0x6200000
	v_lshl_add_u64 v[6:7], v[4:5], 0, s[4:5]
	v_add_co_u32_e32 v4, vcc, 0x6200000, v4
	s_nop 1
	v_addc_co_u32_e32 v5, vcc, 0, v5, vcc
	global_store_dword v[4:5], v3, off
	global_store_dword v[6:7], v2, off offset:256
.LBB0_283:
	s_waitcnt vmcnt(0)
	v_mov_b64_e32 v[2:3], s[0:1]
	global_load_dwordx2 v[4:5], v[2:3], off offset:16 sc0 sc1
	s_waitcnt vmcnt(0)
	global_load_dwordx2 v[6:7], v[2:3], off offset:24 sc0 sc1
	s_waitcnt vmcnt(0)
	global_load_dwordx2 v[8:9], v[2:3], off offset:72 sc0 sc1
	s_waitcnt vmcnt(0)
	s_and_b32 s4, s60, 0x7f
	s_mul_i32 s4, s4, 9
	s_lshr_b32 s8, s4, 1
	s_add_i32 s4, s4, 9
	s_ashr_i32 s2, s60, 7
	v_min_i32_e32 v16, 0xff, v0
	s_lshr_b32 s4, s4, 1
	s_add_i32 s3, s3, s8
	v_lshrrev_b32_e32 v22, 4, v16
	s_cmp_lt_u32 s3, s4
	s_movk_i32 s5, 0x200
	v_or_b32_e32 v22, 0x80, v22
	s_cselect_b64 s[12:13], -1, 0
	v_mov_b32_e32 v19, 0
	v_lshrrev_b32_e32 v27, 4, v0
	v_or_b32_e32 v13, 0x200, v0
	v_or_b32_e32 v14, 0x600, v0
	v_lshlrev_b32_e32 v16, 2, v16
	v_cmp_gt_u32_e32 vcc, s5, v0
	v_min_u32_e32 v22, 0x81, v22
	s_and_b64 s[4:5], s[12:13], exec
	v_mov_b32_e32 v24, 0x2400000
	v_lshlrev_b32_e32 v12, 4, v0
	v_lshlrev_b32_e32 v10, 12, v27
	v_lshrrev_b32_e32 v28, 4, v13
	v_lshrrev_b32_e32 v73, 4, v14
	v_mov_b32_e32 v23, v19
	v_and_b32_e32 v26, 60, v16
	v_lshlrev_b32_e32 v22, 12, v22
	s_cselect_b32 s3, s3, s8
	v_and_b32_e32 v72, 15, v0
	s_mov_b32 s19, 0
	v_mov_b32_e32 v11, v19
	v_and_b32_e32 v20, 0xf0, v12
	v_mov_b32_e32 v13, v19
	v_mov_b32_e32 v15, v19
	v_mov_b32_e32 v59, v19
	v_lshlrev_b32_e32 v12, 12, v28
	v_or_b32_e32 v14, 0x40000, v10
	v_or_b32_e32 v25, 0xffffff80, v73
	v_lshlrev_b32_e32 v58, 2, v26
	s_lshl_b32 s18, s3, 4
	v_lshrrev_b32_e32 v1, 4, v98
	s_mov_b32 s6, 0xfff80000
	v_lshlrev_b32_e32 v2, 2, v72
	v_mov_b32_e32 v3, v19
	v_cndmask_b32_e32 v16, v25, v73, vcc
	v_mul_u32_u24_e32 v18, 0x48000, v1
	s_mov_b32 s7, 0x9000
	s_mov_b32 s3, 0x12000
	v_mov_b32_e32 v21, v19
	v_mov_b32_e32 v17, v19
	v_lshlrev_b64 v[16:17], 12, v[16:17]
	s_waitcnt lgkmcnt(0)
	s_barrier
	v_and_b32_e32 v74, 0x78, v99
	v_lshl_add_u64 v[60:61], v[4:5], 0, v[22:23]
	v_lshl_add_u64 v[10:11], v[6:7], 0, v[10:11]
	v_mad_i64_i32 v[8:9], s[4:5], s2, v24, v[8:9]
	v_lshl_add_u64 v[12:13], v[6:7], 0, v[12:13]
	v_lshl_add_u64 v[14:15], v[6:7], 0, v[14:15]
	v_cndmask_b32_e32 v7, v5, v7, vcc
	v_cndmask_b32_e32 v6, v4, v6, vcc
	v_lshl_add_u64 v[4:5], s[18:19], 2, v[8:9]
	v_lshl_add_u64 v[24:25], v[60:61], 0, v[58:59]
	v_lshl_add_u64 v[30:31], v[4:5], 0, v[2:3]
	v_add_co_u32_e32 v2, vcc, s6, v24
	v_lshl_add_u64 v[70:71], v[30:31], 0, v[18:19]
	s_nop 0
	v_addc_co_u32_e32 v3, vcc, -1, v25, vcc
	v_add_co_u32_e32 v30, vcc, s7, v70
	v_lshl_add_u64 v[66:67], v[10:11], 0, v[20:21]
	s_nop 0
	v_addc_co_u32_e32 v31, vcc, 0, v71, vcc
	v_add_co_u32_e32 v32, vcc, s3, v70
	s_mov_b32 s3, 0x1b000
	s_nop 0
	v_addc_co_u32_e32 v33, vcc, 0, v71, vcc
	v_add_co_u32_e32 v34, vcc, s3, v70
	s_mov_b32 s3, 0x24000
	s_nop 0
	v_addc_co_u32_e32 v35, vcc, 0, v71, vcc
	v_lshl_add_u64 v[62:63], v[12:13], 0, v[20:21]
	v_lshl_add_u64 v[64:65], v[14:15], 0, v[20:21]
	v_lshl_add_u64 v[22:23], v[6:7], 0, v[16:17]
	global_load_dwordx4 v[14:17], v[66:67], off
	global_load_dwordx4 v[10:13], v[62:63], off
	global_load_dwordx4 v[6:9], v[64:65], off
	v_add_co_u32_e32 v36, vcc, s3, v70
	s_mov_b32 s3, 0x2d000
	s_nop 0
	v_addc_co_u32_e32 v37, vcc, 0, v71, vcc
	v_add_co_u32_e32 v38, vcc, s3, v70
	s_mov_b32 s3, 0x36000
	s_nop 0
	v_addc_co_u32_e32 v39, vcc, 0, v71, vcc
	v_add_co_u32_e32 v40, vcc, s3, v70
	s_mov_b32 s3, 0x3f000
	s_nop 0
	v_addc_co_u32_e32 v41, vcc, 0, v71, vcc
	v_add_co_u32_e32 v42, vcc, s3, v70
	s_mov_b32 s3, 0x120000
	s_nop 0
	v_addc_co_u32_e32 v43, vcc, 0, v71, vcc
	v_add_co_u32_e32 v44, vcc, s3, v70
	s_mov_b32 s3, 0x129000
	s_nop 0
	v_addc_co_u32_e32 v45, vcc, 0, v71, vcc
	v_lshl_add_u64 v[68:69], v[22:23], 0, v[20:21]
	global_load_dwordx4 v[2:5], v[2:3], off
	s_waitcnt vmcnt(3)
	v_mul_f32_e32 v29, 0xbfb8aa3b, v14
	global_load_dword v20, v[70:71], off nt
	global_load_dword v26, v[30:31], off nt
	global_load_dword v25, v[32:33], off nt
	global_load_dword v24, v[34:35], off nt
	global_load_dword v23, v[36:37], off nt
	global_load_dword v22, v[38:39], off nt
	global_load_dword v21, v[40:41], off nt
	global_load_dword v18, v[42:43], off nt
	global_load_dword v117, v[44:45], off nt
	v_add_co_u32_e32 v30, vcc, s3, v70
	s_mov_b32 s3, 0x132000
	s_nop 0
	v_addc_co_u32_e32 v31, vcc, 0, v71, vcc
	v_add_co_u32_e32 v32, vcc, s3, v70
	s_mov_b32 s3, 0x13b000
	s_nop 0
	v_addc_co_u32_e32 v33, vcc, 0, v71, vcc
	v_add_co_u32_e32 v34, vcc, s3, v70
	s_mov_b32 s3, 0x144000
	s_nop 0
	v_addc_co_u32_e32 v35, vcc, 0, v71, vcc
	v_add_co_u32_e32 v36, vcc, s3, v70
	s_mov_b32 s3, 0x14d000
	s_nop 0
	v_addc_co_u32_e32 v37, vcc, 0, v71, vcc
	v_add_co_u32_e32 v38, vcc, s3, v70
	s_mov_b32 s3, 0x156000
	s_nop 0
	v_addc_co_u32_e32 v39, vcc, 0, v71, vcc
	v_add_co_u32_e32 v40, vcc, s3, v70
	s_mov_b32 s3, 0x15f000
	s_nop 0
	v_addc_co_u32_e32 v41, vcc, 0, v71, vcc
	v_add_co_u32_e32 v42, vcc, s3, v70
	s_mov_b32 s3, 0x240000
	s_nop 0
	v_addc_co_u32_e32 v43, vcc, 0, v71, vcc
	v_add_co_u32_e32 v44, vcc, s3, v70
	s_mov_b32 s3, 0x249000
	s_nop 0
	v_addc_co_u32_e32 v45, vcc, 0, v71, vcc
	global_load_dword v135, v[30:31], off nt
	global_load_dword v132, v[32:33], off nt
	global_load_dword v129, v[34:35], off nt
	global_load_dword v126, v[36:37], off nt
	global_load_dword v123, v[38:39], off nt
	global_load_dword v120, v[40:41], off nt
	global_load_dword v113, v[42:43], off nt
	global_load_dword v85, v[44:45], off nt
	v_add_co_u32_e32 v30, vcc, s3, v70
	s_mov_b32 s3, 0x252000
	s_nop 0
	v_addc_co_u32_e32 v31, vcc, 0, v71, vcc
	v_add_co_u32_e32 v32, vcc, s3, v70
	s_mov_b32 s3, 0x25b000
	s_nop 0
	v_addc_co_u32_e32 v33, vcc, 0, v71, vcc
	v_add_co_u32_e32 v34, vcc, s3, v70
	s_mov_b32 s3, 0x264000
	s_nop 0
	v_addc_co_u32_e32 v35, vcc, 0, v71, vcc
	v_add_co_u32_e32 v36, vcc, s3, v70
	s_mov_b32 s3, 0x26d000
	s_nop 0
	v_addc_co_u32_e32 v37, vcc, 0, v71, vcc
	v_add_co_u32_e32 v38, vcc, s3, v70
	s_mov_b32 s3, 0x276000
	s_nop 0
	v_addc_co_u32_e32 v39, vcc, 0, v71, vcc
	v_add_co_u32_e32 v40, vcc, s3, v70
	s_mov_b32 s3, 0x27f000
	s_nop 0
	v_addc_co_u32_e32 v41, vcc, 0, v71, vcc
	v_add_co_u32_e32 v42, vcc, s3, v70
	s_mov_b32 s3, 0x360000
	s_nop 0
	v_addc_co_u32_e32 v43, vcc, 0, v71, vcc
	v_add_co_u32_e32 v44, vcc, s3, v70
	s_mov_b32 s3, 0x369000
	s_nop 0
	v_addc_co_u32_e32 v45, vcc, 0, v71, vcc
	global_load_dword v110, v[30:31], off nt
	global_load_dword v106, v[32:33], off nt
	global_load_dword v102, v[34:35], off nt
	global_load_dword v97, v[36:37], off nt
	global_load_dword v92, v[38:39], off nt
	global_load_dword v89, v[40:41], off nt
	global_load_dword v80, v[42:43], off nt
	global_load_dword v121, v[44:45], off nt
	v_add_co_u32_e32 v30, vcc, s3, v70
	s_mov_b32 s3, 0x372000
	s_nop 0
	v_addc_co_u32_e32 v31, vcc, 0, v71, vcc
	v_add_co_u32_e32 v32, vcc, s3, v70
	s_mov_b32 s3, 0x37b000
	s_nop 0
	v_addc_co_u32_e32 v33, vcc, 0, v71, vcc
	v_add_co_u32_e32 v34, vcc, s3, v70
	s_mov_b32 s3, 0x384000
	s_nop 0
	v_addc_co_u32_e32 v35, vcc, 0, v71, vcc
	v_add_co_u32_e32 v36, vcc, s3, v70
	s_mov_b32 s3, 0x38d000
	s_nop 0
	v_addc_co_u32_e32 v37, vcc, 0, v71, vcc
	v_add_co_u32_e32 v38, vcc, s3, v70
	s_mov_b32 s3, 0x396000
	s_nop 0
	v_addc_co_u32_e32 v39, vcc, 0, v71, vcc
	v_add_co_u32_e32 v40, vcc, s3, v70
	s_mov_b32 s3, 0x39f000
	s_nop 0
	v_addc_co_u32_e32 v41, vcc, 0, v71, vcc
	v_add_co_u32_e32 v42, vcc, s3, v70
	s_mov_b32 s3, 0x480000
	s_nop 0
	v_addc_co_u32_e32 v43, vcc, 0, v71, vcc
	v_add_co_u32_e32 v44, vcc, s3, v70
	s_mov_b32 s3, 0x489000
	s_nop 0
	v_addc_co_u32_e32 v45, vcc, 0, v71, vcc
	global_load_dword v137, v[30:31], off nt
	global_load_dword v136, v[32:33], off nt
	global_load_dword v133, v[34:35], off nt
	global_load_dword v130, v[36:37], off nt
	global_load_dword v127, v[38:39], off nt
	global_load_dword v125, v[40:41], off nt
	global_load_dword v118, v[42:43], off nt
	global_load_dword v86, v[44:45], off nt
	v_add_co_u32_e32 v30, vcc, s3, v70
	s_mov_b32 s3, 0x492000
	s_nop 0
	v_addc_co_u32_e32 v31, vcc, 0, v71, vcc
	v_add_co_u32_e32 v32, vcc, s3, v70
	s_mov_b32 s3, 0x49b000
	s_nop 0
	v_addc_co_u32_e32 v33, vcc, 0, v71, vcc
	v_add_co_u32_e32 v34, vcc, s3, v70
	s_mov_b32 s3, 0x4a4000
	s_nop 0
	v_addc_co_u32_e32 v35, vcc, 0, v71, vcc
	v_add_co_u32_e32 v36, vcc, s3, v70
	s_mov_b32 s3, 0x4ad000
	s_nop 0
	v_addc_co_u32_e32 v37, vcc, 0, v71, vcc
	v_add_co_u32_e32 v38, vcc, s3, v70
	s_mov_b32 s3, 0x4b6000
	s_nop 0
	v_addc_co_u32_e32 v39, vcc, 0, v71, vcc
	v_add_co_u32_e32 v40, vcc, s3, v70
	s_mov_b32 s3, 0x4bf000
	s_nop 0
	v_addc_co_u32_e32 v41, vcc, 0, v71, vcc
	v_add_co_u32_e32 v42, vcc, s3, v70
	s_mov_b32 s3, 0x5a0000
	s_nop 0
	v_addc_co_u32_e32 v43, vcc, 0, v71, vcc
	v_add_co_u32_e32 v44, vcc, s3, v70
	s_mov_b32 s3, 0x5a9000
	s_nop 0
	v_addc_co_u32_e32 v45, vcc, 0, v71, vcc
	global_load_dword v115, v[30:31], off nt
	global_load_dword v111, v[32:33], off nt
	global_load_dword v107, v[34:35], off nt
	global_load_dword v103, v[36:37], off nt
	global_load_dword v95, v[38:39], off nt
	global_load_dword v90, v[40:41], off nt
	global_load_dword v83, v[42:43], off nt
	global_load_dword v87, v[44:45], off nt
	v_add_co_u32_e32 v30, vcc, s3, v70
	s_mov_b32 s3, 0x5b2000
	s_nop 0
	v_addc_co_u32_e32 v31, vcc, 0, v71, vcc
	v_add_co_u32_e32 v32, vcc, s3, v70
	s_mov_b32 s3, 0x5bb000
	s_nop 0
	v_addc_co_u32_e32 v33, vcc, 0, v71, vcc
	v_add_co_u32_e32 v34, vcc, s3, v70
	s_mov_b32 s3, 0x5c4000
	s_nop 0
	v_addc_co_u32_e32 v35, vcc, 0, v71, vcc
	v_exp_f32_e32 v29, v29
	v_add_co_u32_e32 v36, vcc, s3, v70
	s_mov_b32 s3, 0x5cd000
	s_nop 0
	v_addc_co_u32_e32 v37, vcc, 0, v71, vcc
	v_add_co_u32_e32 v38, vcc, s3, v70
	s_mov_b32 s3, 0x5d6000
	s_nop 0
	v_addc_co_u32_e32 v39, vcc, 0, v71, vcc
	v_add_f32_e32 v29, 1.0, v29
	v_add_co_u32_e32 v40, vcc, s3, v70
	s_nop 0
	v_addc_co_u32_e32 v41, vcc, 0, v71, vcc
	s_mov_b32 s3, 0x5df000
	v_add_co_u32_e32 v42, vcc, s3, v70
	s_movk_i32 s3, 0x90
	s_nop 0
	v_addc_co_u32_e32 v43, vcc, 0, v71, vcc
	global_load_dword v112, v[30:31], off nt
	global_load_dword v108, v[32:33], off nt
	global_load_dword v104, v[34:35], off nt
	global_load_dword v100, v[36:37], off nt
	global_load_dword v93, v[38:39], off nt
	global_load_dword v91, v[40:41], off nt
	global_load_dword v81, v[42:43], off nt
	v_mul_f32_e32 v32, 0xbfb8aa3b, v15
	v_exp_f32_e32 v32, v32
	s_nop 0
	v_add_f32_e32 v32, 1.0, v32
	v_mul_f32_e32 v31, 0xbfb8aa3b, v16
	v_rcp_f32_e32 v30, v29
	s_nop 0
	v_mul_f32_e32 v29, v14, v30
	v_exp_f32_e32 v31, v31
	s_nop 0
	v_add_f32_e32 v31, 1.0, v31
	v_rcp_f32_e32 v14, v32
	s_nop 0
	v_mul_f32_e32 v30, v15, v14
	v_mul_f32_e32 v32, 0xbfb8aa3b, v17
	v_exp_f32_e32 v32, v32
	s_nop 0
	v_add_f32_e32 v32, 1.0, v32
	v_rcp_f32_e32 v14, v31
	s_nop 0
	v_mul_f32_e32 v31, v16, v14
	v_rcp_f32_e32 v14, v32
	s_nop 0
	v_mul_f32_e32 v17, v17, v14
	v_cvt_pk_bf16_f32 v14, v29, v30
	v_cvt_pk_bf16_f32 v15, v31, v17
	s_nop 0
	v_lshlrev_b32_e32 v16, 16, v14
	v_sub_f32_e32 v16, v29, v16
	v_and_b32_e32 v29, 0xffff0000, v14
	v_sub_f32_e32 v29, v30, v29
	v_cvt_pk_bf16_f32 v16, v16, v29
	v_lshlrev_b32_e32 v29, 16, v15
	v_and_b32_e32 v30, 0xffff0000, v15
	v_sub_f32_e32 v29, v31, v29
	v_sub_f32_e32 v17, v17, v30
	v_cvt_pk_bf16_f32 v17, v29, v17
	s_waitcnt vmcnt(50)
	v_mul_f32_e32 v29, 0xbfb8aa3b, v10
	v_exp_f32_e32 v29, v29
	v_mad_u32_u24 v30, v27, s3, 0
	v_add_u32_e32 v76, v30, v74
	ds_write_b64 v76, v[14:15]
	ds_write_b64 v76, v[16:17] offset:20736
	v_add_f32_e32 v29, 1.0, v29
	v_mul_f32_e32 v16, 0xbfb8aa3b, v11
	v_exp_f32_e32 v16, v16
	s_nop 0
	v_add_f32_e32 v16, 1.0, v16
	v_rcp_f32_e32 v14, v29
	s_nop 0
	v_mul_f32_e32 v14, v10, v14
	v_mul_f32_e32 v29, 0xbfb8aa3b, v12
	v_exp_f32_e32 v29, v29
	s_nop 0
	v_add_f32_e32 v17, 1.0, v29
	v_rcp_f32_e32 v10, v16
	s_nop 0
	v_mul_f32_e32 v15, v11, v10
	v_mul_f32_e32 v16, 0xbfb8aa3b, v13
	v_exp_f32_e32 v16, v16
	s_nop 0
	v_add_f32_e32 v16, 1.0, v16
	v_rcp_f32_e32 v10, v17
	s_nop 0
	v_mul_f32_e32 v17, v12, v10
	v_rcp_f32_e32 v10, v16
	s_nop 0
	v_mul_f32_e32 v13, v13, v10
	s_waitcnt vmcnt(49)
	v_mul_f32_e32 v16, 0xbfb8aa3b, v6
	v_exp_f32_e32 v16, v16
	v_cvt_pk_bf16_f32 v10, v14, v15
	v_cvt_pk_bf16_f32 v11, v17, v13
	s_nop 0
	v_lshlrev_b32_e32 v12, 16, v10
	v_sub_f32_e32 v12, v14, v12
	v_and_b32_e32 v14, 0xffff0000, v10
	v_sub_f32_e32 v14, v15, v14
	v_and_b32_e32 v15, 0xffff0000, v11
	v_cvt_pk_bf16_f32 v12, v12, v14
	v_lshlrev_b32_e32 v14, 16, v11
	v_sub_f32_e32 v13, v13, v15
	v_add_f32_e32 v15, 1.0, v16
	v_sub_f32_e32 v14, v17, v14
	v_cvt_pk_bf16_f32 v13, v14, v13
	v_mad_u32_u24 v14, v28, s3, 0
	v_add_u32_e32 v79, v14, v74
	ds_write_b64 v79, v[10:11]
	ds_write_b64 v79, v[12:13] offset:20736
	v_mul_f32_e32 v12, 0xbfb8aa3b, v7
	v_exp_f32_e32 v12, v12
	s_nop 0
	v_add_f32_e32 v12, 1.0, v12
	v_rcp_f32_e32 v10, v15
	s_nop 0
	v_mul_f32_e32 v10, v6, v10
	v_mul_f32_e32 v15, 0xbfb8aa3b, v8
	v_exp_f32_e32 v15, v15
	s_nop 0
	v_add_f32_e32 v13, 1.0, v15
	v_rcp_f32_e32 v6, v12
	s_nop 0
	v_mul_f32_e32 v11, v7, v6
	v_mul_f32_e32 v12, 0xbfb8aa3b, v9
	v_exp_f32_e32 v12, v12
	s_nop 0
	v_add_f32_e32 v12, 1.0, v12
	v_rcp_f32_e32 v6, v13
	s_nop 0
	v_mul_f32_e32 v13, v8, v6
	s_movk_i32 s3, 0x300
	v_rcp_f32_e32 v6, v12
	s_nop 0
	v_mul_f32_e32 v9, v9, v6
	v_cvt_pk_bf16_f32 v6, v10, v11
	v_cvt_pk_bf16_f32 v7, v13, v9
	v_cmp_gt_u32_e64 s[8:9], s3, v0
	v_lshlrev_b32_e32 v8, 16, v6
	v_sub_f32_e32 v8, v10, v8
	v_and_b32_e32 v10, 0xffff0000, v6
	v_sub_f32_e32 v10, v11, v10
	v_cvt_pk_bf16_f32 v8, v8, v10
	v_lshlrev_b32_e32 v10, 16, v7
	v_and_b32_e32 v11, 0xffff0000, v7
	v_sub_f32_e32 v10, v13, v10
	v_sub_f32_e32 v9, v9, v11
	v_cvt_pk_bf16_f32 v9, v10, v9
	v_add_u32_e32 v10, 0x2400, v30
	v_add_u32_e32 v78, v10, v74
	ds_write_b64 v78, v[6:7]
	ds_write_b64 v78, v[8:9] offset:20736
	s_and_saveexec_b64 s[10:11], s[8:9]
	s_cbranch_execz .LBB0_291
	global_load_dwordx4 v[6:9], v[68:69], off
	s_movk_i32 s3, 0x220
	v_cmp_gt_u32_e64 s[6:7], s3, v0
	s_and_saveexec_b64 s[20:21], s[6:7]
	s_cbranch_execz .LBB0_286
	s_waitcnt vmcnt(0)
	v_mul_f32_e32 v10, 0xbfb8aa3b, v6
	v_exp_f32_e32 v10, v10
	s_nop 0
	v_add_f32_e32 v10, 1.0, v10
	v_rcp_f32_e32 v11, v10
	s_nop 0
	v_mul_f32_e32 v19, v6, v11

.LBB0_306:
	s_nop 5
	v_add_co_u32_e32 v138, vcc, 0x6c0000, v70
	s_nop 1
	v_addc_co_u32_e32 v139, vcc, 0, v71, vcc
	v_add_co_u32_e32 v140, vcc, 0x6c9000, v70
	s_nop 1
	v_addc_co_u32_e32 v141, vcc, 0, v71, vcc
	v_add_co_u32_e32 v142, vcc, 0x6d2000, v70
	s_nop 1
	v_addc_co_u32_e32 v143, vcc, 0, v71, vcc
	v_add_co_u32_e32 v144, vcc, 0x6db000, v70
	s_nop 1
	v_addc_co_u32_e32 v145, vcc, 0, v71, vcc
	v_add_co_u32_e32 v146, vcc, 0x6e4000, v70
	s_nop 1
	v_addc_co_u32_e32 v147, vcc, 0, v71, vcc
	v_add_co_u32_e32 v148, vcc, 0x6ed000, v70
	s_nop 1
	v_addc_co_u32_e32 v149, vcc, 0, v71, vcc
	v_add_co_u32_e32 v150, vcc, 0x6f6000, v70
	s_nop 1
	v_addc_co_u32_e32 v151, vcc, 0, v71, vcc
	v_add_co_u32_e32 v152, vcc, 0x6ff000, v70
	s_nop 1
	v_addc_co_u32_e32 v153, vcc, 0, v71, vcc
	global_load_dword v134, v[138:139], off nt
	global_load_dword v131, v[140:141], off nt
	global_load_dword v128, v[142:143], off nt
	global_load_dword v124, v[144:145], off nt
	global_load_dword v122, v[146:147], off nt
	global_load_dword v119, v[148:149], off nt
	global_load_dword v116, v[150:151], off nt
	global_load_dword v114, v[152:153], off nt
	v_add_co_u32_e32 v138, vcc, 0x7e0000, v70
	s_nop 1
	v_addc_co_u32_e32 v139, vcc, 0, v71, vcc
	v_add_co_u32_e32 v140, vcc, 0x7e9000, v70
	s_nop 1
	v_addc_co_u32_e32 v141, vcc, 0, v71, vcc
	v_add_co_u32_e32 v142, vcc, 0x7f2000, v70
	s_nop 1
	v_addc_co_u32_e32 v143, vcc, 0, v71, vcc
	v_add_co_u32_e32 v144, vcc, 0x7fb000, v70
	s_nop 1
	v_addc_co_u32_e32 v145, vcc, 0, v71, vcc
	v_add_co_u32_e32 v146, vcc, 0x804000, v70
	s_nop 1
	v_addc_co_u32_e32 v147, vcc, 0, v71, vcc
	v_add_co_u32_e32 v148, vcc, 0x80d000, v70
	s_nop 1
	v_addc_co_u32_e32 v149, vcc, 0, v71, vcc
	v_add_co_u32_e32 v150, vcc, 0x816000, v70
	s_nop 1
	v_addc_co_u32_e32 v151, vcc, 0, v71, vcc
	v_add_co_u32_e32 v152, vcc, 0x81f000, v70
	s_nop 1
	v_addc_co_u32_e32 v153, vcc, 0, v71, vcc
	global_load_dword v109, v[138:139], off nt
	global_load_dword v105, v[140:141], off nt
	global_load_dword v101, v[142:143], off nt
	global_load_dword v96, v[144:145], off nt
	global_load_dword v94, v[146:147], off nt
	global_load_dword v88, v[148:149], off nt
	global_load_dword v84, v[150:151], off nt
	global_load_dword v82, v[152:153], off nt
	s_and_b64 vcc, exec, s[6:7]
	s_cbranch_vccnz .LBB0_308
	ds_read_b128 v[146:149], v75 offset:64
	ds_read_b128 v[150:153], v75 offset:39232
	s_waitcnt vmcnt(59)
	v_cvt_pk_bf16_f32 v138, v117, v135
	s_waitcnt vmcnt(57)
	v_cvt_pk_bf16_f32 v139, v132, v129
	s_waitcnt vmcnt(55)
	v_cvt_pk_bf16_f32 v140, v126, v123
	s_waitcnt vmcnt(53)
	v_cvt_pk_bf16_f32 v141, v120, v113
	v_lshlrev_b32_e32 v59, 16, v138
	v_and_b32_e32 v99, 0xffff0000, v138
	v_sub_f32_e32 v59, v117, v59
	v_sub_f32_e32 v99, v135, v99
	v_cvt_pk_bf16_f32 v142, v59, v99
	v_lshlrev_b32_e32 v59, 16, v139
	v_and_b32_e32 v99, 0xffff0000, v139
	v_sub_f32_e32 v59, v132, v59
	v_sub_f32_e32 v99, v129, v99
	s_waitcnt lgkmcnt(1)
	v_mfma_f32_16x16x32_bf16 v[30:33], v[146:149], v[138:141], v[30:33]
	v_cvt_pk_bf16_f32 v143, v59, v99
	v_lshlrev_b32_e32 v59, 16, v140
	v_and_b32_e32 v99, 0xffff0000, v140
	v_sub_f32_e32 v59, v126, v59
	v_sub_f32_e32 v99, v123, v99
	v_cvt_pk_bf16_f32 v144, v59, v99
	v_lshlrev_b32_e32 v59, 16, v141
	v_and_b32_e32 v99, 0xffff0000, v141
	v_sub_f32_e32 v59, v120, v59
	v_sub_f32_e32 v99, v113, v99
	v_cvt_pk_bf16_f32 v145, v59, v99
	s_nop 0
	v_mfma_f32_16x16x32_bf16 v[30:33], v[146:149], v[142:145], v[30:33]
	ds_read_b128 v[146:149], v75 offset:20800
	ds_read_b128 v[154:157], v75 offset:23104
	s_waitcnt lgkmcnt(1)
	v_mfma_f32_16x16x32_bf16 v[30:33], v[146:149], v[138:141], v[30:33]
	ds_read_b128 v[146:149], v75 offset:2368
	ds_read_b128 v[158:161], v75 offset:4672
	s_waitcnt lgkmcnt(1)
	v_mfma_f32_16x16x32_bf16 v[14:17], v[146:149], v[138:141], v[14:17]
	v_mfma_f32_16x16x32_bf16 v[14:17], v[146:149], v[142:145], v[14:17]
	s_waitcnt lgkmcnt(0)
	v_mfma_f32_16x16x32_bf16 v[34:37], v[158:161], v[138:141], v[34:37]
	v_mfma_f32_16x16x32_bf16 v[14:17], v[154:157], v[138:141], v[14:17]
	ds_read_b128 v[146:149], v75 offset:25408
	ds_read_b128 v[154:157], v75 offset:27712
	v_mfma_f32_16x16x32_bf16 v[34:37], v[158:161], v[142:145], v[34:37]
	s_waitcnt lgkmcnt(1)
	v_mfma_f32_16x16x32_bf16 v[34:37], v[146:149], v[138:141], v[34:37]
	ds_read_b128 v[146:149], v75 offset:6976
	ds_read_b128 v[158:161], v75 offset:9280
	s_waitcnt lgkmcnt(1)
	v_mfma_f32_16x16x32_bf16 v[22:25], v[146:149], v[138:141], v[22:25]
	v_mfma_f32_16x16x32_bf16 v[22:25], v[146:149], v[142:145], v[22:25]
	s_waitcnt lgkmcnt(0)
	v_mfma_f32_16x16x32_bf16 v[26:29], v[158:161], v[138:141], v[26:29]
	v_mfma_f32_16x16x32_bf16 v[22:25], v[154:157], v[138:141], v[22:25]
	ds_read_b128 v[146:149], v75 offset:30016
	ds_read_b128 v[154:157], v75 offset:32320
	v_mfma_f32_16x16x32_bf16 v[26:29], v[158:161], v[142:145], v[26:29]
	s_waitcnt lgkmcnt(1)
	v_mfma_f32_16x16x32_bf16 v[26:29], v[146:149], v[138:141], v[26:29]
	ds_read_b128 v[146:149], v75 offset:11584
	ds_read_b128 v[158:161], v75 offset:13888
	s_waitcnt lgkmcnt(1)
	v_mfma_f32_16x16x32_bf16 v[10:13], v[146:149], v[138:141], v[10:13]
	v_mfma_f32_16x16x32_bf16 v[10:13], v[146:149], v[142:145], v[10:13]
	s_waitcnt lgkmcnt(0)
	v_mfma_f32_16x16x32_bf16 v[18:21], v[158:161], v[138:141], v[18:21]
	v_mfma_f32_16x16x32_bf16 v[10:13], v[154:157], v[138:141], v[10:13]
	ds_read_b128 v[146:149], v75 offset:34624
	ds_read_b128 v[154:157], v75 offset:36928
	v_mfma_f32_16x16x32_bf16 v[18:21], v[158:161], v[142:145], v[18:21]
	s_waitcnt lgkmcnt(1)
	v_mfma_f32_16x16x32_bf16 v[18:21], v[146:149], v[138:141], v[18:21]
	ds_read_b128 v[146:149], v75 offset:16192
	ds_read_b128 v[158:161], v75 offset:18496
	s_waitcnt lgkmcnt(1)
	v_mfma_f32_16x16x32_bf16 v[6:9], v[146:149], v[138:141], v[6:9]
	s_waitcnt lgkmcnt(0)
	v_mfma_f32_16x16x32_bf16 v[2:5], v[158:161], v[138:141], v[2:5]
	v_mfma_f32_16x16x32_bf16 v[6:9], v[146:149], v[142:145], v[6:9]
	v_mfma_f32_16x16x32_bf16 v[2:5], v[158:161], v[142:145], v[2:5]
	v_mfma_f32_16x16x32_bf16 v[6:9], v[154:157], v[138:141], v[6:9]
	v_mfma_f32_16x16x32_bf16 v[2:5], v[150:153], v[138:141], v[2:5]

.LBB0_330:
	v_add_co_u32_e32 v138, vcc, 0x900000, v70
	s_nop 1
	v_addc_co_u32_e32 v139, vcc, 0, v71, vcc
	v_add_co_u32_e32 v140, vcc, 0x909000, v70
	s_nop 1
	v_addc_co_u32_e32 v141, vcc, 0, v71, vcc
	v_add_co_u32_e32 v142, vcc, 0x912000, v70
	s_nop 1
	v_addc_co_u32_e32 v143, vcc, 0, v71, vcc
	v_add_co_u32_e32 v144, vcc, 0x91b000, v70
	s_nop 1
	v_addc_co_u32_e32 v145, vcc, 0, v71, vcc
	v_add_co_u32_e32 v146, vcc, 0x924000, v70
	s_nop 1
	v_addc_co_u32_e32 v147, vcc, 0, v71, vcc
	v_add_co_u32_e32 v148, vcc, 0x92d000, v70
	s_nop 1
	v_addc_co_u32_e32 v149, vcc, 0, v71, vcc
	v_add_co_u32_e32 v150, vcc, 0x936000, v70
	s_nop 1
	v_addc_co_u32_e32 v151, vcc, 0, v71, vcc
	v_add_co_u32_e32 v152, vcc, 0x93f000, v70
	s_nop 1
	v_addc_co_u32_e32 v153, vcc, 0, v71, vcc
	global_load_dword v135, v[138:139], off nt
	global_load_dword v132, v[140:141], off nt
	global_load_dword v129, v[142:143], off nt
	global_load_dword v126, v[144:145], off nt
	global_load_dword v123, v[146:147], off nt
	global_load_dword v120, v[148:149], off nt
	global_load_dword v117, v[150:151], off nt
	global_load_dword v113, v[152:153], off nt
	v_add_co_u32_e32 v138, vcc, 0xa20000, v70
	s_nop 1
	v_addc_co_u32_e32 v139, vcc, 0, v71, vcc
	v_add_co_u32_e32 v140, vcc, 0xa29000, v70
	s_nop 1
	v_addc_co_u32_e32 v141, vcc, 0, v71, vcc
	v_add_co_u32_e32 v142, vcc, 0xa32000, v70
	s_nop 1
	v_addc_co_u32_e32 v143, vcc, 0, v71, vcc
	v_add_co_u32_e32 v144, vcc, 0xa3b000, v70
	s_nop 1
	v_addc_co_u32_e32 v145, vcc, 0, v71, vcc
	v_add_co_u32_e32 v146, vcc, 0xa44000, v70
	s_nop 1
	v_addc_co_u32_e32 v147, vcc, 0, v71, vcc
	v_add_co_u32_e32 v148, vcc, 0xa4d000, v70
	s_nop 1
	v_addc_co_u32_e32 v149, vcc, 0, v71, vcc
	v_add_co_u32_e32 v150, vcc, 0xa56000, v70
	s_nop 1
	v_addc_co_u32_e32 v151, vcc, 0, v71, vcc
	v_add_co_u32_e32 v152, vcc, 0xa5f000, v70
	s_nop 1
	v_addc_co_u32_e32 v153, vcc, 0, v71, vcc
	global_load_dword v110, v[138:139], off nt
	global_load_dword v106, v[140:141], off nt
	global_load_dword v102, v[142:143], off nt
	global_load_dword v97, v[144:145], off nt
	global_load_dword v92, v[146:147], off nt
	global_load_dword v89, v[148:149], off nt
	global_load_dword v85, v[150:151], off nt
	global_load_dword v80, v[152:153], off nt
	s_and_b64 vcc, exec, s[6:7]
	s_cbranch_vccnz .LBB0_332
	ds_read_b128 v[146:149], v75 offset:41536
	v_cvt_pk_bf16_f32 v138, v121, v137
	v_cvt_pk_bf16_f32 v139, v136, v133
	v_cvt_pk_bf16_f32 v140, v130, v127
	v_cvt_pk_bf16_f32 v141, v125, v118
	s_nop 0
	v_and_b32_e32 v99, 0xffff0000, v138
	v_lshlrev_b32_e32 v59, 16, v138
	v_sub_f32_e32 v99, v137, v99
	v_sub_f32_e32 v59, v121, v59
	v_cvt_pk_bf16_f32 v142, v59, v99
	v_and_b32_e32 v99, 0xffff0000, v139
	v_lshlrev_b32_e32 v59, 16, v139
	v_sub_f32_e32 v99, v133, v99
	v_sub_f32_e32 v59, v136, v59
	v_cvt_pk_bf16_f32 v143, v59, v99
	v_and_b32_e32 v99, 0xffff0000, v140
	v_lshlrev_b32_e32 v59, 16, v140
	v_sub_f32_e32 v99, v127, v99
	v_sub_f32_e32 v59, v130, v59
	v_cvt_pk_bf16_f32 v144, v59, v99
	v_add_u32_e32 v99, 0xa240, v75
	ds_read_b128 v[150:153], v99 offset:32256
	s_waitcnt lgkmcnt(1)
	v_mfma_f32_16x16x32_bf16 v[30:33], v[146:149], v[138:141], v[30:33]
	v_lshlrev_b32_e32 v59, 16, v141
	v_and_b32_e32 v121, 0xffff0000, v141
	v_sub_f32_e32 v59, v125, v59
	v_sub_f32_e32 v118, v118, v121
	v_cvt_pk_bf16_f32 v145, v59, v118
	s_nop 0
	v_mfma_f32_16x16x32_bf16 v[30:33], v[146:149], v[142:145], v[30:33]
	ds_read_b128 v[146:149], v75 offset:62272
	ds_read_b128 v[154:157], v75 offset:64576
	s_waitcnt lgkmcnt(1)
	v_mfma_f32_16x16x32_bf16 v[30:33], v[146:149], v[138:141], v[30:33]
	ds_read_b128 v[146:149], v75 offset:43840
	ds_read_b128 v[158:161], v75 offset:46144
	s_waitcnt lgkmcnt(1)
	v_mfma_f32_16x16x32_bf16 v[14:17], v[146:149], v[138:141], v[14:17]
	v_mfma_f32_16x16x32_bf16 v[14:17], v[146:149], v[142:145], v[14:17]
	s_waitcnt lgkmcnt(0)
	v_mfma_f32_16x16x32_bf16 v[34:37], v[158:161], v[138:141], v[34:37]
	v_mfma_f32_16x16x32_bf16 v[14:17], v[154:157], v[138:141], v[14:17]
	ds_read_b128 v[146:149], v99 offset:25344
	ds_read_b128 v[154:157], v99 offset:39168
	v_mfma_f32_16x16x32_bf16 v[34:37], v[158:161], v[142:145], v[34:37]
	s_waitcnt lgkmcnt(1)
	v_mfma_f32_16x16x32_bf16 v[34:37], v[146:149], v[138:141], v[34:37]
	ds_read_b128 v[146:149], v75 offset:48448
	ds_read_b128 v[158:161], v75 offset:50752
	s_waitcnt lgkmcnt(1)
	v_mfma_f32_16x16x32_bf16 v[22:25], v[146:149], v[138:141], v[22:25]
	v_mfma_f32_16x16x32_bf16 v[22:25], v[146:149], v[142:145], v[22:25]
	ds_read_b128 v[146:149], v99 offset:27648
	ds_read_b128 v[162:165], v99 offset:29952
	s_waitcnt lgkmcnt(2)
	v_mfma_f32_16x16x32_bf16 v[26:29], v[158:161], v[138:141], v[26:29]
	s_waitcnt lgkmcnt(1)
	v_mfma_f32_16x16x32_bf16 v[22:25], v[146:149], v[138:141], v[22:25]
	v_mfma_f32_16x16x32_bf16 v[26:29], v[158:161], v[142:145], v[26:29]
	ds_read_b128 v[146:149], v75 offset:53056
	ds_read_b128 v[158:161], v75 offset:55360
	s_waitcnt lgkmcnt(1)
	v_mfma_f32_16x16x32_bf16 v[10:13], v[146:149], v[138:141], v[10:13]
	v_mfma_f32_16x16x32_bf16 v[10:13], v[146:149], v[142:145], v[10:13]
	s_waitcnt lgkmcnt(0)
	v_mfma_f32_16x16x32_bf16 v[18:21], v[158:161], v[138:141], v[18:21]
	v_mfma_f32_16x16x32_bf16 v[10:13], v[150:153], v[138:141], v[10:13]
	ds_read_b128 v[146:149], v99 offset:34560
	ds_read_b128 v[150:153], v99 offset:36864
	v_mfma_f32_16x16x32_bf16 v[18:21], v[158:161], v[142:145], v[18:21]
	s_waitcnt lgkmcnt(1)
	v_mfma_f32_16x16x32_bf16 v[18:21], v[146:149], v[138:141], v[18:21]
	ds_read_b128 v[146:149], v75 offset:57664
	ds_read_b128 v[158:161], v75 offset:59968
	s_waitcnt lgkmcnt(1)
	v_mfma_f32_16x16x32_bf16 v[6:9], v[146:149], v[138:141], v[6:9]
	s_waitcnt lgkmcnt(0)
	v_mfma_f32_16x16x32_bf16 v[2:5], v[158:161], v[138:141], v[2:5]
	v_mfma_f32_16x16x32_bf16 v[6:9], v[146:149], v[142:145], v[6:9]
	v_mfma_f32_16x16x32_bf16 v[2:5], v[158:161], v[142:145], v[2:5]
	v_mfma_f32_16x16x32_bf16 v[26:29], v[162:165], v[138:141], v[26:29]
	v_mfma_f32_16x16x32_bf16 v[6:9], v[150:153], v[138:141], v[6:9]
	v_mfma_f32_16x16x32_bf16 v[2:5], v[154:157], v[138:141], v[2:5]

.LBB0_354:
	v_add_co_u32_e32 v136, vcc, 0xb40000, v70
	s_nop 1
	v_addc_co_u32_e32 v137, vcc, 0, v71, vcc
	v_add_co_u32_e32 v138, vcc, 0xb49000, v70
	s_nop 1
	v_addc_co_u32_e32 v139, vcc, 0, v71, vcc
	v_add_co_u32_e32 v140, vcc, 0xb52000, v70
	s_nop 1
	v_addc_co_u32_e32 v141, vcc, 0, v71, vcc
	v_add_co_u32_e32 v142, vcc, 0xb5b000, v70
	s_nop 1
	v_addc_co_u32_e32 v143, vcc, 0, v71, vcc
	v_add_co_u32_e32 v144, vcc, 0xb64000, v70
	s_nop 1
	v_addc_co_u32_e32 v145, vcc, 0, v71, vcc
	v_add_co_u32_e32 v146, vcc, 0xb6d000, v70
	s_nop 1
	v_addc_co_u32_e32 v147, vcc, 0, v71, vcc
	v_add_co_u32_e32 v148, vcc, 0xb76000, v70
	s_nop 1
	v_addc_co_u32_e32 v149, vcc, 0, v71, vcc
	v_add_co_u32_e32 v150, vcc, 0xb7f000, v70
	s_nop 1
	v_addc_co_u32_e32 v151, vcc, 0, v71, vcc
	global_load_dword v136, v[136:137], off nt
	s_nop 0
	global_load_dword v133, v[138:139], off nt
	global_load_dword v130, v[140:141], off nt
	global_load_dword v127, v[142:143], off nt
	global_load_dword v125, v[144:145], off nt
	global_load_dword v121, v[146:147], off nt
	global_load_dword v118, v[148:149], off nt
	global_load_dword v115, v[150:151], off nt
	v_add_co_u32_e32 v138, vcc, 0xc60000, v70
	s_nop 1
	v_addc_co_u32_e32 v139, vcc, 0, v71, vcc
	v_add_co_u32_e32 v140, vcc, 0xc69000, v70
	s_nop 1
	v_addc_co_u32_e32 v141, vcc, 0, v71, vcc
	v_add_co_u32_e32 v142, vcc, 0xc72000, v70
	s_nop 1
	v_addc_co_u32_e32 v143, vcc, 0, v71, vcc
	v_add_co_u32_e32 v144, vcc, 0xc7b000, v70
	s_nop 1
	v_addc_co_u32_e32 v145, vcc, 0, v71, vcc
	v_add_co_u32_e32 v146, vcc, 0xc84000, v70
	s_nop 1
	v_addc_co_u32_e32 v147, vcc, 0, v71, vcc
	v_add_co_u32_e32 v148, vcc, 0xc8d000, v70
	s_nop 1
	v_addc_co_u32_e32 v149, vcc, 0, v71, vcc
	v_add_co_u32_e32 v150, vcc, 0xc96000, v70
	s_nop 1
	v_addc_co_u32_e32 v151, vcc, 0, v71, vcc
	v_add_co_u32_e32 v152, vcc, 0xc9f000, v70
	s_nop 1
	v_addc_co_u32_e32 v153, vcc, 0, v71, vcc
	global_load_dword v111, v[138:139], off nt
	global_load_dword v107, v[140:141], off nt
	global_load_dword v103, v[142:143], off nt
	global_load_dword v99, v[144:145], off nt
	global_load_dword v95, v[146:147], off nt
	global_load_dword v90, v[148:149], off nt
	global_load_dword v86, v[150:151], off nt
	global_load_dword v83, v[152:153], off nt
	s_and_b64 vcc, exec, s[6:7]
	s_cbranch_vccnz .LBB0_356
	ds_read_b128 v[146:149], v75 offset:64
	ds_read_b128 v[150:153], v75 offset:39232
	v_cvt_pk_bf16_f32 v138, v87, v112
	v_cvt_pk_bf16_f32 v139, v108, v104
	v_cvt_pk_bf16_f32 v140, v100, v93
	v_cvt_pk_bf16_f32 v141, v91, v81
	s_nop 0
	v_lshlrev_b32_e32 v59, 16, v138
	v_sub_f32_e32 v59, v87, v59
	v_and_b32_e32 v87, 0xffff0000, v138
	v_sub_f32_e32 v87, v112, v87
	v_cvt_pk_bf16_f32 v142, v59, v87
	v_lshlrev_b32_e32 v59, 16, v139
	v_and_b32_e32 v87, 0xffff0000, v139
	v_sub_f32_e32 v59, v108, v59
	v_sub_f32_e32 v87, v104, v87
	s_waitcnt lgkmcnt(1)
	v_mfma_f32_16x16x32_bf16 v[30:33], v[146:149], v[138:141], v[30:33]
	v_cvt_pk_bf16_f32 v143, v59, v87
	v_lshlrev_b32_e32 v59, 16, v140
	v_and_b32_e32 v87, 0xffff0000, v140
	v_sub_f32_e32 v59, v100, v59
	v_sub_f32_e32 v87, v93, v87
	v_cvt_pk_bf16_f32 v144, v59, v87
	v_lshlrev_b32_e32 v59, 16, v141
	v_and_b32_e32 v87, 0xffff0000, v141
	v_sub_f32_e32 v59, v91, v59
	v_sub_f32_e32 v81, v81, v87
	v_cvt_pk_bf16_f32 v145, v59, v81
	s_nop 0
	v_mfma_f32_16x16x32_bf16 v[30:33], v[146:149], v[142:145], v[30:33]
	ds_read_b128 v[146:149], v75 offset:20800
	ds_read_b128 v[154:157], v75 offset:23104
	s_waitcnt lgkmcnt(1)
	v_mfma_f32_16x16x32_bf16 v[30:33], v[146:149], v[138:141], v[30:33]
	ds_read_b128 v[146:149], v75 offset:2368
	ds_read_b128 v[158:161], v75 offset:4672
	s_waitcnt lgkmcnt(1)
	v_mfma_f32_16x16x32_bf16 v[14:17], v[146:149], v[138:141], v[14:17]
	v_mfma_f32_16x16x32_bf16 v[14:17], v[146:149], v[142:145], v[14:17]
	s_waitcnt lgkmcnt(0)
	v_mfma_f32_16x16x32_bf16 v[34:37], v[158:161], v[138:141], v[34:37]
	v_mfma_f32_16x16x32_bf16 v[14:17], v[154:157], v[138:141], v[14:17]
	ds_read_b128 v[146:149], v75 offset:25408
	ds_read_b128 v[154:157], v75 offset:27712
	v_mfma_f32_16x16x32_bf16 v[34:37], v[158:161], v[142:145], v[34:37]
	s_waitcnt lgkmcnt(1)
	v_mfma_f32_16x16x32_bf16 v[34:37], v[146:149], v[138:141], v[34:37]
	ds_read_b128 v[146:149], v75 offset:6976
	ds_read_b128 v[158:161], v75 offset:9280
	s_waitcnt lgkmcnt(1)
	v_mfma_f32_16x16x32_bf16 v[22:25], v[146:149], v[138:141], v[22:25]
	v_mfma_f32_16x16x32_bf16 v[22:25], v[146:149], v[142:145], v[22:25]
	s_waitcnt lgkmcnt(0)
	v_mfma_f32_16x16x32_bf16 v[26:29], v[158:161], v[138:141], v[26:29]
	v_mfma_f32_16x16x32_bf16 v[22:25], v[154:157], v[138:141], v[22:25]
	ds_read_b128 v[146:149], v75 offset:30016
	ds_read_b128 v[154:157], v75 offset:32320
	v_mfma_f32_16x16x32_bf16 v[26:29], v[158:161], v[142:145], v[26:29]
	s_waitcnt lgkmcnt(1)
	v_mfma_f32_16x16x32_bf16 v[26:29], v[146:149], v[138:141], v[26:29]
	ds_read_b128 v[146:149], v75 offset:11584
	ds_read_b128 v[158:161], v75 offset:13888
	s_waitcnt lgkmcnt(1)
	v_mfma_f32_16x16x32_bf16 v[10:13], v[146:149], v[138:141], v[10:13]
	v_mfma_f32_16x16x32_bf16 v[10:13], v[146:149], v[142:145], v[10:13]
	s_waitcnt lgkmcnt(0)
	v_mfma_f32_16x16x32_bf16 v[18:21], v[158:161], v[138:141], v[18:21]
	v_mfma_f32_16x16x32_bf16 v[10:13], v[154:157], v[138:141], v[10:13]
	ds_read_b128 v[146:149], v75 offset:34624
	ds_read_b128 v[154:157], v75 offset:36928
	v_mfma_f32_16x16x32_bf16 v[18:21], v[158:161], v[142:145], v[18:21]
	s_waitcnt lgkmcnt(1)
	v_mfma_f32_16x16x32_bf16 v[18:21], v[146:149], v[138:141], v[18:21]
	ds_read_b128 v[146:149], v75 offset:16192
	ds_read_b128 v[158:161], v75 offset:18496
	s_waitcnt lgkmcnt(1)
	v_mfma_f32_16x16x32_bf16 v[6:9], v[146:149], v[138:141], v[6:9]
	s_waitcnt lgkmcnt(0)
	v_mfma_f32_16x16x32_bf16 v[2:5], v[158:161], v[138:141], v[2:5]
	v_mfma_f32_16x16x32_bf16 v[6:9], v[146:149], v[142:145], v[6:9]
	v_mfma_f32_16x16x32_bf16 v[2:5], v[158:161], v[142:145], v[2:5]
	v_mfma_f32_16x16x32_bf16 v[6:9], v[154:157], v[138:141], v[6:9]
	v_mfma_f32_16x16x32_bf16 v[2:5], v[150:153], v[138:141], v[2:5]

.LBB0_378:
	v_add_co_u32_e32 v138, vcc, 0xd80000, v70
	s_nop 1
	v_addc_co_u32_e32 v139, vcc, 0, v71, vcc
	v_add_co_u32_e32 v140, vcc, 0xd89000, v70
	s_nop 1
	v_addc_co_u32_e32 v141, vcc, 0, v71, vcc
	v_add_co_u32_e32 v142, vcc, 0xd92000, v70
	s_nop 1
	v_addc_co_u32_e32 v143, vcc, 0, v71, vcc
	v_add_co_u32_e32 v144, vcc, 0xd9b000, v70
	s_nop 1
	v_addc_co_u32_e32 v145, vcc, 0, v71, vcc
	v_add_co_u32_e32 v146, vcc, 0xda4000, v70
	s_nop 1
	v_addc_co_u32_e32 v147, vcc, 0, v71, vcc
	v_add_co_u32_e32 v148, vcc, 0xdad000, v70
	s_nop 1
	v_addc_co_u32_e32 v149, vcc, 0, v71, vcc
	v_add_co_u32_e32 v150, vcc, 0xdb6000, v70
	s_nop 1
	v_addc_co_u32_e32 v151, vcc, 0, v71, vcc
	v_add_co_u32_e32 v152, vcc, 0xdbf000, v70
	s_nop 1
	v_addc_co_u32_e32 v153, vcc, 0, v71, vcc
	global_load_dword v137, v[138:139], off nt
	global_load_dword v134, v[140:141], off nt
	global_load_dword v131, v[142:143], off nt
	global_load_dword v128, v[144:145], off nt
	global_load_dword v124, v[146:147], off nt
	global_load_dword v122, v[148:149], off nt
	global_load_dword v119, v[150:151], off nt
	global_load_dword v114, v[152:153], off nt
	v_add_co_u32_e32 v138, vcc, 0xea0000, v70
	s_nop 1
	v_addc_co_u32_e32 v139, vcc, 0, v71, vcc
	v_add_co_u32_e32 v140, vcc, 0xea9000, v70
	s_nop 1
	v_addc_co_u32_e32 v141, vcc, 0, v71, vcc
	v_add_co_u32_e32 v142, vcc, 0xeb2000, v70
	s_nop 1
	v_addc_co_u32_e32 v143, vcc, 0, v71, vcc
	v_add_co_u32_e32 v144, vcc, 0xebb000, v70
	s_nop 1
	v_addc_co_u32_e32 v145, vcc, 0, v71, vcc
	v_add_co_u32_e32 v146, vcc, 0xec4000, v70
	s_nop 1
	v_addc_co_u32_e32 v147, vcc, 0, v71, vcc
	v_add_co_u32_e32 v148, vcc, 0xecd000, v70
	s_nop 1
	v_addc_co_u32_e32 v149, vcc, 0, v71, vcc
	v_add_co_u32_e32 v150, vcc, 0xed6000, v70
	s_nop 1
	v_addc_co_u32_e32 v151, vcc, 0, v71, vcc
	v_add_co_u32_e32 v152, vcc, 0xedf000, v70
	s_nop 1
	v_addc_co_u32_e32 v153, vcc, 0, v71, vcc
	global_load_dword v112, v[138:139], off nt
	global_load_dword v108, v[140:141], off nt
	global_load_dword v104, v[142:143], off nt
	global_load_dword v100, v[144:145], off nt
	global_load_dword v93, v[146:147], off nt
	global_load_dword v91, v[148:149], off nt
	global_load_dword v87, v[150:151], off nt
	global_load_dword v81, v[152:153], off nt
	s_and_b64 vcc, exec, s[6:7]
	s_cbranch_vccnz .LBB0_380
	ds_read_b128 v[146:149], v75 offset:41536
	v_cvt_pk_bf16_f32 v138, v109, v105
	v_cvt_pk_bf16_f32 v139, v101, v96
	v_cvt_pk_bf16_f32 v140, v94, v88
	v_cvt_pk_bf16_f32 v141, v84, v82
	s_nop 0
	v_lshlrev_b32_e32 v59, 16, v138
	v_sub_f32_e32 v59, v109, v59
	v_and_b32_e32 v109, 0xffff0000, v138
	v_sub_f32_e32 v105, v105, v109
	v_cvt_pk_bf16_f32 v142, v59, v105
	v_lshlrev_b32_e32 v59, 16, v139
	v_sub_f32_e32 v59, v101, v59
	v_and_b32_e32 v101, 0xffff0000, v139
	v_sub_f32_e32 v96, v96, v101
	v_cvt_pk_bf16_f32 v143, v59, v96
	v_lshlrev_b32_e32 v59, 16, v140
	v_sub_f32_e32 v59, v94, v59
	v_and_b32_e32 v94, 0xffff0000, v140
	v_sub_f32_e32 v88, v88, v94
	v_cvt_pk_bf16_f32 v144, v59, v88
	v_lshlrev_b32_e32 v59, 16, v141
	v_sub_f32_e32 v59, v84, v59
	v_add_u32_e32 v84, 0xa240, v75
	ds_read_b128 v[150:153], v84 offset:32256
	s_waitcnt lgkmcnt(1)
	v_mfma_f32_16x16x32_bf16 v[30:33], v[146:149], v[138:141], v[30:33]
	v_and_b32_e32 v88, 0xffff0000, v141
	v_sub_f32_e32 v82, v82, v88
	v_cvt_pk_bf16_f32 v145, v59, v82
	s_nop 0
	v_mfma_f32_16x16x32_bf16 v[30:33], v[146:149], v[142:145], v[30:33]
	ds_read_b128 v[146:149], v75 offset:62272
	ds_read_b128 v[154:157], v75 offset:64576
	s_waitcnt lgkmcnt(1)
	v_mfma_f32_16x16x32_bf16 v[30:33], v[146:149], v[138:141], v[30:33]
	ds_read_b128 v[146:149], v75 offset:43840
	ds_read_b128 v[158:161], v75 offset:46144
	s_waitcnt lgkmcnt(1)
	v_mfma_f32_16x16x32_bf16 v[14:17], v[146:149], v[138:141], v[14:17]
	v_mfma_f32_16x16x32_bf16 v[14:17], v[146:149], v[142:145], v[14:17]
	s_waitcnt lgkmcnt(0)
	v_mfma_f32_16x16x32_bf16 v[34:37], v[158:161], v[138:141], v[34:37]
	v_mfma_f32_16x16x32_bf16 v[14:17], v[154:157], v[138:141], v[14:17]
	ds_read_b128 v[146:149], v84 offset:25344
	ds_read_b128 v[154:157], v84 offset:39168
	v_mfma_f32_16x16x32_bf16 v[34:37], v[158:161], v[142:145], v[34:37]
	s_waitcnt lgkmcnt(1)
	v_mfma_f32_16x16x32_bf16 v[34:37], v[146:149], v[138:141], v[34:37]
	ds_read_b128 v[146:149], v75 offset:48448
	ds_read_b128 v[158:161], v75 offset:50752
	s_waitcnt lgkmcnt(1)
	v_mfma_f32_16x16x32_bf16 v[22:25], v[146:149], v[138:141], v[22:25]
	v_mfma_f32_16x16x32_bf16 v[22:25], v[146:149], v[142:145], v[22:25]
	ds_read_b128 v[146:149], v84 offset:27648
	ds_read_b128 v[162:165], v84 offset:29952
	s_waitcnt lgkmcnt(2)
	v_mfma_f32_16x16x32_bf16 v[26:29], v[158:161], v[138:141], v[26:29]
	s_waitcnt lgkmcnt(1)
	v_mfma_f32_16x16x32_bf16 v[22:25], v[146:149], v[138:141], v[22:25]
	v_mfma_f32_16x16x32_bf16 v[26:29], v[158:161], v[142:145], v[26:29]
	ds_read_b128 v[146:149], v75 offset:53056
	ds_read_b128 v[158:161], v75 offset:55360
	s_waitcnt lgkmcnt(1)
	v_mfma_f32_16x16x32_bf16 v[10:13], v[146:149], v[138:141], v[10:13]
	v_mfma_f32_16x16x32_bf16 v[10:13], v[146:149], v[142:145], v[10:13]
	s_waitcnt lgkmcnt(0)
	v_mfma_f32_16x16x32_bf16 v[18:21], v[158:161], v[138:141], v[18:21]
	v_mfma_f32_16x16x32_bf16 v[10:13], v[150:153], v[138:141], v[10:13]
	ds_read_b128 v[146:149], v84 offset:34560
	ds_read_b128 v[150:153], v84 offset:36864
	v_mfma_f32_16x16x32_bf16 v[18:21], v[158:161], v[142:145], v[18:21]
	s_waitcnt lgkmcnt(1)
	v_mfma_f32_16x16x32_bf16 v[18:21], v[146:149], v[138:141], v[18:21]
	ds_read_b128 v[146:149], v75 offset:57664
	ds_read_b128 v[158:161], v75 offset:59968
	s_waitcnt lgkmcnt(1)
	v_mfma_f32_16x16x32_bf16 v[6:9], v[146:149], v[138:141], v[6:9]
	s_waitcnt lgkmcnt(0)
	v_mfma_f32_16x16x32_bf16 v[2:5], v[158:161], v[138:141], v[2:5]
	v_mfma_f32_16x16x32_bf16 v[6:9], v[146:149], v[142:145], v[6:9]
	v_mfma_f32_16x16x32_bf16 v[2:5], v[158:161], v[142:145], v[2:5]
	v_mfma_f32_16x16x32_bf16 v[26:29], v[162:165], v[138:141], v[26:29]
	v_mfma_f32_16x16x32_bf16 v[6:9], v[150:153], v[138:141], v[6:9]
	v_mfma_f32_16x16x32_bf16 v[2:5], v[154:157], v[138:141], v[2:5]

.LBB0_402:
	v_add_co_u32_e32 v116, vcc, 0xfc0000, v70
	s_nop 1
	v_addc_co_u32_e32 v117, vcc, 0, v71, vcc
	v_add_co_u32_e32 v140, vcc, 0xfc9000, v70
	s_nop 1
	v_addc_co_u32_e32 v141, vcc, 0, v71, vcc
	v_add_co_u32_e32 v142, vcc, 0xfd2000, v70
	s_nop 1
	v_addc_co_u32_e32 v143, vcc, 0, v71, vcc
	v_add_co_u32_e32 v144, vcc, 0xfdb000, v70
	s_nop 1
	v_addc_co_u32_e32 v145, vcc, 0, v71, vcc
	v_add_co_u32_e32 v146, vcc, 0xfe4000, v70
	s_nop 1
	v_addc_co_u32_e32 v147, vcc, 0, v71, vcc
	v_add_co_u32_e32 v148, vcc, 0xfed000, v70
	s_nop 1
	v_addc_co_u32_e32 v149, vcc, 0, v71, vcc
	v_add_co_u32_e32 v150, vcc, 0xff6000, v70
	s_nop 1
	v_addc_co_u32_e32 v151, vcc, 0, v71, vcc
	v_add_co_u32_e32 v152, vcc, 0xfff000, v70
	s_nop 1
	v_addc_co_u32_e32 v153, vcc, 0, v71, vcc
	global_load_dword v138, v[116:117], off nt
	global_load_dword v135, v[140:141], off nt
	global_load_dword v132, v[142:143], off nt
	global_load_dword v129, v[144:145], off nt
	global_load_dword v126, v[146:147], off nt
	global_load_dword v120, v[148:149], off nt
	global_load_dword v117, v[150:151], off nt
	global_load_dword v116, v[152:153], off nt
	v_add_co_u32_e32 v140, vcc, 0x10e0000, v70
	s_nop 1
	v_addc_co_u32_e32 v141, vcc, 0, v71, vcc
	v_add_co_u32_e32 v142, vcc, 0x10e9000, v70
	s_nop 1
	v_addc_co_u32_e32 v143, vcc, 0, v71, vcc
	v_add_co_u32_e32 v144, vcc, 0x10f2000, v70
	s_nop 1
	v_addc_co_u32_e32 v145, vcc, 0, v71, vcc
	v_add_co_u32_e32 v146, vcc, 0x10fb000, v70
	s_nop 1
	v_addc_co_u32_e32 v147, vcc, 0, v71, vcc
	v_add_co_u32_e32 v148, vcc, 0x1104000, v70
	s_nop 1
	v_addc_co_u32_e32 v149, vcc, 0, v71, vcc
	v_add_co_u32_e32 v150, vcc, 0x110d000, v70
	s_nop 1
	v_addc_co_u32_e32 v151, vcc, 0, v71, vcc
	v_add_co_u32_e32 v152, vcc, 0x1116000, v70
	s_nop 1
	v_addc_co_u32_e32 v153, vcc, 0, v71, vcc
	v_add_co_u32_e32 v154, vcc, 0x111f000, v70
	s_nop 1
	v_addc_co_u32_e32 v155, vcc, 0, v71, vcc
	global_load_dword v109, v[140:141], off nt
	global_load_dword v105, v[142:143], off nt
	global_load_dword v101, v[144:145], off nt
	global_load_dword v96, v[146:147], off nt
	global_load_dword v94, v[148:149], off nt
	global_load_dword v88, v[150:151], off nt
	global_load_dword v84, v[152:153], off nt
	global_load_dword v82, v[154:155], off nt
	s_and_b64 vcc, exec, s[6:7]
	s_cbranch_vccnz .LBB0_404
	ds_read_b128 v[148:151], v75 offset:64
	ds_read_b128 v[152:155], v75 offset:39232
	v_cvt_pk_bf16_f32 v140, v110, v106
	v_cvt_pk_bf16_f32 v141, v102, v97
	v_cvt_pk_bf16_f32 v142, v92, v89
	v_cvt_pk_bf16_f32 v143, v85, v80
	s_nop 0
	v_lshlrev_b32_e32 v59, 16, v140
	v_sub_f32_e32 v59, v110, v59
	v_and_b32_e32 v110, 0xffff0000, v140
	v_sub_f32_e32 v106, v106, v110
	v_cvt_pk_bf16_f32 v144, v59, v106
	v_lshlrev_b32_e32 v59, 16, v141
	v_sub_f32_e32 v59, v102, v59
	v_and_b32_e32 v102, 0xffff0000, v141
	v_sub_f32_e32 v97, v97, v102
	v_cvt_pk_bf16_f32 v145, v59, v97
	v_lshlrev_b32_e32 v59, 16, v142
	s_waitcnt lgkmcnt(1)
	v_mfma_f32_16x16x32_bf16 v[30:33], v[148:151], v[140:143], v[30:33]
	v_sub_f32_e32 v59, v92, v59
	v_and_b32_e32 v92, 0xffff0000, v142
	v_sub_f32_e32 v89, v89, v92
	v_cvt_pk_bf16_f32 v146, v59, v89
	v_lshlrev_b32_e32 v59, 16, v143
	v_sub_f32_e32 v59, v85, v59
	v_and_b32_e32 v85, 0xffff0000, v143
	v_sub_f32_e32 v80, v80, v85
	v_cvt_pk_bf16_f32 v147, v59, v80
	s_nop 0
	v_mfma_f32_16x16x32_bf16 v[30:33], v[148:151], v[144:147], v[30:33]
	ds_read_b128 v[148:151], v75 offset:20800
	ds_read_b128 v[156:159], v75 offset:23104
	s_waitcnt lgkmcnt(1)
	v_mfma_f32_16x16x32_bf16 v[30:33], v[148:151], v[140:143], v[30:33]
	ds_read_b128 v[148:151], v75 offset:2368
	ds_read_b128 v[160:163], v75 offset:4672
	s_waitcnt lgkmcnt(1)
	v_mfma_f32_16x16x32_bf16 v[14:17], v[148:151], v[140:143], v[14:17]
	v_mfma_f32_16x16x32_bf16 v[14:17], v[148:151], v[144:147], v[14:17]
	s_waitcnt lgkmcnt(0)
	v_mfma_f32_16x16x32_bf16 v[34:37], v[160:163], v[140:143], v[34:37]
	v_mfma_f32_16x16x32_bf16 v[14:17], v[156:159], v[140:143], v[14:17]
	ds_read_b128 v[148:151], v75 offset:25408
	ds_read_b128 v[156:159], v75 offset:27712
	v_mfma_f32_16x16x32_bf16 v[34:37], v[160:163], v[144:147], v[34:37]
	s_waitcnt lgkmcnt(1)
	v_mfma_f32_16x16x32_bf16 v[34:37], v[148:151], v[140:143], v[34:37]
	ds_read_b128 v[148:151], v75 offset:6976
	ds_read_b128 v[160:163], v75 offset:9280
	s_waitcnt lgkmcnt(1)
	v_mfma_f32_16x16x32_bf16 v[22:25], v[148:151], v[140:143], v[22:25]
	v_mfma_f32_16x16x32_bf16 v[22:25], v[148:151], v[144:147], v[22:25]
	s_waitcnt lgkmcnt(0)
	v_mfma_f32_16x16x32_bf16 v[26:29], v[160:163], v[140:143], v[26:29]
	v_mfma_f32_16x16x32_bf16 v[22:25], v[156:159], v[140:143], v[22:25]
	ds_read_b128 v[148:151], v75 offset:30016
	ds_read_b128 v[156:159], v75 offset:32320
	v_mfma_f32_16x16x32_bf16 v[26:29], v[160:163], v[144:147], v[26:29]
	s_waitcnt lgkmcnt(1)
	v_mfma_f32_16x16x32_bf16 v[26:29], v[148:151], v[140:143], v[26:29]
	ds_read_b128 v[148:151], v75 offset:11584
	ds_read_b128 v[160:163], v75 offset:13888
	s_waitcnt lgkmcnt(1)
	v_mfma_f32_16x16x32_bf16 v[10:13], v[148:151], v[140:143], v[10:13]
	v_mfma_f32_16x16x32_bf16 v[10:13], v[148:151], v[144:147], v[10:13]
	s_waitcnt lgkmcnt(0)
	v_mfma_f32_16x16x32_bf16 v[18:21], v[160:163], v[140:143], v[18:21]
	v_mfma_f32_16x16x32_bf16 v[10:13], v[156:159], v[140:143], v[10:13]
	ds_read_b128 v[148:151], v75 offset:34624
	ds_read_b128 v[156:159], v75 offset:36928
	v_mfma_f32_16x16x32_bf16 v[18:21], v[160:163], v[144:147], v[18:21]
	s_waitcnt lgkmcnt(1)
	v_mfma_f32_16x16x32_bf16 v[18:21], v[148:151], v[140:143], v[18:21]
	ds_read_b128 v[148:151], v75 offset:16192
	ds_read_b128 v[160:163], v75 offset:18496
	s_waitcnt lgkmcnt(1)
	v_mfma_f32_16x16x32_bf16 v[6:9], v[148:151], v[140:143], v[6:9]
	s_waitcnt lgkmcnt(0)
	v_mfma_f32_16x16x32_bf16 v[2:5], v[160:163], v[140:143], v[2:5]
	v_mfma_f32_16x16x32_bf16 v[6:9], v[148:151], v[144:147], v[6:9]
	v_mfma_f32_16x16x32_bf16 v[2:5], v[160:163], v[144:147], v[2:5]
	v_mfma_f32_16x16x32_bf16 v[6:9], v[156:159], v[140:143], v[6:9]
	v_mfma_f32_16x16x32_bf16 v[2:5], v[152:155], v[140:143], v[2:5]

.LBB0_426:
	v_add_co_u32_e32 v140, vcc, 0x1200000, v70
	s_nop 1
	v_addc_co_u32_e32 v141, vcc, 0, v71, vcc
	v_add_co_u32_e32 v142, vcc, 0x1209000, v70
	s_nop 1
	v_addc_co_u32_e32 v143, vcc, 0, v71, vcc
	v_add_co_u32_e32 v144, vcc, 0x1212000, v70
	s_nop 1
	v_addc_co_u32_e32 v145, vcc, 0, v71, vcc
	v_add_co_u32_e32 v146, vcc, 0x121b000, v70
	s_nop 1
	v_addc_co_u32_e32 v147, vcc, 0, v71, vcc
	v_add_co_u32_e32 v148, vcc, 0x1224000, v70
	s_nop 1
	v_addc_co_u32_e32 v149, vcc, 0, v71, vcc
	v_add_co_u32_e32 v150, vcc, 0x122d000, v70
	s_nop 1
	v_addc_co_u32_e32 v151, vcc, 0, v71, vcc
	v_add_co_u32_e32 v152, vcc, 0x1236000, v70
	s_nop 1
	v_addc_co_u32_e32 v153, vcc, 0, v71, vcc
	v_add_co_u32_e32 v154, vcc, 0x123f000, v70
	s_nop 1
	v_addc_co_u32_e32 v155, vcc, 0, v71, vcc
	global_load_dword v136, v[140:141], off nt
	global_load_dword v133, v[142:143], off nt
	global_load_dword v130, v[144:145], off nt
	global_load_dword v127, v[146:147], off nt
	global_load_dword v123, v[148:149], off nt
	global_load_dword v121, v[150:151], off nt
	global_load_dword v118, v[152:153], off nt
	global_load_dword v113, v[154:155], off nt
	v_add_co_u32_e32 v140, vcc, 0x1320000, v70
	s_nop 1
	v_addc_co_u32_e32 v141, vcc, 0, v71, vcc
	v_add_co_u32_e32 v142, vcc, 0x1329000, v70
	s_nop 1
	v_addc_co_u32_e32 v143, vcc, 0, v71, vcc
	v_add_co_u32_e32 v144, vcc, 0x1332000, v70
	s_nop 1
	v_addc_co_u32_e32 v145, vcc, 0, v71, vcc
	v_add_co_u32_e32 v146, vcc, 0x133b000, v70
	s_nop 1
	v_addc_co_u32_e32 v147, vcc, 0, v71, vcc
	v_add_co_u32_e32 v148, vcc, 0x1344000, v70
	s_nop 1
	v_addc_co_u32_e32 v149, vcc, 0, v71, vcc
	v_add_co_u32_e32 v150, vcc, 0x134d000, v70
	s_nop 1
	v_addc_co_u32_e32 v151, vcc, 0, v71, vcc
	v_add_co_u32_e32 v152, vcc, 0x1356000, v70
	s_nop 1
	v_addc_co_u32_e32 v153, vcc, 0, v71, vcc
	v_add_co_u32_e32 v154, vcc, 0x135f000, v70
	s_nop 1
	v_addc_co_u32_e32 v155, vcc, 0, v71, vcc
	global_load_dword v110, v[140:141], off nt
	global_load_dword v106, v[142:143], off nt
	global_load_dword v102, v[144:145], off nt
	global_load_dword v97, v[146:147], off nt
	global_load_dword v92, v[148:149], off nt
	global_load_dword v89, v[150:151], off nt
	global_load_dword v85, v[152:153], off nt
	global_load_dword v80, v[154:155], off nt
	s_and_b64 vcc, exec, s[6:7]
	s_cbranch_vccnz .LBB0_428
	ds_read_b128 v[148:151], v75 offset:41536
	v_cvt_pk_bf16_f32 v140, v111, v107
	v_cvt_pk_bf16_f32 v141, v103, v99
	v_cvt_pk_bf16_f32 v142, v95, v90
	v_cvt_pk_bf16_f32 v143, v86, v83
	s_nop 0
	v_lshlrev_b32_e32 v59, 16, v140
	v_sub_f32_e32 v59, v111, v59
	v_and_b32_e32 v111, 0xffff0000, v140
	v_sub_f32_e32 v107, v107, v111
	v_cvt_pk_bf16_f32 v144, v59, v107
	v_lshlrev_b32_e32 v59, 16, v141
	v_sub_f32_e32 v59, v103, v59
	v_and_b32_e32 v103, 0xffff0000, v141
	v_sub_f32_e32 v99, v99, v103
	v_cvt_pk_bf16_f32 v145, v59, v99
	v_lshlrev_b32_e32 v59, 16, v142
	v_sub_f32_e32 v59, v95, v59
	v_and_b32_e32 v95, 0xffff0000, v142
	v_sub_f32_e32 v90, v90, v95
	v_cvt_pk_bf16_f32 v146, v59, v90
	v_lshlrev_b32_e32 v59, 16, v143
	v_sub_f32_e32 v59, v86, v59
	v_add_u32_e32 v86, 0xa240, v75
	ds_read_b128 v[152:155], v86 offset:32256
	s_waitcnt lgkmcnt(1)
	v_mfma_f32_16x16x32_bf16 v[30:33], v[148:151], v[140:143], v[30:33]
	v_and_b32_e32 v90, 0xffff0000, v143
	v_sub_f32_e32 v83, v83, v90
	v_cvt_pk_bf16_f32 v147, v59, v83
	s_nop 0
	v_mfma_f32_16x16x32_bf16 v[30:33], v[148:151], v[144:147], v[30:33]
	ds_read_b128 v[148:151], v75 offset:62272
	ds_read_b128 v[156:159], v75 offset:64576
	s_waitcnt lgkmcnt(1)
	v_mfma_f32_16x16x32_bf16 v[30:33], v[148:151], v[140:143], v[30:33]
	ds_read_b128 v[148:151], v75 offset:43840
	ds_read_b128 v[160:163], v75 offset:46144
	s_waitcnt lgkmcnt(1)
	v_mfma_f32_16x16x32_bf16 v[14:17], v[148:151], v[140:143], v[14:17]
	v_mfma_f32_16x16x32_bf16 v[14:17], v[148:151], v[144:147], v[14:17]
	s_waitcnt lgkmcnt(0)
	v_mfma_f32_16x16x32_bf16 v[34:37], v[160:163], v[140:143], v[34:37]
	v_mfma_f32_16x16x32_bf16 v[14:17], v[156:159], v[140:143], v[14:17]
	ds_read_b128 v[148:151], v86 offset:25344
	ds_read_b128 v[156:159], v86 offset:39168
	v_mfma_f32_16x16x32_bf16 v[34:37], v[160:163], v[144:147], v[34:37]
	s_waitcnt lgkmcnt(1)
	v_mfma_f32_16x16x32_bf16 v[34:37], v[148:151], v[140:143], v[34:37]
	ds_read_b128 v[148:151], v75 offset:48448
	ds_read_b128 v[160:163], v75 offset:50752
	s_waitcnt lgkmcnt(1)
	v_mfma_f32_16x16x32_bf16 v[22:25], v[148:151], v[140:143], v[22:25]
	v_mfma_f32_16x16x32_bf16 v[22:25], v[148:151], v[144:147], v[22:25]
	ds_read_b128 v[148:151], v86 offset:27648
	ds_read_b128 v[164:167], v86 offset:29952
	s_waitcnt lgkmcnt(2)
	v_mfma_f32_16x16x32_bf16 v[26:29], v[160:163], v[140:143], v[26:29]
	s_waitcnt lgkmcnt(1)
	v_mfma_f32_16x16x32_bf16 v[22:25], v[148:151], v[140:143], v[22:25]
	v_mfma_f32_16x16x32_bf16 v[26:29], v[160:163], v[144:147], v[26:29]
	ds_read_b128 v[148:151], v75 offset:53056
	ds_read_b128 v[160:163], v75 offset:55360
	s_waitcnt lgkmcnt(1)
	v_mfma_f32_16x16x32_bf16 v[10:13], v[148:151], v[140:143], v[10:13]
	v_mfma_f32_16x16x32_bf16 v[10:13], v[148:151], v[144:147], v[10:13]
	s_waitcnt lgkmcnt(0)
	v_mfma_f32_16x16x32_bf16 v[18:21], v[160:163], v[140:143], v[18:21]
	v_mfma_f32_16x16x32_bf16 v[10:13], v[152:155], v[140:143], v[10:13]
	ds_read_b128 v[148:151], v86 offset:34560
	ds_read_b128 v[152:155], v86 offset:36864
	v_mfma_f32_16x16x32_bf16 v[18:21], v[160:163], v[144:147], v[18:21]
	s_waitcnt lgkmcnt(1)
	v_mfma_f32_16x16x32_bf16 v[18:21], v[148:151], v[140:143], v[18:21]
	ds_read_b128 v[148:151], v75 offset:57664
	ds_read_b128 v[160:163], v75 offset:59968
	s_waitcnt lgkmcnt(1)
	v_mfma_f32_16x16x32_bf16 v[6:9], v[148:151], v[140:143], v[6:9]
	s_waitcnt lgkmcnt(0)
	v_mfma_f32_16x16x32_bf16 v[2:5], v[160:163], v[140:143], v[2:5]
	v_mfma_f32_16x16x32_bf16 v[6:9], v[148:151], v[144:147], v[6:9]
	v_mfma_f32_16x16x32_bf16 v[2:5], v[160:163], v[144:147], v[2:5]
	v_mfma_f32_16x16x32_bf16 v[26:29], v[164:167], v[140:143], v[26:29]
	v_mfma_f32_16x16x32_bf16 v[6:9], v[152:155], v[140:143], v[6:9]
	v_mfma_f32_16x16x32_bf16 v[2:5], v[156:159], v[140:143], v[2:5]

.LBB0_450:
	v_add_co_u32_e32 v114, vcc, 0x1440000, v70
	s_nop 1
	v_addc_co_u32_e32 v115, vcc, 0, v71, vcc
	v_add_co_u32_e32 v124, vcc, 0x1449000, v70
	s_nop 1
	v_addc_co_u32_e32 v125, vcc, 0, v71, vcc
	v_add_co_u32_e32 v140, vcc, 0x1452000, v70
	s_nop 1
	v_addc_co_u32_e32 v141, vcc, 0, v71, vcc
	v_add_co_u32_e32 v142, vcc, 0x145b000, v70
	s_nop 1
	v_addc_co_u32_e32 v143, vcc, 0, v71, vcc
	v_add_co_u32_e32 v144, vcc, 0x1464000, v70
	s_nop 1
	v_addc_co_u32_e32 v145, vcc, 0, v71, vcc
	v_add_co_u32_e32 v146, vcc, 0x146d000, v70
	s_nop 1
	v_addc_co_u32_e32 v147, vcc, 0, v71, vcc
	v_add_co_u32_e32 v148, vcc, 0x1476000, v70
	s_nop 1
	v_addc_co_u32_e32 v149, vcc, 0, v71, vcc
	v_add_co_u32_e32 v150, vcc, 0x147f000, v70
	s_nop 1
	v_addc_co_u32_e32 v151, vcc, 0, v71, vcc
	global_load_dword v137, v[114:115], off nt
	global_load_dword v134, v[124:125], off nt
	global_load_dword v131, v[140:141], off nt
	global_load_dword v128, v[142:143], off nt
	s_nop 0
	global_load_dword v125, v[144:145], off nt
	global_load_dword v122, v[146:147], off nt
	global_load_dword v119, v[148:149], off nt
	global_load_dword v115, v[150:151], off nt
	v_add_co_u32_e32 v140, vcc, 0x1560000, v70
	s_nop 1
	v_addc_co_u32_e32 v141, vcc, 0, v71, vcc
	v_add_co_u32_e32 v142, vcc, 0x1569000, v70
	s_nop 1
	v_addc_co_u32_e32 v143, vcc, 0, v71, vcc
	v_add_co_u32_e32 v144, vcc, 0x1572000, v70
	s_nop 1
	v_addc_co_u32_e32 v145, vcc, 0, v71, vcc
	v_add_co_u32_e32 v146, vcc, 0x157b000, v70
	s_nop 1
	v_addc_co_u32_e32 v147, vcc, 0, v71, vcc
	v_add_co_u32_e32 v148, vcc, 0x1584000, v70
	s_nop 1
	v_addc_co_u32_e32 v149, vcc, 0, v71, vcc
	v_add_co_u32_e32 v150, vcc, 0x158d000, v70
	s_nop 1
	v_addc_co_u32_e32 v151, vcc, 0, v71, vcc
	v_add_co_u32_e32 v152, vcc, 0x1596000, v70
	s_nop 1
	v_addc_co_u32_e32 v153, vcc, 0, v71, vcc
	v_add_co_u32_e32 v154, vcc, 0x159f000, v70
	s_nop 1
	v_addc_co_u32_e32 v155, vcc, 0, v71, vcc
	global_load_dword v111, v[140:141], off nt
	global_load_dword v107, v[142:143], off nt
	global_load_dword v103, v[144:145], off nt
	global_load_dword v99, v[146:147], off nt
	global_load_dword v95, v[148:149], off nt
	global_load_dword v90, v[150:151], off nt
	global_load_dword v86, v[152:153], off nt
	global_load_dword v83, v[154:155], off nt
	s_and_b64 vcc, exec, s[6:7]
	s_cbranch_vccnz .LBB0_452
	ds_read_b128 v[148:151], v75 offset:64
	ds_read_b128 v[152:155], v75 offset:39232
	v_cvt_pk_bf16_f32 v140, v112, v108
	v_cvt_pk_bf16_f32 v141, v104, v100
	v_cvt_pk_bf16_f32 v142, v93, v91
	v_cvt_pk_bf16_f32 v143, v87, v81
	s_nop 0
	v_lshlrev_b32_e32 v59, 16, v140
	v_sub_f32_e32 v59, v112, v59
	v_and_b32_e32 v112, 0xffff0000, v140
	v_sub_f32_e32 v108, v108, v112
	v_cvt_pk_bf16_f32 v144, v59, v108
	v_lshlrev_b32_e32 v59, 16, v141
	v_sub_f32_e32 v59, v104, v59
	v_and_b32_e32 v104, 0xffff0000, v141
	v_sub_f32_e32 v100, v100, v104
	v_cvt_pk_bf16_f32 v145, v59, v100
	v_lshlrev_b32_e32 v59, 16, v142
	s_waitcnt lgkmcnt(1)
	v_mfma_f32_16x16x32_bf16 v[30:33], v[148:151], v[140:143], v[30:33]
	v_sub_f32_e32 v59, v93, v59
	v_and_b32_e32 v93, 0xffff0000, v142
	v_sub_f32_e32 v91, v91, v93
	v_cvt_pk_bf16_f32 v146, v59, v91
	v_lshlrev_b32_e32 v59, 16, v143
	v_sub_f32_e32 v59, v87, v59
	v_and_b32_e32 v87, 0xffff0000, v143
	v_sub_f32_e32 v81, v81, v87
	v_cvt_pk_bf16_f32 v147, v59, v81
	s_nop 0
	v_mfma_f32_16x16x32_bf16 v[30:33], v[148:151], v[144:147], v[30:33]
	ds_read_b128 v[148:151], v75 offset:20800
	ds_read_b128 v[156:159], v75 offset:23104
	s_waitcnt lgkmcnt(1)
	v_mfma_f32_16x16x32_bf16 v[30:33], v[148:151], v[140:143], v[30:33]
	ds_read_b128 v[148:151], v75 offset:2368
	ds_read_b128 v[160:163], v75 offset:4672
	s_waitcnt lgkmcnt(1)
	v_mfma_f32_16x16x32_bf16 v[14:17], v[148:151], v[140:143], v[14:17]
	v_mfma_f32_16x16x32_bf16 v[14:17], v[148:151], v[144:147], v[14:17]
	s_waitcnt lgkmcnt(0)
	v_mfma_f32_16x16x32_bf16 v[34:37], v[160:163], v[140:143], v[34:37]
	v_mfma_f32_16x16x32_bf16 v[14:17], v[156:159], v[140:143], v[14:17]
	ds_read_b128 v[148:151], v75 offset:25408
	ds_read_b128 v[156:159], v75 offset:27712
	v_mfma_f32_16x16x32_bf16 v[34:37], v[160:163], v[144:147], v[34:37]
	s_waitcnt lgkmcnt(1)
	v_mfma_f32_16x16x32_bf16 v[34:37], v[148:151], v[140:143], v[34:37]
	ds_read_b128 v[148:151], v75 offset:6976
	ds_read_b128 v[160:163], v75 offset:9280
	s_waitcnt lgkmcnt(1)
	v_mfma_f32_16x16x32_bf16 v[22:25], v[148:151], v[140:143], v[22:25]
	v_mfma_f32_16x16x32_bf16 v[22:25], v[148:151], v[144:147], v[22:25]
	s_waitcnt lgkmcnt(0)
	v_mfma_f32_16x16x32_bf16 v[26:29], v[160:163], v[140:143], v[26:29]
	v_mfma_f32_16x16x32_bf16 v[22:25], v[156:159], v[140:143], v[22:25]
	ds_read_b128 v[148:151], v75 offset:30016
	ds_read_b128 v[156:159], v75 offset:32320
	v_mfma_f32_16x16x32_bf16 v[26:29], v[160:163], v[144:147], v[26:29]
	s_waitcnt lgkmcnt(1)
	v_mfma_f32_16x16x32_bf16 v[26:29], v[148:151], v[140:143], v[26:29]
	ds_read_b128 v[148:151], v75 offset:11584
	ds_read_b128 v[160:163], v75 offset:13888
	s_waitcnt lgkmcnt(1)
	v_mfma_f32_16x16x32_bf16 v[10:13], v[148:151], v[140:143], v[10:13]
	v_mfma_f32_16x16x32_bf16 v[10:13], v[148:151], v[144:147], v[10:13]
	s_waitcnt lgkmcnt(0)
	v_mfma_f32_16x16x32_bf16 v[18:21], v[160:163], v[140:143], v[18:21]
	v_mfma_f32_16x16x32_bf16 v[10:13], v[156:159], v[140:143], v[10:13]
	ds_read_b128 v[148:151], v75 offset:34624
	ds_read_b128 v[156:159], v75 offset:36928
	v_mfma_f32_16x16x32_bf16 v[18:21], v[160:163], v[144:147], v[18:21]
	s_waitcnt lgkmcnt(1)
	v_mfma_f32_16x16x32_bf16 v[18:21], v[148:151], v[140:143], v[18:21]
	ds_read_b128 v[148:151], v75 offset:16192
	ds_read_b128 v[160:163], v75 offset:18496
	s_waitcnt lgkmcnt(1)
	v_mfma_f32_16x16x32_bf16 v[6:9], v[148:151], v[140:143], v[6:9]
	s_waitcnt lgkmcnt(0)
	v_mfma_f32_16x16x32_bf16 v[2:5], v[160:163], v[140:143], v[2:5]
	v_mfma_f32_16x16x32_bf16 v[6:9], v[148:151], v[144:147], v[6:9]
	v_mfma_f32_16x16x32_bf16 v[2:5], v[160:163], v[144:147], v[2:5]
	v_mfma_f32_16x16x32_bf16 v[6:9], v[156:159], v[140:143], v[6:9]
	v_mfma_f32_16x16x32_bf16 v[2:5], v[152:155], v[140:143], v[2:5]

.LBB0_474:
	v_add_co_u32_e32 v116, vcc, 0x1680000, v70
	s_nop 1
	v_addc_co_u32_e32 v117, vcc, 0, v71, vcc
	v_add_co_u32_e32 v138, vcc, 0x1689000, v70
	s_nop 1
	v_addc_co_u32_e32 v139, vcc, 0, v71, vcc
	v_add_co_u32_e32 v140, vcc, 0x1692000, v70
	s_nop 1
	v_addc_co_u32_e32 v141, vcc, 0, v71, vcc
	v_add_co_u32_e32 v142, vcc, 0x169b000, v70
	s_nop 1
	v_addc_co_u32_e32 v143, vcc, 0, v71, vcc
	v_add_co_u32_e32 v144, vcc, 0x16a4000, v70
	s_nop 1
	v_addc_co_u32_e32 v145, vcc, 0, v71, vcc
	v_add_co_u32_e32 v146, vcc, 0x16ad000, v70
	s_nop 1
	v_addc_co_u32_e32 v147, vcc, 0, v71, vcc
	v_add_co_u32_e32 v148, vcc, 0x16b6000, v70
	s_nop 1
	v_addc_co_u32_e32 v149, vcc, 0, v71, vcc
	v_add_co_u32_e32 v150, vcc, 0x16bf000, v70
	s_nop 1
	v_addc_co_u32_e32 v151, vcc, 0, v71, vcc
	global_load_dword v135, v[116:117], off nt
	global_load_dword v132, v[138:139], off nt
	global_load_dword v129, v[140:141], off nt
	global_load_dword v126, v[142:143], off nt
	global_load_dword v124, v[144:145], off nt
	global_load_dword v120, v[146:147], off nt
	global_load_dword v117, v[148:149], off nt
	global_load_dword v114, v[150:151], off nt
	v_add_co_u32_e32 v138, vcc, 0x17a0000, v70
	s_nop 1
	v_addc_co_u32_e32 v139, vcc, 0, v71, vcc
	v_add_co_u32_e32 v140, vcc, 0x17a9000, v70
	s_nop 1
	v_addc_co_u32_e32 v141, vcc, 0, v71, vcc
	v_add_co_u32_e32 v142, vcc, 0x17b2000, v70
	s_nop 1
	v_addc_co_u32_e32 v143, vcc, 0, v71, vcc
	v_add_co_u32_e32 v144, vcc, 0x17bb000, v70
	s_nop 1
	v_addc_co_u32_e32 v145, vcc, 0, v71, vcc
	v_add_co_u32_e32 v146, vcc, 0x17c4000, v70
	s_nop 1
	v_addc_co_u32_e32 v147, vcc, 0, v71, vcc
	v_add_co_u32_e32 v148, vcc, 0x17cd000, v70
	s_nop 1
	v_addc_co_u32_e32 v149, vcc, 0, v71, vcc
	v_add_co_u32_e32 v150, vcc, 0x17d6000, v70
	s_nop 1
	v_addc_co_u32_e32 v151, vcc, 0, v71, vcc
	v_add_co_u32_e32 v152, vcc, 0x17df000, v70
	s_nop 1
	v_addc_co_u32_e32 v153, vcc, 0, v71, vcc
	global_load_dword v112, v[138:139], off nt
	global_load_dword v108, v[140:141], off nt
	global_load_dword v104, v[142:143], off nt
	global_load_dword v100, v[144:145], off nt
	global_load_dword v93, v[146:147], off nt
	global_load_dword v91, v[148:149], off nt
	global_load_dword v87, v[150:151], off nt
	global_load_dword v81, v[152:153], off nt
	s_and_b64 vcc, exec, s[6:7]
	s_cbranch_vccnz .LBB0_476
	ds_read_b128 v[146:149], v75 offset:41536
	v_cvt_pk_bf16_f32 v138, v109, v105
	v_cvt_pk_bf16_f32 v139, v101, v96
	v_cvt_pk_bf16_f32 v140, v94, v88
	v_cvt_pk_bf16_f32 v141, v84, v82
	s_nop 0
	v_lshlrev_b32_e32 v59, 16, v138
	v_sub_f32_e32 v59, v109, v59
	v_and_b32_e32 v109, 0xffff0000, v138
	v_sub_f32_e32 v105, v105, v109
	v_cvt_pk_bf16_f32 v142, v59, v105
	v_lshlrev_b32_e32 v59, 16, v139
	v_sub_f32_e32 v59, v101, v59
	v_and_b32_e32 v101, 0xffff0000, v139
	v_sub_f32_e32 v96, v96, v101
	v_cvt_pk_bf16_f32 v143, v59, v96
	v_lshlrev_b32_e32 v59, 16, v140
	v_sub_f32_e32 v59, v94, v59
	v_and_b32_e32 v94, 0xffff0000, v140
	v_sub_f32_e32 v88, v88, v94
	v_cvt_pk_bf16_f32 v144, v59, v88
	v_lshlrev_b32_e32 v59, 16, v141
	v_sub_f32_e32 v59, v84, v59
	v_add_u32_e32 v84, 0xa240, v75
	ds_read_b128 v[150:153], v84 offset:32256
	s_waitcnt lgkmcnt(1)
	v_mfma_f32_16x16x32_bf16 v[30:33], v[146:149], v[138:141], v[30:33]
	v_and_b32_e32 v88, 0xffff0000, v141
	v_sub_f32_e32 v82, v82, v88
	v_cvt_pk_bf16_f32 v145, v59, v82
	s_nop 0
	v_mfma_f32_16x16x32_bf16 v[30:33], v[146:149], v[142:145], v[30:33]
	ds_read_b128 v[146:149], v75 offset:62272
	ds_read_b128 v[154:157], v75 offset:64576
	s_waitcnt lgkmcnt(1)
	v_mfma_f32_16x16x32_bf16 v[30:33], v[146:149], v[138:141], v[30:33]
	ds_read_b128 v[146:149], v75 offset:43840
	ds_read_b128 v[158:161], v75 offset:46144
	s_waitcnt lgkmcnt(1)
	v_mfma_f32_16x16x32_bf16 v[14:17], v[146:149], v[138:141], v[14:17]
	v_mfma_f32_16x16x32_bf16 v[14:17], v[146:149], v[142:145], v[14:17]
	s_waitcnt lgkmcnt(0)
	v_mfma_f32_16x16x32_bf16 v[34:37], v[158:161], v[138:141], v[34:37]
	v_mfma_f32_16x16x32_bf16 v[14:17], v[154:157], v[138:141], v[14:17]
	ds_read_b128 v[146:149], v84 offset:25344
	ds_read_b128 v[154:157], v84 offset:39168
	v_mfma_f32_16x16x32_bf16 v[34:37], v[158:161], v[142:145], v[34:37]
	s_waitcnt lgkmcnt(1)
	v_mfma_f32_16x16x32_bf16 v[34:37], v[146:149], v[138:141], v[34:37]
	ds_read_b128 v[146:149], v75 offset:48448
	ds_read_b128 v[158:161], v75 offset:50752
	s_waitcnt lgkmcnt(1)
	v_mfma_f32_16x16x32_bf16 v[22:25], v[146:149], v[138:141], v[22:25]
	v_mfma_f32_16x16x32_bf16 v[22:25], v[146:149], v[142:145], v[22:25]
	ds_read_b128 v[146:149], v84 offset:27648
	ds_read_b128 v[162:165], v84 offset:29952
	s_waitcnt lgkmcnt(2)
	v_mfma_f32_16x16x32_bf16 v[26:29], v[158:161], v[138:141], v[26:29]
	s_waitcnt lgkmcnt(1)
	v_mfma_f32_16x16x32_bf16 v[22:25], v[146:149], v[138:141], v[22:25]
	v_mfma_f32_16x16x32_bf16 v[26:29], v[158:161], v[142:145], v[26:29]
	ds_read_b128 v[146:149], v75 offset:53056
	ds_read_b128 v[158:161], v75 offset:55360
	s_waitcnt lgkmcnt(1)
	v_mfma_f32_16x16x32_bf16 v[10:13], v[146:149], v[138:141], v[10:13]
	v_mfma_f32_16x16x32_bf16 v[10:13], v[146:149], v[142:145], v[10:13]
	s_waitcnt lgkmcnt(0)
	v_mfma_f32_16x16x32_bf16 v[18:21], v[158:161], v[138:141], v[18:21]
	v_mfma_f32_16x16x32_bf16 v[10:13], v[150:153], v[138:141], v[10:13]
	ds_read_b128 v[146:149], v84 offset:34560
	ds_read_b128 v[150:153], v84 offset:36864
	v_mfma_f32_16x16x32_bf16 v[18:21], v[158:161], v[142:145], v[18:21]
	s_waitcnt lgkmcnt(1)
	v_mfma_f32_16x16x32_bf16 v[18:21], v[146:149], v[138:141], v[18:21]
	ds_read_b128 v[146:149], v75 offset:57664
	ds_read_b128 v[158:161], v75 offset:59968
	s_waitcnt lgkmcnt(1)
	v_mfma_f32_16x16x32_bf16 v[6:9], v[146:149], v[138:141], v[6:9]
	s_waitcnt lgkmcnt(0)
	v_mfma_f32_16x16x32_bf16 v[2:5], v[158:161], v[138:141], v[2:5]
	v_mfma_f32_16x16x32_bf16 v[6:9], v[146:149], v[142:145], v[6:9]
	v_mfma_f32_16x16x32_bf16 v[2:5], v[158:161], v[142:145], v[2:5]
	v_mfma_f32_16x16x32_bf16 v[26:29], v[162:165], v[138:141], v[26:29]
	v_mfma_f32_16x16x32_bf16 v[6:9], v[150:153], v[138:141], v[6:9]
	v_mfma_f32_16x16x32_bf16 v[2:5], v[154:157], v[138:141], v[2:5]

.LBB0_498:
	v_add_co_u32_e32 v138, vcc, 0x18c0000, v70
	s_nop 1
	v_addc_co_u32_e32 v139, vcc, 0, v71, vcc
	v_add_co_u32_e32 v140, vcc, 0x18c9000, v70
	s_nop 1
	v_addc_co_u32_e32 v141, vcc, 0, v71, vcc
	v_add_co_u32_e32 v142, vcc, 0x18d2000, v70
	s_nop 1
	v_addc_co_u32_e32 v143, vcc, 0, v71, vcc
	v_add_co_u32_e32 v144, vcc, 0x18db000, v70
	s_nop 1
	v_addc_co_u32_e32 v145, vcc, 0, v71, vcc
	v_add_co_u32_e32 v146, vcc, 0x18e4000, v70
	s_nop 1
	v_addc_co_u32_e32 v147, vcc, 0, v71, vcc
	v_add_co_u32_e32 v148, vcc, 0x18ed000, v70
	s_nop 1
	v_addc_co_u32_e32 v149, vcc, 0, v71, vcc
	v_add_co_u32_e32 v150, vcc, 0x18f6000, v70
	s_nop 1
	v_addc_co_u32_e32 v151, vcc, 0, v71, vcc
	v_add_co_u32_e32 v152, vcc, 0x18ff000, v70
	s_nop 1
	v_addc_co_u32_e32 v153, vcc, 0, v71, vcc
	global_load_dword v136, v[138:139], off nt
	global_load_dword v133, v[140:141], off nt
	global_load_dword v130, v[142:143], off nt
	global_load_dword v127, v[144:145], off nt
	global_load_dword v123, v[146:147], off nt
	global_load_dword v121, v[148:149], off nt
	global_load_dword v118, v[150:151], off nt
	global_load_dword v116, v[152:153], off nt
	v_add_co_u32_e32 v138, vcc, 0x19e0000, v70
	s_nop 1
	v_addc_co_u32_e32 v139, vcc, 0, v71, vcc
	v_add_co_u32_e32 v140, vcc, 0x19e9000, v70
	s_nop 1
	v_addc_co_u32_e32 v141, vcc, 0, v71, vcc
	v_add_co_u32_e32 v142, vcc, 0x19f2000, v70
	s_nop 1
	v_addc_co_u32_e32 v143, vcc, 0, v71, vcc
	v_add_co_u32_e32 v144, vcc, 0x19fb000, v70
	s_nop 1
	v_addc_co_u32_e32 v145, vcc, 0, v71, vcc
	v_add_co_u32_e32 v146, vcc, 0x1a04000, v70
	s_nop 1
	v_addc_co_u32_e32 v147, vcc, 0, v71, vcc
	v_add_co_u32_e32 v148, vcc, 0x1a0d000, v70
	s_nop 1
	v_addc_co_u32_e32 v149, vcc, 0, v71, vcc
	v_add_co_u32_e32 v150, vcc, 0x1a16000, v70
	s_nop 1
	v_addc_co_u32_e32 v151, vcc, 0, v71, vcc
	v_add_co_u32_e32 v152, vcc, 0x1a1f000, v70
	s_nop 1
	v_addc_co_u32_e32 v153, vcc, 0, v71, vcc
	global_load_dword v109, v[138:139], off nt
	global_load_dword v105, v[140:141], off nt
	global_load_dword v101, v[142:143], off nt
	global_load_dword v96, v[144:145], off nt
	global_load_dword v94, v[146:147], off nt
	global_load_dword v88, v[148:149], off nt
	global_load_dword v84, v[150:151], off nt
	global_load_dword v82, v[152:153], off nt
	s_and_b64 vcc, exec, s[6:7]
	s_cbranch_vccnz .LBB0_500
	ds_read_b128 v[146:149], v75 offset:64
	ds_read_b128 v[150:153], v75 offset:39232
	v_cvt_pk_bf16_f32 v138, v110, v106
	v_cvt_pk_bf16_f32 v139, v102, v97
	v_cvt_pk_bf16_f32 v140, v92, v89
	v_cvt_pk_bf16_f32 v141, v85, v80
	s_nop 0
	v_lshlrev_b32_e32 v59, 16, v138
	v_sub_f32_e32 v59, v110, v59
	v_and_b32_e32 v110, 0xffff0000, v138
	v_sub_f32_e32 v106, v106, v110
	v_cvt_pk_bf16_f32 v142, v59, v106
	v_lshlrev_b32_e32 v59, 16, v139
	v_sub_f32_e32 v59, v102, v59
	v_and_b32_e32 v102, 0xffff0000, v139
	v_sub_f32_e32 v97, v97, v102
	v_cvt_pk_bf16_f32 v143, v59, v97
	v_lshlrev_b32_e32 v59, 16, v140
	s_waitcnt lgkmcnt(1)
	v_mfma_f32_16x16x32_bf16 v[30:33], v[146:149], v[138:141], v[30:33]
	v_sub_f32_e32 v59, v92, v59
	v_and_b32_e32 v92, 0xffff0000, v140
	v_sub_f32_e32 v89, v89, v92
	v_cvt_pk_bf16_f32 v144, v59, v89
	v_lshlrev_b32_e32 v59, 16, v141
	v_sub_f32_e32 v59, v85, v59
	v_and_b32_e32 v85, 0xffff0000, v141
	v_sub_f32_e32 v80, v80, v85
	v_cvt_pk_bf16_f32 v145, v59, v80
	s_nop 0
	v_mfma_f32_16x16x32_bf16 v[30:33], v[146:149], v[142:145], v[30:33]
	ds_read_b128 v[146:149], v75 offset:20800
	ds_read_b128 v[154:157], v75 offset:23104
	s_waitcnt lgkmcnt(1)
	v_mfma_f32_16x16x32_bf16 v[30:33], v[146:149], v[138:141], v[30:33]
	ds_read_b128 v[146:149], v75 offset:2368
	ds_read_b128 v[158:161], v75 offset:4672
	s_waitcnt lgkmcnt(1)
	v_mfma_f32_16x16x32_bf16 v[14:17], v[146:149], v[138:141], v[14:17]
	v_mfma_f32_16x16x32_bf16 v[14:17], v[146:149], v[142:145], v[14:17]
	s_waitcnt lgkmcnt(0)
	v_mfma_f32_16x16x32_bf16 v[34:37], v[158:161], v[138:141], v[34:37]
	v_mfma_f32_16x16x32_bf16 v[14:17], v[154:157], v[138:141], v[14:17]
	ds_read_b128 v[146:149], v75 offset:25408
	ds_read_b128 v[154:157], v75 offset:27712
	v_mfma_f32_16x16x32_bf16 v[34:37], v[158:161], v[142:145], v[34:37]
	s_waitcnt lgkmcnt(1)
	v_mfma_f32_16x16x32_bf16 v[34:37], v[146:149], v[138:141], v[34:37]
	ds_read_b128 v[146:149], v75 offset:6976
	ds_read_b128 v[158:161], v75 offset:9280
	s_waitcnt lgkmcnt(1)
	v_mfma_f32_16x16x32_bf16 v[22:25], v[146:149], v[138:141], v[22:25]
	v_mfma_f32_16x16x32_bf16 v[22:25], v[146:149], v[142:145], v[22:25]
	s_waitcnt lgkmcnt(0)
	v_mfma_f32_16x16x32_bf16 v[26:29], v[158:161], v[138:141], v[26:29]
	v_mfma_f32_16x16x32_bf16 v[22:25], v[154:157], v[138:141], v[22:25]
	ds_read_b128 v[146:149], v75 offset:30016
	ds_read_b128 v[154:157], v75 offset:32320
	v_mfma_f32_16x16x32_bf16 v[26:29], v[158:161], v[142:145], v[26:29]
	s_waitcnt lgkmcnt(1)
	v_mfma_f32_16x16x32_bf16 v[26:29], v[146:149], v[138:141], v[26:29]
	ds_read_b128 v[146:149], v75 offset:11584
	ds_read_b128 v[158:161], v75 offset:13888
	s_waitcnt lgkmcnt(1)
	v_mfma_f32_16x16x32_bf16 v[10:13], v[146:149], v[138:141], v[10:13]
	v_mfma_f32_16x16x32_bf16 v[10:13], v[146:149], v[142:145], v[10:13]
	s_waitcnt lgkmcnt(0)
	v_mfma_f32_16x16x32_bf16 v[18:21], v[158:161], v[138:141], v[18:21]
	v_mfma_f32_16x16x32_bf16 v[10:13], v[154:157], v[138:141], v[10:13]
	ds_read_b128 v[146:149], v75 offset:34624
	ds_read_b128 v[154:157], v75 offset:36928
	v_mfma_f32_16x16x32_bf16 v[18:21], v[158:161], v[142:145], v[18:21]
	s_waitcnt lgkmcnt(1)
	v_mfma_f32_16x16x32_bf16 v[18:21], v[146:149], v[138:141], v[18:21]
	ds_read_b128 v[146:149], v75 offset:16192
	ds_read_b128 v[158:161], v75 offset:18496
	s_waitcnt lgkmcnt(1)
	v_mfma_f32_16x16x32_bf16 v[6:9], v[146:149], v[138:141], v[6:9]
	s_waitcnt lgkmcnt(0)
	v_mfma_f32_16x16x32_bf16 v[2:5], v[158:161], v[138:141], v[2:5]
	v_mfma_f32_16x16x32_bf16 v[6:9], v[146:149], v[142:145], v[6:9]
	v_mfma_f32_16x16x32_bf16 v[2:5], v[158:161], v[142:145], v[2:5]
	v_mfma_f32_16x16x32_bf16 v[6:9], v[154:157], v[138:141], v[6:9]
	v_mfma_f32_16x16x32_bf16 v[2:5], v[150:153], v[138:141], v[2:5]

.LBB0_522:
	v_add_co_u32_e32 v138, vcc, 0x1b00000, v70
	s_nop 1
	v_addc_co_u32_e32 v139, vcc, 0, v71, vcc
	v_add_co_u32_e32 v140, vcc, 0x1b09000, v70
	s_nop 1
	v_addc_co_u32_e32 v141, vcc, 0, v71, vcc
	v_add_co_u32_e32 v142, vcc, 0x1b12000, v70
	s_nop 1
	v_addc_co_u32_e32 v143, vcc, 0, v71, vcc
	v_add_co_u32_e32 v144, vcc, 0x1b1b000, v70
	s_nop 1
	v_addc_co_u32_e32 v145, vcc, 0, v71, vcc
	v_add_co_u32_e32 v146, vcc, 0x1b24000, v70
	s_nop 1
	v_addc_co_u32_e32 v147, vcc, 0, v71, vcc
	v_add_co_u32_e32 v148, vcc, 0x1b2d000, v70
	s_nop 1
	v_addc_co_u32_e32 v149, vcc, 0, v71, vcc
	v_add_co_u32_e32 v150, vcc, 0x1b36000, v70
	s_nop 1
	v_addc_co_u32_e32 v151, vcc, 0, v71, vcc
	v_add_co_u32_e32 v152, vcc, 0x1b3f000, v70
	s_nop 1
	v_addc_co_u32_e32 v153, vcc, 0, v71, vcc
	global_load_dword v134, v[138:139], off nt
	global_load_dword v131, v[140:141], off nt
	global_load_dword v128, v[142:143], off nt
	global_load_dword v125, v[144:145], off nt
	global_load_dword v122, v[146:147], off nt
	global_load_dword v119, v[148:149], off nt
	global_load_dword v115, v[150:151], off nt
	global_load_dword v113, v[152:153], off nt
	v_add_co_u32_e32 v138, vcc, 0x1c20000, v70
	s_nop 1
	v_addc_co_u32_e32 v139, vcc, 0, v71, vcc
	v_add_co_u32_e32 v140, vcc, 0x1c29000, v70
	s_nop 1
	v_addc_co_u32_e32 v141, vcc, 0, v71, vcc
	v_add_co_u32_e32 v142, vcc, 0x1c32000, v70
	s_nop 1
	v_addc_co_u32_e32 v143, vcc, 0, v71, vcc
	v_add_co_u32_e32 v144, vcc, 0x1c3b000, v70
	s_nop 1
	v_addc_co_u32_e32 v145, vcc, 0, v71, vcc
	v_add_co_u32_e32 v146, vcc, 0x1c44000, v70
	s_nop 1
	v_addc_co_u32_e32 v147, vcc, 0, v71, vcc
	v_add_co_u32_e32 v148, vcc, 0x1c4d000, v70
	s_nop 1
	v_addc_co_u32_e32 v149, vcc, 0, v71, vcc
	v_add_co_u32_e32 v150, vcc, 0x1c56000, v70
	s_nop 1
	v_addc_co_u32_e32 v151, vcc, 0, v71, vcc
	v_add_co_u32_e32 v152, vcc, 0x1c5f000, v70
	s_nop 1
	v_addc_co_u32_e32 v153, vcc, 0, v71, vcc
	global_load_dword v110, v[138:139], off nt
	global_load_dword v106, v[140:141], off nt
	global_load_dword v102, v[142:143], off nt
	global_load_dword v97, v[144:145], off nt
	global_load_dword v92, v[146:147], off nt
	global_load_dword v89, v[148:149], off nt
	global_load_dword v85, v[150:151], off nt
	global_load_dword v80, v[152:153], off nt
	s_and_b64 vcc, exec, s[6:7]
	s_cbranch_vccnz .LBB0_524
	ds_read_b128 v[146:149], v75 offset:41536
	v_cvt_pk_bf16_f32 v138, v111, v107
	v_cvt_pk_bf16_f32 v139, v103, v99
	v_cvt_pk_bf16_f32 v140, v95, v90
	v_cvt_pk_bf16_f32 v141, v86, v83
	s_nop 0
	v_lshlrev_b32_e32 v59, 16, v138
	v_sub_f32_e32 v59, v111, v59
	v_and_b32_e32 v111, 0xffff0000, v138
	v_sub_f32_e32 v107, v107, v111
	v_cvt_pk_bf16_f32 v142, v59, v107
	v_lshlrev_b32_e32 v59, 16, v139
	v_sub_f32_e32 v59, v103, v59
	v_and_b32_e32 v103, 0xffff0000, v139
	v_sub_f32_e32 v99, v99, v103
	v_cvt_pk_bf16_f32 v143, v59, v99
	v_lshlrev_b32_e32 v59, 16, v140
	v_sub_f32_e32 v59, v95, v59
	v_and_b32_e32 v95, 0xffff0000, v140
	v_sub_f32_e32 v90, v90, v95
	v_cvt_pk_bf16_f32 v144, v59, v90
	v_lshlrev_b32_e32 v59, 16, v141
	v_sub_f32_e32 v59, v86, v59
	v_add_u32_e32 v86, 0xa240, v75
	ds_read_b128 v[150:153], v86 offset:32256
	s_waitcnt lgkmcnt(1)
	v_mfma_f32_16x16x32_bf16 v[30:33], v[146:149], v[138:141], v[30:33]
	v_and_b32_e32 v90, 0xffff0000, v141
	v_sub_f32_e32 v83, v83, v90
	v_cvt_pk_bf16_f32 v145, v59, v83
	s_nop 0
	v_mfma_f32_16x16x32_bf16 v[30:33], v[146:149], v[142:145], v[30:33]
	ds_read_b128 v[146:149], v75 offset:62272
	ds_read_b128 v[154:157], v75 offset:64576
	s_waitcnt lgkmcnt(1)
	v_mfma_f32_16x16x32_bf16 v[30:33], v[146:149], v[138:141], v[30:33]
	ds_read_b128 v[146:149], v75 offset:43840
	ds_read_b128 v[158:161], v75 offset:46144
	s_waitcnt lgkmcnt(1)
	v_mfma_f32_16x16x32_bf16 v[14:17], v[146:149], v[138:141], v[14:17]
	v_mfma_f32_16x16x32_bf16 v[14:17], v[146:149], v[142:145], v[14:17]
	s_waitcnt lgkmcnt(0)
	v_mfma_f32_16x16x32_bf16 v[34:37], v[158:161], v[138:141], v[34:37]
	v_mfma_f32_16x16x32_bf16 v[14:17], v[154:157], v[138:141], v[14:17]
	ds_read_b128 v[146:149], v86 offset:25344
	ds_read_b128 v[154:157], v86 offset:39168
	v_mfma_f32_16x16x32_bf16 v[34:37], v[158:161], v[142:145], v[34:37]
	s_waitcnt lgkmcnt(1)
	v_mfma_f32_16x16x32_bf16 v[34:37], v[146:149], v[138:141], v[34:37]
	ds_read_b128 v[146:149], v75 offset:48448
	ds_read_b128 v[158:161], v75 offset:50752
	s_waitcnt lgkmcnt(1)
	v_mfma_f32_16x16x32_bf16 v[22:25], v[146:149], v[138:141], v[22:25]
	v_mfma_f32_16x16x32_bf16 v[22:25], v[146:149], v[142:145], v[22:25]
	ds_read_b128 v[146:149], v86 offset:27648
	ds_read_b128 v[162:165], v86 offset:29952
	s_waitcnt lgkmcnt(2)
	v_mfma_f32_16x16x32_bf16 v[26:29], v[158:161], v[138:141], v[26:29]
	s_waitcnt lgkmcnt(1)
	v_mfma_f32_16x16x32_bf16 v[22:25], v[146:149], v[138:141], v[22:25]
	v_mfma_f32_16x16x32_bf16 v[26:29], v[158:161], v[142:145], v[26:29]
	ds_read_b128 v[146:149], v75 offset:53056
	ds_read_b128 v[158:161], v75 offset:55360
	s_waitcnt lgkmcnt(1)
	v_mfma_f32_16x16x32_bf16 v[10:13], v[146:149], v[138:141], v[10:13]
	v_mfma_f32_16x16x32_bf16 v[10:13], v[146:149], v[142:145], v[10:13]
	s_waitcnt lgkmcnt(0)
	v_mfma_f32_16x16x32_bf16 v[18:21], v[158:161], v[138:141], v[18:21]
	v_mfma_f32_16x16x32_bf16 v[10:13], v[150:153], v[138:141], v[10:13]
	ds_read_b128 v[146:149], v86 offset:34560
	ds_read_b128 v[150:153], v86 offset:36864
	v_mfma_f32_16x16x32_bf16 v[18:21], v[158:161], v[142:145], v[18:21]
	s_waitcnt lgkmcnt(1)
	v_mfma_f32_16x16x32_bf16 v[18:21], v[146:149], v[138:141], v[18:21]
	ds_read_b128 v[146:149], v75 offset:57664
	ds_read_b128 v[158:161], v75 offset:59968
	s_waitcnt lgkmcnt(1)
	v_mfma_f32_16x16x32_bf16 v[6:9], v[146:149], v[138:141], v[6:9]
	s_waitcnt lgkmcnt(0)
	v_mfma_f32_16x16x32_bf16 v[2:5], v[158:161], v[138:141], v[2:5]
	v_mfma_f32_16x16x32_bf16 v[6:9], v[146:149], v[142:145], v[6:9]
	v_mfma_f32_16x16x32_bf16 v[2:5], v[158:161], v[142:145], v[2:5]
	v_mfma_f32_16x16x32_bf16 v[26:29], v[162:165], v[138:141], v[26:29]
	v_mfma_f32_16x16x32_bf16 v[6:9], v[150:153], v[138:141], v[6:9]
	v_mfma_f32_16x16x32_bf16 v[2:5], v[154:157], v[138:141], v[2:5]

.LBB0_546:
	v_add_co_u32_e32 v138, vcc, 0x1d40000, v70
	s_nop 1
	v_addc_co_u32_e32 v139, vcc, 0, v71, vcc
	v_add_co_u32_e32 v140, vcc, 0x1d49000, v70
	s_nop 1
	v_addc_co_u32_e32 v141, vcc, 0, v71, vcc
	v_add_co_u32_e32 v142, vcc, 0x1d52000, v70
	s_nop 1
	v_addc_co_u32_e32 v143, vcc, 0, v71, vcc
	v_add_co_u32_e32 v144, vcc, 0x1d5b000, v70
	s_nop 1
	v_addc_co_u32_e32 v145, vcc, 0, v71, vcc
	v_add_co_u32_e32 v146, vcc, 0x1d64000, v70
	s_nop 1
	v_addc_co_u32_e32 v147, vcc, 0, v71, vcc
	v_add_co_u32_e32 v148, vcc, 0x1d6d000, v70
	s_nop 1
	v_addc_co_u32_e32 v149, vcc, 0, v71, vcc
	v_add_co_u32_e32 v150, vcc, 0x1d76000, v70
	s_nop 1
	v_addc_co_u32_e32 v151, vcc, 0, v71, vcc
	v_add_co_u32_e32 v152, vcc, 0x1d7f000, v70
	s_nop 1
	v_addc_co_u32_e32 v153, vcc, 0, v71, vcc
	global_load_dword v135, v[138:139], off nt
	global_load_dword v132, v[140:141], off nt
	global_load_dword v129, v[142:143], off nt
	global_load_dword v126, v[144:145], off nt
	global_load_dword v124, v[146:147], off nt
	global_load_dword v120, v[148:149], off nt
	global_load_dword v117, v[150:151], off nt
	global_load_dword v114, v[152:153], off nt
	v_add_co_u32_e32 v138, vcc, 0x1e60000, v70
	s_nop 1
	v_addc_co_u32_e32 v139, vcc, 0, v71, vcc
	v_add_co_u32_e32 v140, vcc, 0x1e69000, v70
	s_nop 1
	v_addc_co_u32_e32 v141, vcc, 0, v71, vcc
	v_add_co_u32_e32 v142, vcc, 0x1e72000, v70
	s_nop 1
	v_addc_co_u32_e32 v143, vcc, 0, v71, vcc
	v_add_co_u32_e32 v144, vcc, 0x1e7b000, v70
	s_nop 1
	v_addc_co_u32_e32 v145, vcc, 0, v71, vcc
	v_add_co_u32_e32 v146, vcc, 0x1e84000, v70
	s_nop 1
	v_addc_co_u32_e32 v147, vcc, 0, v71, vcc
	v_add_co_u32_e32 v148, vcc, 0x1e8d000, v70
	s_nop 1
	v_addc_co_u32_e32 v149, vcc, 0, v71, vcc
	v_add_co_u32_e32 v150, vcc, 0x1e96000, v70
	s_nop 1
	v_addc_co_u32_e32 v151, vcc, 0, v71, vcc
	v_add_co_u32_e32 v152, vcc, 0x1e9f000, v70
	s_nop 1
	v_addc_co_u32_e32 v153, vcc, 0, v71, vcc
	global_load_dword v111, v[138:139], off nt
	global_load_dword v107, v[140:141], off nt
	global_load_dword v103, v[142:143], off nt
	global_load_dword v99, v[144:145], off nt
	global_load_dword v95, v[146:147], off nt
	global_load_dword v90, v[148:149], off nt
	global_load_dword v86, v[150:151], off nt
	global_load_dword v83, v[152:153], off nt
	s_and_b64 vcc, exec, s[6:7]
	s_cbranch_vccnz .LBB0_548
	ds_read_b128 v[146:149], v75 offset:64
	ds_read_b128 v[150:153], v75 offset:39232
	v_cvt_pk_bf16_f32 v138, v112, v108
	v_cvt_pk_bf16_f32 v139, v104, v100
	v_cvt_pk_bf16_f32 v140, v93, v91
	v_cvt_pk_bf16_f32 v141, v87, v81
	s_nop 0
	v_lshlrev_b32_e32 v59, 16, v138
	v_sub_f32_e32 v59, v112, v59
	v_and_b32_e32 v112, 0xffff0000, v138
	v_sub_f32_e32 v108, v108, v112
	v_cvt_pk_bf16_f32 v142, v59, v108
	v_lshlrev_b32_e32 v59, 16, v139
	v_sub_f32_e32 v59, v104, v59
	v_and_b32_e32 v104, 0xffff0000, v139
	v_sub_f32_e32 v100, v100, v104
	v_cvt_pk_bf16_f32 v143, v59, v100
	v_lshlrev_b32_e32 v59, 16, v140
	s_waitcnt lgkmcnt(1)
	v_mfma_f32_16x16x32_bf16 v[30:33], v[146:149], v[138:141], v[30:33]
	v_sub_f32_e32 v59, v93, v59
	v_and_b32_e32 v93, 0xffff0000, v140
	v_sub_f32_e32 v91, v91, v93
	v_cvt_pk_bf16_f32 v144, v59, v91
	v_lshlrev_b32_e32 v59, 16, v141
	v_sub_f32_e32 v59, v87, v59
	v_and_b32_e32 v87, 0xffff0000, v141
	v_sub_f32_e32 v81, v81, v87
	v_cvt_pk_bf16_f32 v145, v59, v81
	s_nop 0
	v_mfma_f32_16x16x32_bf16 v[30:33], v[146:149], v[142:145], v[30:33]
	ds_read_b128 v[146:149], v75 offset:20800
	ds_read_b128 v[154:157], v75 offset:23104
	s_waitcnt lgkmcnt(1)
	v_mfma_f32_16x16x32_bf16 v[30:33], v[146:149], v[138:141], v[30:33]
	ds_read_b128 v[146:149], v75 offset:2368
	ds_read_b128 v[158:161], v75 offset:4672
	s_waitcnt lgkmcnt(1)
	v_mfma_f32_16x16x32_bf16 v[14:17], v[146:149], v[138:141], v[14:17]
	v_mfma_f32_16x16x32_bf16 v[14:17], v[146:149], v[142:145], v[14:17]
	s_waitcnt lgkmcnt(0)
	v_mfma_f32_16x16x32_bf16 v[34:37], v[158:161], v[138:141], v[34:37]
	v_mfma_f32_16x16x32_bf16 v[14:17], v[154:157], v[138:141], v[14:17]
	ds_read_b128 v[146:149], v75 offset:25408
	ds_read_b128 v[154:157], v75 offset:27712
	v_mfma_f32_16x16x32_bf16 v[34:37], v[158:161], v[142:145], v[34:37]
	s_waitcnt lgkmcnt(1)
	v_mfma_f32_16x16x32_bf16 v[34:37], v[146:149], v[138:141], v[34:37]
	ds_read_b128 v[146:149], v75 offset:6976
	ds_read_b128 v[158:161], v75 offset:9280
	s_waitcnt lgkmcnt(1)
	v_mfma_f32_16x16x32_bf16 v[22:25], v[146:149], v[138:141], v[22:25]
	v_mfma_f32_16x16x32_bf16 v[22:25], v[146:149], v[142:145], v[22:25]
	s_waitcnt lgkmcnt(0)
	v_mfma_f32_16x16x32_bf16 v[26:29], v[158:161], v[138:141], v[26:29]
	v_mfma_f32_16x16x32_bf16 v[22:25], v[154:157], v[138:141], v[22:25]
	ds_read_b128 v[146:149], v75 offset:30016
	ds_read_b128 v[154:157], v75 offset:32320
	v_mfma_f32_16x16x32_bf16 v[26:29], v[158:161], v[142:145], v[26:29]
	s_waitcnt lgkmcnt(1)
	v_mfma_f32_16x16x32_bf16 v[26:29], v[146:149], v[138:141], v[26:29]
	ds_read_b128 v[146:149], v75 offset:11584
	ds_read_b128 v[158:161], v75 offset:13888
	s_waitcnt lgkmcnt(1)
	v_mfma_f32_16x16x32_bf16 v[10:13], v[146:149], v[138:141], v[10:13]
	v_mfma_f32_16x16x32_bf16 v[10:13], v[146:149], v[142:145], v[10:13]
	s_waitcnt lgkmcnt(0)
	v_mfma_f32_16x16x32_bf16 v[18:21], v[158:161], v[138:141], v[18:21]
	v_mfma_f32_16x16x32_bf16 v[10:13], v[154:157], v[138:141], v[10:13]
	ds_read_b128 v[146:149], v75 offset:34624
	ds_read_b128 v[154:157], v75 offset:36928
	v_mfma_f32_16x16x32_bf16 v[18:21], v[158:161], v[142:145], v[18:21]
	s_waitcnt lgkmcnt(1)
	v_mfma_f32_16x16x32_bf16 v[18:21], v[146:149], v[138:141], v[18:21]
	ds_read_b128 v[146:149], v75 offset:16192
	ds_read_b128 v[158:161], v75 offset:18496
	s_waitcnt lgkmcnt(1)
	v_mfma_f32_16x16x32_bf16 v[6:9], v[146:149], v[138:141], v[6:9]
	s_waitcnt lgkmcnt(0)
	v_mfma_f32_16x16x32_bf16 v[2:5], v[158:161], v[138:141], v[2:5]
	v_mfma_f32_16x16x32_bf16 v[6:9], v[146:149], v[142:145], v[6:9]
	v_mfma_f32_16x16x32_bf16 v[2:5], v[158:161], v[142:145], v[2:5]
	v_mfma_f32_16x16x32_bf16 v[6:9], v[154:157], v[138:141], v[6:9]
	v_mfma_f32_16x16x32_bf16 v[2:5], v[150:153], v[138:141], v[2:5]

.LBB0_570:
	v_add_co_u32_e32 v136, vcc, 0x1f80000, v70
	s_nop 1
	v_addc_co_u32_e32 v137, vcc, 0, v71, vcc
	v_add_co_u32_e32 v138, vcc, 0x1f89000, v70
	s_nop 1
	v_addc_co_u32_e32 v139, vcc, 0, v71, vcc
	v_add_co_u32_e32 v140, vcc, 0x1f92000, v70
	s_nop 1
	v_addc_co_u32_e32 v141, vcc, 0, v71, vcc
	v_add_co_u32_e32 v142, vcc, 0x1f9b000, v70
	s_nop 1
	v_addc_co_u32_e32 v143, vcc, 0, v71, vcc
	v_add_co_u32_e32 v144, vcc, 0x1fa4000, v70
	s_nop 1
	v_addc_co_u32_e32 v145, vcc, 0, v71, vcc
	v_add_co_u32_e32 v146, vcc, 0x1fad000, v70
	s_nop 1
	v_addc_co_u32_e32 v147, vcc, 0, v71, vcc
	v_add_co_u32_e32 v148, vcc, 0x1fb6000, v70
	s_nop 1
	v_addc_co_u32_e32 v149, vcc, 0, v71, vcc
	v_add_co_u32_e32 v150, vcc, 0x1fbf000, v70
	s_nop 1
	v_addc_co_u32_e32 v151, vcc, 0, v71, vcc
	global_load_dword v136, v[136:137], off nt
	s_nop 0
	global_load_dword v133, v[138:139], off nt
	global_load_dword v130, v[140:141], off nt
	global_load_dword v127, v[142:143], off nt
	global_load_dword v123, v[144:145], off nt
	global_load_dword v121, v[146:147], off nt
	global_load_dword v118, v[148:149], off nt
	global_load_dword v116, v[150:151], off nt
	v_add_co_u32_e32 v138, vcc, 0x20a0000, v70
	s_nop 1
	v_addc_co_u32_e32 v139, vcc, 0, v71, vcc
	v_add_co_u32_e32 v140, vcc, 0x20a9000, v70
	s_nop 1
	v_addc_co_u32_e32 v141, vcc, 0, v71, vcc
	v_add_co_u32_e32 v142, vcc, 0x20b2000, v70
	s_nop 1
	v_addc_co_u32_e32 v143, vcc, 0, v71, vcc
	v_add_co_u32_e32 v144, vcc, 0x20bb000, v70
	s_nop 1
	v_addc_co_u32_e32 v145, vcc, 0, v71, vcc
	v_add_co_u32_e32 v146, vcc, 0x20c4000, v70
	s_nop 1
	v_addc_co_u32_e32 v147, vcc, 0, v71, vcc
	v_add_co_u32_e32 v148, vcc, 0x20cd000, v70
	s_nop 1
	v_addc_co_u32_e32 v149, vcc, 0, v71, vcc
	v_add_co_u32_e32 v150, vcc, 0x20d6000, v70
	s_nop 1
	v_addc_co_u32_e32 v151, vcc, 0, v71, vcc
	v_add_co_u32_e32 v152, vcc, 0x20df000, v70
	s_nop 1
	v_addc_co_u32_e32 v153, vcc, 0, v71, vcc
	global_load_dword v112, v[138:139], off nt
	global_load_dword v108, v[140:141], off nt
	global_load_dword v104, v[142:143], off nt
	global_load_dword v100, v[144:145], off nt
	global_load_dword v93, v[146:147], off nt
	global_load_dword v91, v[148:149], off nt
	global_load_dword v87, v[150:151], off nt
	global_load_dword v81, v[152:153], off nt
	s_and_b64 vcc, exec, s[6:7]
	s_cbranch_vccnz .LBB0_572
	ds_read_b128 v[146:149], v75 offset:41536
	v_cvt_pk_bf16_f32 v138, v109, v105
	v_cvt_pk_bf16_f32 v139, v101, v96
	v_cvt_pk_bf16_f32 v140, v94, v88
	v_cvt_pk_bf16_f32 v141, v84, v82
	s_nop 0
	v_lshlrev_b32_e32 v59, 16, v138
	v_sub_f32_e32 v59, v109, v59
	v_and_b32_e32 v109, 0xffff0000, v138
	v_sub_f32_e32 v105, v105, v109
	v_cvt_pk_bf16_f32 v142, v59, v105
	v_lshlrev_b32_e32 v59, 16, v139
	v_sub_f32_e32 v59, v101, v59
	v_and_b32_e32 v101, 0xffff0000, v139
	v_sub_f32_e32 v96, v96, v101
	v_cvt_pk_bf16_f32 v143, v59, v96
	v_lshlrev_b32_e32 v59, 16, v140
	v_sub_f32_e32 v59, v94, v59
	v_and_b32_e32 v94, 0xffff0000, v140
	v_sub_f32_e32 v88, v88, v94
	v_cvt_pk_bf16_f32 v144, v59, v88
	v_lshlrev_b32_e32 v59, 16, v141
	v_sub_f32_e32 v59, v84, v59
	v_add_u32_e32 v84, 0xa240, v75
	ds_read_b128 v[150:153], v84 offset:32256
	s_waitcnt lgkmcnt(1)
	v_mfma_f32_16x16x32_bf16 v[30:33], v[146:149], v[138:141], v[30:33]
	v_and_b32_e32 v88, 0xffff0000, v141
	v_sub_f32_e32 v82, v82, v88
	v_cvt_pk_bf16_f32 v145, v59, v82
	s_nop 0
	v_mfma_f32_16x16x32_bf16 v[30:33], v[146:149], v[142:145], v[30:33]
	ds_read_b128 v[146:149], v75 offset:62272
	ds_read_b128 v[154:157], v75 offset:64576
	s_waitcnt lgkmcnt(1)
	v_mfma_f32_16x16x32_bf16 v[30:33], v[146:149], v[138:141], v[30:33]
	ds_read_b128 v[146:149], v75 offset:43840
	ds_read_b128 v[158:161], v75 offset:46144
	s_waitcnt lgkmcnt(1)
	v_mfma_f32_16x16x32_bf16 v[14:17], v[146:149], v[138:141], v[14:17]
	v_mfma_f32_16x16x32_bf16 v[14:17], v[146:149], v[142:145], v[14:17]
	s_waitcnt lgkmcnt(0)
	v_mfma_f32_16x16x32_bf16 v[34:37], v[158:161], v[138:141], v[34:37]
	v_mfma_f32_16x16x32_bf16 v[14:17], v[154:157], v[138:141], v[14:17]
	ds_read_b128 v[146:149], v84 offset:25344
	ds_read_b128 v[154:157], v84 offset:39168
	v_mfma_f32_16x16x32_bf16 v[34:37], v[158:161], v[142:145], v[34:37]
	s_waitcnt lgkmcnt(1)
	v_mfma_f32_16x16x32_bf16 v[34:37], v[146:149], v[138:141], v[34:37]
	ds_read_b128 v[146:149], v75 offset:48448
	ds_read_b128 v[158:161], v75 offset:50752
	s_waitcnt lgkmcnt(1)
	v_mfma_f32_16x16x32_bf16 v[22:25], v[146:149], v[138:141], v[22:25]
	v_mfma_f32_16x16x32_bf16 v[22:25], v[146:149], v[142:145], v[22:25]
	ds_read_b128 v[146:149], v84 offset:27648
	ds_read_b128 v[162:165], v84 offset:29952
	s_waitcnt lgkmcnt(2)
	v_mfma_f32_16x16x32_bf16 v[26:29], v[158:161], v[138:141], v[26:29]
	s_waitcnt lgkmcnt(1)
	v_mfma_f32_16x16x32_bf16 v[22:25], v[146:149], v[138:141], v[22:25]
	v_mfma_f32_16x16x32_bf16 v[26:29], v[158:161], v[142:145], v[26:29]
	ds_read_b128 v[146:149], v75 offset:53056
	ds_read_b128 v[158:161], v75 offset:55360
	s_waitcnt lgkmcnt(1)
	v_mfma_f32_16x16x32_bf16 v[10:13], v[146:149], v[138:141], v[10:13]
	v_mfma_f32_16x16x32_bf16 v[10:13], v[146:149], v[142:145], v[10:13]
	s_waitcnt lgkmcnt(0)
	v_mfma_f32_16x16x32_bf16 v[18:21], v[158:161], v[138:141], v[18:21]
	v_mfma_f32_16x16x32_bf16 v[10:13], v[150:153], v[138:141], v[10:13]
	ds_read_b128 v[146:149], v84 offset:34560
	ds_read_b128 v[150:153], v84 offset:36864
	v_mfma_f32_16x16x32_bf16 v[18:21], v[158:161], v[142:145], v[18:21]
	s_waitcnt lgkmcnt(1)
	v_mfma_f32_16x16x32_bf16 v[18:21], v[146:149], v[138:141], v[18:21]
	ds_read_b128 v[146:149], v75 offset:57664
	ds_read_b128 v[158:161], v75 offset:59968
	s_waitcnt lgkmcnt(1)
	v_mfma_f32_16x16x32_bf16 v[6:9], v[146:149], v[138:141], v[6:9]
	s_waitcnt lgkmcnt(0)
	v_mfma_f32_16x16x32_bf16 v[2:5], v[158:161], v[138:141], v[2:5]
	v_mfma_f32_16x16x32_bf16 v[6:9], v[146:149], v[142:145], v[6:9]
	v_mfma_f32_16x16x32_bf16 v[2:5], v[158:161], v[142:145], v[2:5]
	v_mfma_f32_16x16x32_bf16 v[26:29], v[162:165], v[138:141], v[26:29]
	v_mfma_f32_16x16x32_bf16 v[6:9], v[150:153], v[138:141], v[6:9]
	v_mfma_f32_16x16x32_bf16 v[2:5], v[154:157], v[138:141], v[2:5]

.LBB0_594:
	v_add_co_u32_e32 v138, vcc, 0x21c0000, v70
	s_nop 1
	v_addc_co_u32_e32 v139, vcc, 0, v71, vcc
	v_add_co_u32_e32 v140, vcc, 0x21c9000, v70
	s_nop 1
	v_addc_co_u32_e32 v141, vcc, 0, v71, vcc
	v_add_co_u32_e32 v142, vcc, 0x21d2000, v70
	s_nop 1
	v_addc_co_u32_e32 v143, vcc, 0, v71, vcc
	v_add_co_u32_e32 v144, vcc, 0x21db000, v70
	s_nop 1
	v_addc_co_u32_e32 v145, vcc, 0, v71, vcc
	v_add_co_u32_e32 v146, vcc, 0x21e4000, v70
	s_nop 1
	v_addc_co_u32_e32 v147, vcc, 0, v71, vcc
	v_add_co_u32_e32 v148, vcc, 0x21ed000, v70
	s_nop 1
	v_addc_co_u32_e32 v149, vcc, 0, v71, vcc
	v_add_co_u32_e32 v150, vcc, 0x21f6000, v70
	s_nop 1
	v_addc_co_u32_e32 v151, vcc, 0, v71, vcc
	v_add_co_u32_e32 v152, vcc, 0x21ff000, v70
	s_nop 1
	v_addc_co_u32_e32 v153, vcc, 0, v71, vcc
	global_load_dword v128, v[138:139], off nt
	global_load_dword v125, v[140:141], off nt
	global_load_dword v122, v[142:143], off nt
	global_load_dword v119, v[144:145], off nt
	global_load_dword v115, v[146:147], off nt
	global_load_dword v113, v[148:149], off nt
	global_load_dword v109, v[150:151], off nt
	global_load_dword v105, v[152:153], off nt
	v_add_co_u32_e32 v138, vcc, 0x22e0000, v70
	s_nop 1
	v_addc_co_u32_e32 v139, vcc, 0, v71, vcc
	v_add_co_u32_e32 v140, vcc, 0x22e9000, v70
	s_nop 1
	v_addc_co_u32_e32 v141, vcc, 0, v71, vcc
	v_add_co_u32_e32 v142, vcc, 0x22f2000, v70
	s_nop 1
	v_addc_co_u32_e32 v143, vcc, 0, v71, vcc
	v_add_co_u32_e32 v144, vcc, 0x22fb000, v70
	s_nop 1
	v_addc_co_u32_e32 v145, vcc, 0, v71, vcc
	v_add_co_u32_e32 v146, vcc, 0x2304000, v70
	s_nop 1
	v_addc_co_u32_e32 v147, vcc, 0, v71, vcc
	v_add_co_u32_e32 v148, vcc, 0x230d000, v70
	s_nop 1
	v_addc_co_u32_e32 v149, vcc, 0, v71, vcc
	v_add_co_u32_e32 v150, vcc, 0x2316000, v70
	s_nop 1
	v_addc_co_u32_e32 v151, vcc, 0, v71, vcc
	v_add_co_u32_e32 v152, vcc, 0x231f000, v70
	s_nop 1
	v_addc_co_u32_e32 v153, vcc, 0, v71, vcc
	global_load_dword v101, v[138:139], off nt
	global_load_dword v96, v[140:141], off nt
	global_load_dword v94, v[142:143], off nt
	global_load_dword v88, v[144:145], off nt
	global_load_dword v84, v[146:147], off nt
	global_load_dword v82, v[148:149], off nt
	global_load_dword v71, v[150:151], off nt
	global_load_dword v70, v[152:153], off nt
	s_and_b64 vcc, exec, s[6:7]
	s_cbranch_vccnz .LBB0_596
	ds_read_b128 v[146:149], v75 offset:64
	ds_read_b128 v[150:153], v75 offset:39232
	v_cvt_pk_bf16_f32 v138, v110, v106
	v_cvt_pk_bf16_f32 v139, v102, v97
	v_cvt_pk_bf16_f32 v140, v92, v89
	v_cvt_pk_bf16_f32 v141, v85, v80
	s_nop 0
	v_lshlrev_b32_e32 v59, 16, v138
	v_sub_f32_e32 v59, v110, v59
	v_and_b32_e32 v110, 0xffff0000, v138
	v_sub_f32_e32 v106, v106, v110
	v_cvt_pk_bf16_f32 v142, v59, v106
	v_lshlrev_b32_e32 v59, 16, v139
	v_sub_f32_e32 v59, v102, v59
	v_and_b32_e32 v102, 0xffff0000, v139
	v_sub_f32_e32 v97, v97, v102
	v_cvt_pk_bf16_f32 v143, v59, v97
	v_lshlrev_b32_e32 v59, 16, v140
	s_waitcnt lgkmcnt(1)
	v_mfma_f32_16x16x32_bf16 v[30:33], v[146:149], v[138:141], v[30:33]
	v_sub_f32_e32 v59, v92, v59
	v_and_b32_e32 v92, 0xffff0000, v140
	v_sub_f32_e32 v89, v89, v92
	v_cvt_pk_bf16_f32 v144, v59, v89
	v_lshlrev_b32_e32 v59, 16, v141
	v_sub_f32_e32 v59, v85, v59
	v_and_b32_e32 v85, 0xffff0000, v141
	v_sub_f32_e32 v80, v80, v85
	v_cvt_pk_bf16_f32 v145, v59, v80
	s_nop 0
	v_mfma_f32_16x16x32_bf16 v[30:33], v[146:149], v[142:145], v[30:33]
	ds_read_b128 v[146:149], v75 offset:20800
	ds_read_b128 v[154:157], v75 offset:23104
	s_waitcnt lgkmcnt(1)
	v_mfma_f32_16x16x32_bf16 v[30:33], v[146:149], v[138:141], v[30:33]
	ds_read_b128 v[146:149], v75 offset:2368
	ds_read_b128 v[158:161], v75 offset:4672
	s_waitcnt lgkmcnt(1)
	v_mfma_f32_16x16x32_bf16 v[14:17], v[146:149], v[138:141], v[14:17]
	v_mfma_f32_16x16x32_bf16 v[14:17], v[146:149], v[142:145], v[14:17]
	s_waitcnt lgkmcnt(0)
	v_mfma_f32_16x16x32_bf16 v[34:37], v[158:161], v[138:141], v[34:37]
	v_mfma_f32_16x16x32_bf16 v[14:17], v[154:157], v[138:141], v[14:17]
	ds_read_b128 v[146:149], v75 offset:25408
	ds_read_b128 v[154:157], v75 offset:27712
	v_mfma_f32_16x16x32_bf16 v[34:37], v[158:161], v[142:145], v[34:37]
	s_waitcnt lgkmcnt(1)
	v_mfma_f32_16x16x32_bf16 v[34:37], v[146:149], v[138:141], v[34:37]
	ds_read_b128 v[146:149], v75 offset:6976
	ds_read_b128 v[158:161], v75 offset:9280
	s_waitcnt lgkmcnt(1)
	v_mfma_f32_16x16x32_bf16 v[22:25], v[146:149], v[138:141], v[22:25]
	v_mfma_f32_16x16x32_bf16 v[22:25], v[146:149], v[142:145], v[22:25]
	s_waitcnt lgkmcnt(0)
	v_mfma_f32_16x16x32_bf16 v[26:29], v[158:161], v[138:141], v[26:29]
	v_mfma_f32_16x16x32_bf16 v[22:25], v[154:157], v[138:141], v[22:25]
	ds_read_b128 v[146:149], v75 offset:30016
	ds_read_b128 v[154:157], v75 offset:32320
	v_mfma_f32_16x16x32_bf16 v[26:29], v[158:161], v[142:145], v[26:29]
	s_waitcnt lgkmcnt(1)
	v_mfma_f32_16x16x32_bf16 v[26:29], v[146:149], v[138:141], v[26:29]
	ds_read_b128 v[146:149], v75 offset:11584
	ds_read_b128 v[158:161], v75 offset:13888
	s_waitcnt lgkmcnt(1)
	v_mfma_f32_16x16x32_bf16 v[10:13], v[146:149], v[138:141], v[10:13]
	v_mfma_f32_16x16x32_bf16 v[10:13], v[146:149], v[142:145], v[10:13]
	s_waitcnt lgkmcnt(0)
	v_mfma_f32_16x16x32_bf16 v[18:21], v[158:161], v[138:141], v[18:21]
	v_mfma_f32_16x16x32_bf16 v[10:13], v[154:157], v[138:141], v[10:13]
	ds_read_b128 v[146:149], v75 offset:34624
	ds_read_b128 v[154:157], v75 offset:36928
	v_mfma_f32_16x16x32_bf16 v[18:21], v[158:161], v[142:145], v[18:21]
	s_waitcnt lgkmcnt(1)
	v_mfma_f32_16x16x32_bf16 v[18:21], v[146:149], v[138:141], v[18:21]
	ds_read_b128 v[146:149], v75 offset:16192
	ds_read_b128 v[158:161], v75 offset:18496
	s_waitcnt lgkmcnt(1)
	v_mfma_f32_16x16x32_bf16 v[6:9], v[146:149], v[138:141], v[6:9]
	s_waitcnt lgkmcnt(0)
	v_mfma_f32_16x16x32_bf16 v[2:5], v[158:161], v[138:141], v[2:5]
	v_mfma_f32_16x16x32_bf16 v[6:9], v[146:149], v[142:145], v[6:9]
	v_mfma_f32_16x16x32_bf16 v[2:5], v[158:161], v[142:145], v[2:5]
	v_mfma_f32_16x16x32_bf16 v[6:9], v[154:157], v[138:141], v[6:9]
	v_mfma_f32_16x16x32_bf16 v[2:5], v[150:153], v[138:141], v[2:5]

.LBB0_668:
	s_and_b64 vcc, exec, s[6:7]
	s_barrier
	s_cbranch_vccnz .LBB0_672
	s_nop 4
	v_mov_b64_e32 v[4:5], s[0:1]
	s_waitcnt vmcnt(0)
	global_load_dwordx2 v[38:39], v[4:5], off offset:80 sc0 sc1
	s_waitcnt vmcnt(0)
	s_mul_i32 s4, s2, 0x492000
	s_mul_hi_i32 s3, s2, 0x492000
	v_or_b32_e32 v40, s18, v72
	v_mov_b32_e32 v41, 0
	v_mov_b32_e32 v44, 0x9000
	s_add_u32 s4, s94, s4
	v_lshlrev_b64 v[42:43], 2, v[40:41]
	s_addc_u32 s5, s95, s3
	v_mul_u32_u24_e32 v40, 0x24000, v1
	s_mov_b64 s[6:7], 0x5800000
	v_lshl_add_u64 v[4:5], s[4:5], 0, v[42:43]
	v_lshl_add_u64 v[4:5], v[4:5], 0, s[6:7]
	s_mov_b32 s9, 0x12000
	v_lshl_add_u64 v[40:41], v[4:5], 0, v[40:41]
	s_mov_b32 s10, 0x1b000
	s_mov_b32 s8, 0x24000
	s_mov_b32 s11, 0x2d000
	s_mov_b32 s12, 0xa2000
	s_mov_b32 s13, 0xab000
	s_mov_b32 s18, 0xb4000
	s_mov_b32 s19, 0xbd000
	s_mov_b32 s20, 0x132000
	s_mov_b32 s21, 0x13b000
	s_mov_b32 s22, 0x144000
	s_mov_b32 s23, 0x14d000
	s_mov_b32 s24, 0x1c2000
	s_mov_b32 s25, 0x1cb000
	s_mov_b32 s26, 0x1d4000
	s_mov_b32 s27, 0x1dd000
	s_mov_b32 s28, 0x252000
	s_mov_b32 s29, 0x25b000
	s_mov_b32 s30, 0x264000
	s_mov_b32 s31, 0x26d000
	s_mov_b32 s33, 0x2e2000
	s_waitcnt lgkmcnt(0)
	v_mad_i64_i32 v[38:39], s[2:3], s2, v44, v[38:39]
	v_lshl_add_u64 v[38:39], v[38:39], 0, v[42:43]
	global_load_dword v1, v[38:39], off nt
	v_add_co_u32_e32 v38, vcc, s9, v40
	s_mov_b32 s2, 0x2eb000
	s_nop 0
	v_addc_co_u32_e32 v39, vcc, 0, v41, vcc
	v_add_co_u32_e32 v42, vcc, s10, v40
	s_waitcnt vmcnt(0)
	v_add_f32_e32 v30, v30, v1
	v_addc_co_u32_e32 v43, vcc, 0, v41, vcc
	v_add_co_u32_e32 v44, vcc, s8, v40
	v_add_f32_e32 v14, v14, v1
	s_nop 0
	v_addc_co_u32_e32 v45, vcc, 0, v41, vcc
	v_add_co_u32_e32 v46, vcc, s11, v40
	v_add_f32_e32 v31, v31, v1
	s_nop 0
	v_addc_co_u32_e32 v47, vcc, 0, v41, vcc
	v_add_co_u32_e32 v48, vcc, s12, v40
	v_add_f32_e32 v32, v32, v1
	s_nop 0
	v_addc_co_u32_e32 v49, vcc, 0, v41, vcc
	v_add_co_u32_e32 v50, vcc, s13, v40
	v_add_f32_e32 v33, v33, v1
	s_nop 0
	v_addc_co_u32_e32 v51, vcc, 0, v41, vcc
	v_add_co_u32_e32 v52, vcc, s18, v40
	v_add_f32_e32 v15, v15, v1
	s_nop 0
	v_addc_co_u32_e32 v53, vcc, 0, v41, vcc
	v_add_co_u32_e32 v54, vcc, s19, v40
	v_add_f32_e32 v16, v16, v1
	s_nop 0
	v_addc_co_u32_e32 v55, vcc, 0, v41, vcc
	v_add_co_u32_e32 v56, vcc, s20, v40
	v_add_f32_e32 v17, v17, v1
	s_nop 0
	v_addc_co_u32_e32 v57, vcc, 0, v41, vcc
	v_add_co_u32_e32 v58, vcc, s21, v40
	v_add_f32_e32 v34, v34, v1
	s_nop 0
	v_addc_co_u32_e32 v59, vcc, 0, v41, vcc
	v_add_co_u32_e32 v60, vcc, s22, v40
	v_add_f32_e32 v35, v35, v1
	s_nop 0
	v_addc_co_u32_e32 v61, vcc, 0, v41, vcc
	v_add_co_u32_e32 v62, vcc, s23, v40
	v_add_f32_e32 v36, v36, v1
	s_nop 0
	v_addc_co_u32_e32 v63, vcc, 0, v41, vcc
	v_add_co_u32_e32 v64, vcc, s24, v40
	v_add_f32_e32 v37, v37, v1
	s_nop 0
	v_addc_co_u32_e32 v65, vcc, 0, v41, vcc
	v_add_co_u32_e32 v66, vcc, s25, v40
	v_add_f32_e32 v22, v22, v1
	s_nop 0
	v_addc_co_u32_e32 v67, vcc, 0, v41, vcc
	v_add_co_u32_e32 v68, vcc, s26, v40
	v_add_f32_e32 v23, v23, v1
	s_nop 0
	v_addc_co_u32_e32 v69, vcc, 0, v41, vcc
	v_add_co_u32_e32 v70, vcc, s27, v40
	v_add_f32_e32 v24, v24, v1
	s_nop 0
	v_addc_co_u32_e32 v71, vcc, 0, v41, vcc
	v_add_co_u32_e32 v72, vcc, s28, v40
	v_add_f32_e32 v25, v25, v1
	s_nop 0
	v_addc_co_u32_e32 v73, vcc, 0, v41, vcc
	v_add_co_u32_e32 v74, vcc, s29, v40
	v_add_f32_e32 v26, v26, v1
	s_nop 0
	v_addc_co_u32_e32 v75, vcc, 0, v41, vcc
	v_add_co_u32_e32 v76, vcc, s30, v40
	v_add_f32_e32 v27, v27, v1
	s_nop 0
	v_addc_co_u32_e32 v77, vcc, 0, v41, vcc
	v_add_co_u32_e32 v78, vcc, s31, v40
	v_add_f32_e32 v28, v28, v1
	s_nop 0
	v_addc_co_u32_e32 v79, vcc, 0, v41, vcc
	v_add_f32_e32 v29, v29, v1
	global_store_dword v[38:39], v30, off
	global_store_dword v[42:43], v31, off
	global_store_dword v[44:45], v32, off
	global_store_dword v[46:47], v33, off
	global_store_dword v[48:49], v14, off
	global_store_dword v[50:51], v15, off
	global_store_dword v[52:53], v16, off
	global_store_dword v[54:55], v17, off
	global_store_dword v[56:57], v34, off
	global_store_dword v[58:59], v35, off
	global_store_dword v[60:61], v36, off
	global_store_dword v[62:63], v37, off
	global_store_dword v[64:65], v22, off
	global_store_dword v[66:67], v23, off
	global_store_dword v[68:69], v24, off
	global_store_dword v[70:71], v25, off
	global_store_dword v[72:73], v26, off
	global_store_dword v[74:75], v27, off
	global_store_dword v[76:77], v28, off
	global_store_dword v[78:79], v29, off
	v_add_co_u32_e32 v14, vcc, s33, v40
	v_add_f32_e32 v10, v10, v1
	s_nop 0
	v_addc_co_u32_e32 v15, vcc, 0, v41, vcc
	global_store_dword v[14:15], v10, off
	v_add_co_u32_e32 v10, vcc, s2, v40
	v_add_f32_e32 v14, v11, v1
	s_nop 0
	v_addc_co_u32_e32 v11, vcc, 0, v41, vcc
	s_mov_b32 s2, 0x2f4000
	global_store_dword v[10:11], v14, off
	v_add_co_u32_e32 v10, vcc, s2, v40
	v_add_f32_e32 v12, v12, v1
	s_nop 0
	v_addc_co_u32_e32 v11, vcc, 0, v41, vcc
	s_mov_b32 s2, 0x2fd000
	global_store_dword v[10:11], v12, off
	v_add_co_u32_e32 v10, vcc, s2, v40
	v_add_f32_e32 v12, v13, v1
	s_nop 0
	v_addc_co_u32_e32 v11, vcc, 0, v41, vcc
	s_mov_b32 s2, 0x372000
	global_store_dword v[10:11], v12, off
	v_add_co_u32_e32 v10, vcc, s2, v40
	v_add_f32_e32 v12, v18, v1
	s_nop 0
	v_addc_co_u32_e32 v11, vcc, 0, v41, vcc
	s_mov_b32 s2, 0x37b000
	global_store_dword v[10:11], v12, off
	v_add_co_u32_e32 v10, vcc, s2, v40
	v_add_f32_e32 v12, v19, v1
	s_nop 0
	v_addc_co_u32_e32 v11, vcc, 0, v41, vcc
	s_mov_b32 s2, 0x384000
	global_store_dword v[10:11], v12, off
	v_add_co_u32_e32 v10, vcc, s2, v40
	v_add_f32_e32 v12, v20, v1
	s_nop 0
	v_addc_co_u32_e32 v11, vcc, 0, v41, vcc
	s_mov_b32 s2, 0x38d000
	global_store_dword v[10:11], v12, off
	v_add_co_u32_e32 v10, vcc, s2, v40
	v_add_f32_e32 v12, v21, v1
	s_nop 0
	v_addc_co_u32_e32 v11, vcc, 0, v41, vcc
	s_mov_b32 s2, 0x402000
	global_store_dword v[10:11], v12, off
	v_add_co_u32_e32 v10, vcc, s2, v40
	v_add_f32_e32 v6, v6, v1
	s_nop 0
	v_addc_co_u32_e32 v11, vcc, 0, v41, vcc
	s_mov_b32 s2, 0x40b000
	global_store_dword v[10:11], v6, off
	v_add_co_u32_e32 v6, vcc, s2, v40
	v_add_f32_e32 v10, v7, v1
	s_nop 0
	v_addc_co_u32_e32 v7, vcc, 0, v41, vcc
	s_mov_b32 s2, 0x414000
	global_store_dword v[6:7], v10, off
	v_add_co_u32_e32 v6, vcc, s2, v40
	v_add_f32_e32 v8, v8, v1
	s_nop 0
	v_addc_co_u32_e32 v7, vcc, 0, v41, vcc
	global_store_dword v[6:7], v8, off
	v_add_co_u32_e32 v6, vcc, 0x41d000, v40
	v_add_f32_e32 v8, v9, v1
	s_nop 0
	v_addc_co_u32_e32 v7, vcc, 0, v41, vcc
	v_cmp_gt_u32_e32 vcc, 16, v98
	global_store_dword v[6:7], v8, off
	s_and_saveexec_b64 s[6:7], vcc
	s_cbranch_execz .LBB0_671
	v_add_f32_e32 v2, v2, v1
	global_store_dword v[4:5], v2, off
	v_add_co_u32_e32 v2, vcc, 0x9000, v4
	v_add_f32_e32 v1, v3, v1
	s_nop 0
	v_addc_co_u32_e32 v3, vcc, 0, v5, vcc
	global_store_dword v[2:3], v1, off

.LBB0_1711:
	s_cmp_lt_i32 s90, 9
	s_cselect_b64 s[4:5], -1, 0
	s_cmp_gt_i32 s91, 8
	s_cselect_b64 s[6:7], -1, 0
	s_and_b64 s[4:5], s[4:5], s[6:7]
	s_andn2_b64 vcc, exec, s[4:5]
	s_cbranch_vccnz .LBB0_2258
	s_add_u32 s2, s38, 0x31600000
	s_addc_u32 s4, s39, 0
	s_cmp_gt_i32 s40, 15
	s_cselect_b64 s[6:7], -1, 0
	s_and_b32 s5, s40, 6
	s_cmp_eq_u32 s5, 6
	s_cselect_b64 s[8:9], -1, 0
	s_ashr_i32 s41, s40, 31
	s_or_b64 s[14:15], s[6:7], s[8:9]
	s_lshl_b32 s8, s3, 5
	s_lshl_b64 s[6:7], s[40:41], 18
	s_add_u32 s26, s2, s6
	s_addc_u32 s27, s4, s7
	s_add_u32 s16, s26, 0x80000
	s_addc_u32 s17, s27, 0
	s_ashr_i32 s9, s8, 31
	s_lshl_b64 s[6:7], s[8:9], 10
	s_add_u32 s6, s26, s6
	s_addc_u32 s7, s27, s7
	s_add_u32 s5, s6, 0x800
	s_addc_u32 s9, s7, 0
	v_mov_b32_e32 v133, 0
	s_and_b64 s[10:11], s[14:15], exec
	s_cselect_b32 s10, s6, s16
	s_cselect_b32 s11, s7, s17
	s_cmp_lt_i32 s3, 8
	v_lshlrev_b64 v[24:25], 2, v[132:133]
	s_cselect_b32 s11, s9, s11
	s_cselect_b32 s10, s5, s10
	v_lshl_add_u64 v[2:3], s[6:7], 0, v[24:25]
	s_or_b32 s6, s8, 1
	s_ashr_i32 s7, s6, 31
	global_load_dword v20, v[2:3], off nt
	global_load_dword v21, v[2:3], off offset:256 nt
	v_lshl_add_u64 v[2:3], s[10:11], 0, v[24:25]
	s_lshl_b64 s[10:11], s[6:7], 10
	s_add_u32 s10, s26, s10
	s_addc_u32 s11, s27, s11
	s_add_u32 s5, s10, 0x800
	s_addc_u32 s7, s11, 0
	s_add_u32 s9, s26, 0x80400
	s_addc_u32 s28, s27, 0
	s_and_b64 s[12:13], s[14:15], exec
	s_cselect_b32 s12, s10, s9
	s_cselect_b32 s13, s11, s28
	s_cmpk_lt_i32 s6, 0xfe
	s_cselect_b32 s7, s7, s13
	s_cselect_b32 s6, s5, s12
	s_or_b32 s90, s8, 2
	global_load_dword v22, v[2:3], off offset:512 nt
	global_load_dword v23, v[2:3], off offset:768 nt
	v_lshl_add_u64 v[2:3], s[10:11], 0, v[24:25]
	s_ashr_i32 s91, s90, 31
	global_load_dword v107, v[2:3], off nt
	global_load_dword v105, v[2:3], off offset:256 nt
	v_lshl_add_u64 v[2:3], s[6:7], 0, v[24:25]
	s_lshl_b64 s[6:7], s[90:91], 10
	s_add_u32 s6, s26, s6
	s_addc_u32 s7, s27, s7
	s_add_u32 s5, s6, 0x800
	s_addc_u32 s12, s7, 0
	s_and_b64 s[10:11], s[14:15], exec
	s_cselect_b32 s10, s6, s16
	s_cselect_b32 s11, s7, s17
	s_cmpk_lt_i32 s90, 0xfe
	s_cselect_b32 s11, s12, s11
	s_cselect_b32 s10, s5, s10
	s_or_b32 s88, s8, 3
	s_ashr_i32 s89, s88, 31
	global_load_dword v108, v[2:3], off offset:512 nt
	global_load_dword v106, v[2:3], off offset:768 nt
	v_lshl_add_u64 v[2:3], s[6:7], 0, v[24:25]
	s_lshl_b64 s[6:7], s[88:89], 10
	s_add_u32 s6, s26, s6
	s_addc_u32 s7, s27, s7
	s_add_u32 s5, s6, 0x800
	s_addc_u32 s12, s7, 0
	global_load_dword v103, v[2:3], off nt
	global_load_dword v100, v[2:3], off offset:256 nt
	v_lshl_add_u64 v[2:3], s[10:11], 0, v[24:25]
	s_and_b64 s[10:11], s[14:15], exec
	s_cselect_b32 s10, s6, s9
	s_cselect_b32 s11, s7, s28
	s_cmpk_lt_i32 s88, 0xfe
	s_cselect_b32 s11, s12, s11
	s_cselect_b32 s10, s5, s10
	s_or_b32 s86, s8, 4
	s_ashr_i32 s87, s86, 31
	global_load_dword v104, v[2:3], off offset:512 nt
	global_load_dword v102, v[2:3], off offset:768 nt
	v_lshl_add_u64 v[2:3], s[6:7], 0, v[24:25]
	s_lshl_b64 s[6:7], s[86:87], 10
	s_add_u32 s6, s26, s6
	s_addc_u32 s7, s27, s7
	s_add_u32 s5, s6, 0x800
	s_addc_u32 s12, s7, 0
	global_load_dword v98, v[2:3], off nt
	global_load_dword v97, v[2:3], off offset:256 nt
	v_lshl_add_u64 v[2:3], s[10:11], 0, v[24:25]
	s_and_b64 s[10:11], s[14:15], exec
	s_cselect_b32 s10, s6, s16
	s_cselect_b32 s11, s7, s17
	s_cmpk_lt_i32 s86, 0xfe
	s_cselect_b32 s11, s12, s11
	s_cselect_b32 s10, s5, s10
	s_or_b32 s84, s8, 5
	s_ashr_i32 s85, s84, 31
	global_load_dword v101, v[2:3], off offset:512 nt
	global_load_dword v99, v[2:3], off offset:768 nt
	v_lshl_add_u64 v[2:3], s[6:7], 0, v[24:25]
	s_lshl_b64 s[6:7], s[84:85], 10
	s_add_u32 s6, s26, s6
	s_addc_u32 s7, s27, s7
	s_add_u32 s5, s6, 0x800
	s_addc_u32 s12, s7, 0
	global_load_dword v94, v[2:3], off nt
	global_load_dword v93, v[2:3], off offset:256 nt
	v_lshl_add_u64 v[2:3], s[10:11], 0, v[24:25]
	s_and_b64 s[10:11], s[14:15], exec
	s_cselect_b32 s10, s6, s9
	s_cselect_b32 s11, s7, s28
	s_cmpk_lt_i32 s84, 0xfe
	s_cselect_b32 s11, s12, s11
	s_cselect_b32 s10, s5, s10
	s_or_b32 s82, s8, 6
	s_ashr_i32 s83, s82, 31
	global_load_dword v96, v[2:3], off offset:512 nt
	global_load_dword v95, v[2:3], off offset:768 nt
	v_lshl_add_u64 v[2:3], s[6:7], 0, v[24:25]
	s_lshl_b64 s[6:7], s[82:83], 10
	s_add_u32 s6, s26, s6
	s_addc_u32 s7, s27, s7
	s_add_u32 s5, s6, 0x800
	s_addc_u32 s12, s7, 0
	global_load_dword v90, v[2:3], off nt
	global_load_dword v89, v[2:3], off offset:256 nt
	v_lshl_add_u64 v[2:3], s[10:11], 0, v[24:25]
	s_and_b64 s[10:11], s[14:15], exec
	s_cselect_b32 s10, s6, s16
	s_cselect_b32 s11, s7, s17
	s_cmpk_lt_i32 s82, 0xfe
	s_cselect_b32 s11, s12, s11
	s_cselect_b32 s10, s5, s10
	s_or_b32 s80, s8, 7
	s_ashr_i32 s81, s80, 31
	global_load_dword v92, v[2:3], off offset:512 nt
	global_load_dword v91, v[2:3], off offset:768 nt
	v_lshl_add_u64 v[2:3], s[6:7], 0, v[24:25]
	s_lshl_b64 s[6:7], s[80:81], 10
	s_add_u32 s6, s26, s6
	s_addc_u32 s7, s27, s7
	s_add_u32 s5, s6, 0x800
	s_addc_u32 s12, s7, 0
	global_load_dword v87, v[2:3], off nt
	global_load_dword v85, v[2:3], off offset:256 nt
	v_lshl_add_u64 v[2:3], s[10:11], 0, v[24:25]
	s_and_b64 s[10:11], s[14:15], exec
	s_cselect_b32 s10, s6, s9
	s_cselect_b32 s11, s7, s28
	s_cmpk_lt_i32 s80, 0xfe
	s_cselect_b32 s11, s12, s11
	s_cselect_b32 s10, s5, s10
	s_or_b32 s78, s8, 8
	s_ashr_i32 s79, s78, 31
	global_load_dword v88, v[2:3], off offset:512 nt
	global_load_dword v86, v[2:3], off offset:768 nt
	v_lshl_add_u64 v[2:3], s[6:7], 0, v[24:25]
	s_lshl_b64 s[6:7], s[78:79], 10
	s_add_u32 s6, s26, s6
	s_addc_u32 s7, s27, s7
	s_add_u32 s5, s6, 0x800
	s_addc_u32 s12, s7, 0
	global_load_dword v82, v[2:3], off nt
	global_load_dword v81, v[2:3], off offset:256 nt
	v_lshl_add_u64 v[2:3], s[10:11], 0, v[24:25]
	s_and_b64 s[10:11], s[14:15], exec
	s_cselect_b32 s10, s6, s16
	s_cselect_b32 s11, s7, s17
	s_cmpk_lt_i32 s78, 0xfe
	s_cselect_b32 s11, s12, s11
	s_cselect_b32 s10, s5, s10
	s_or_b32 s76, s8, 9
	s_ashr_i32 s77, s76, 31
	global_load_dword v84, v[2:3], off offset:512 nt
	global_load_dword v83, v[2:3], off offset:768 nt
	v_lshl_add_u64 v[2:3], s[6:7], 0, v[24:25]
	s_lshl_b64 s[6:7], s[76:77], 10
	s_add_u32 s6, s26, s6
	s_addc_u32 s7, s27, s7
	s_add_u32 s5, s6, 0x800
	s_addc_u32 s12, s7, 0
	global_load_dword v79, v[2:3], off nt
	global_load_dword v77, v[2:3], off offset:256 nt
	v_lshl_add_u64 v[2:3], s[10:11], 0, v[24:25]
	s_and_b64 s[10:11], s[14:15], exec
	s_cselect_b32 s10, s6, s9
	s_cselect_b32 s11, s7, s28
	s_cmpk_lt_i32 s76, 0xfe
	s_cselect_b32 s11, s12, s11
	s_cselect_b32 s10, s5, s10
	s_or_b32 s74, s8, 10
	s_ashr_i32 s75, s74, 31
	global_load_dword v80, v[2:3], off offset:512 nt
	global_load_dword v78, v[2:3], off offset:768 nt
	v_lshl_add_u64 v[2:3], s[6:7], 0, v[24:25]
	s_lshl_b64 s[6:7], s[74:75], 10
	s_add_u32 s6, s26, s6
	s_addc_u32 s7, s27, s7
	s_add_u32 s5, s6, 0x800
	s_addc_u32 s12, s7, 0
	global_load_dword v73, v[2:3], off nt
	global_load_dword v72, v[2:3], off offset:256 nt
	v_lshl_add_u64 v[2:3], s[10:11], 0, v[24:25]
	s_and_b64 s[10:11], s[14:15], exec
	s_cselect_b32 s10, s6, s16
	s_cselect_b32 s11, s7, s17
	s_cmpk_lt_i32 s74, 0xfe
	s_cselect_b32 s11, s12, s11
	s_cselect_b32 s10, s5, s10
	s_or_b32 s70, s8, 11
	s_ashr_i32 s71, s70, 31
	global_load_dword v76, v[2:3], off offset:512 nt
	global_load_dword v74, v[2:3], off offset:768 nt
	v_lshl_add_u64 v[2:3], s[6:7], 0, v[24:25]
	s_lshl_b64 s[6:7], s[70:71], 10
	s_add_u32 s6, s26, s6
	s_addc_u32 s7, s27, s7
	s_add_u32 s5, s6, 0x800
	s_addc_u32 s12, s7, 0
	global_load_dword v70, v[2:3], off nt
	global_load_dword v68, v[2:3], off offset:256 nt
	v_lshl_add_u64 v[2:3], s[10:11], 0, v[24:25]
	s_and_b64 s[10:11], s[14:15], exec
	s_cselect_b32 s10, s6, s9
	s_cselect_b32 s11, s7, s28
	s_cmpk_lt_i32 s70, 0xfe
	s_cselect_b32 s11, s12, s11
	s_cselect_b32 s10, s5, s10
	s_or_b32 s66, s8, 12
	s_ashr_i32 s67, s66, 31
	global_load_dword v71, v[2:3], off offset:512 nt
	global_load_dword v69, v[2:3], off offset:768 nt
	v_lshl_add_u64 v[2:3], s[6:7], 0, v[24:25]
	s_lshl_b64 s[6:7], s[66:67], 10
	s_add_u32 s6, s26, s6
	s_addc_u32 s7, s27, s7
	s_add_u32 s5, s6, 0x800
	s_addc_u32 s12, s7, 0
	global_load_dword v65, v[2:3], off nt
	global_load_dword v64, v[2:3], off offset:256 nt
	v_lshl_add_u64 v[2:3], s[10:11], 0, v[24:25]
	s_and_b64 s[10:11], s[14:15], exec
	s_cselect_b32 s10, s6, s16
	s_cselect_b32 s11, s7, s17
	s_cmpk_lt_i32 s66, 0xfe
	s_cselect_b32 s11, s12, s11
	s_cselect_b32 s10, s5, s10
	s_or_b32 s64, s8, 13
	s_ashr_i32 s65, s64, 31
	global_load_dword v67, v[2:3], off offset:512 nt
	global_load_dword v66, v[2:3], off offset:768 nt
	v_lshl_add_u64 v[2:3], s[6:7], 0, v[24:25]
	s_lshl_b64 s[6:7], s[64:65], 10
	s_add_u32 s6, s26, s6
	s_addc_u32 s7, s27, s7
	s_add_u32 s5, s6, 0x800
	s_addc_u32 s12, s7, 0
	global_load_dword v62, v[2:3], off nt
	global_load_dword v60, v[2:3], off offset:256 nt
	v_lshl_add_u64 v[2:3], s[10:11], 0, v[24:25]
	s_and_b64 s[10:11], s[14:15], exec
	s_cselect_b32 s10, s6, s9
	s_cselect_b32 s11, s7, s28
	s_cmpk_lt_i32 s64, 0xfe
	global_load_dword v63, v[2:3], off offset:512 nt
	global_load_dword v61, v[2:3], off offset:768 nt
	s_cselect_b32 s11, s12, s11
	s_cselect_b32 s10, s5, s10
	v_lshl_add_u64 v[2:3], s[6:7], 0, v[24:25]
	global_load_dword v56, v[2:3], off nt
	global_load_dword v55, v[2:3], off offset:256 nt
	v_lshl_add_u64 v[2:3], s[10:11], 0, v[24:25]
	s_or_b32 s10, s8, 14
	s_ashr_i32 s11, s10, 31
	s_lshl_b64 s[6:7], s[10:11], 10
	s_add_u32 s6, s26, s6
	s_addc_u32 s7, s27, s7
	s_add_u32 s5, s6, 0x800
	s_addc_u32 s11, s7, 0
	s_and_b64 s[12:13], s[14:15], exec
	s_cselect_b32 s12, s6, s16
	s_cselect_b32 s13, s7, s17
	s_cmpk_lt_i32 s10, 0xfe
	global_load_dword v59, v[2:3], off offset:512 nt
	global_load_dword v57, v[2:3], off offset:768 nt
	s_cselect_b32 s13, s11, s13
	s_cselect_b32 s12, s5, s12
	v_lshl_add_u64 v[2:3], s[6:7], 0, v[24:25]
	s_or_b32 s6, s8, 15
	s_ashr_i32 s7, s6, 31
	global_load_dword v53, v[2:3], off nt
	global_load_dword v51, v[2:3], off offset:256 nt
	v_lshl_add_u64 v[2:3], s[12:13], 0, v[24:25]
	s_lshl_b64 s[12:13], s[6:7], 10
	s_add_u32 s12, s26, s12
	s_addc_u32 s13, s27, s13
	s_add_u32 s5, s12, 0x800
	s_addc_u32 s7, s13, 0
	s_and_b64 s[18:19], s[14:15], exec
	s_cselect_b32 s11, s12, s9
	s_cselect_b32 s18, s13, s28
	s_cmpk_lt_i32 s6, 0xfe
	global_load_dword v54, v[2:3], off offset:512 nt
	global_load_dword v52, v[2:3], off offset:768 nt
	s_cselect_b32 s19, s7, s18
	s_cselect_b32 s18, s5, s11
	v_lshl_add_u64 v[2:3], s[12:13], 0, v[24:25]
	s_or_b32 s12, s8, 16
	s_ashr_i32 s13, s12, 31
	global_load_dword v49, v[2:3], off nt
	global_load_dword v1, v[2:3], off offset:256 nt
	v_lshl_add_u64 v[2:3], s[18:19], 0, v[24:25]
	s_and_b32 s5, s40, 1
	s_lshl_b64 s[18:19], s[12:13], 10
	s_add_u32 s18, s26, s18
	s_addc_u32 s19, s27, s19
	s_add_u32 s7, s18, 0x800
	s_addc_u32 s11, s19, 0
	s_and_b64 s[20:21], s[14:15], exec
	s_cselect_b32 s13, s18, s16
	s_cselect_b32 s20, s19, s17
	s_cmpk_lt_i32 s12, 0xfe
	s_cselect_b32 s21, s11, s20
	s_cselect_b32 s20, s7, s13
	s_or_b32 s62, s8, 17
	s_ashr_i32 s63, s62, 31
	global_load_dword v50, v[2:3], off offset:512 nt
	global_load_dword v48, v[2:3], off offset:768 nt
	v_lshl_add_u64 v[2:3], s[18:19], 0, v[24:25]
	s_lshl_b64 s[18:19], s[62:63], 10
	s_add_u32 s18, s26, s18
	s_addc_u32 s19, s27, s19
	s_add_u32 s7, s18, 0x800
	s_addc_u32 s11, s19, 0
	global_load_dword v38, v[2:3], off nt
	global_load_dword v39, v[2:3], off offset:256 nt
	v_lshl_add_u64 v[2:3], s[20:21], 0, v[24:25]
	s_and_b64 s[20:21], s[14:15], exec
	s_cselect_b32 s13, s18, s9
	s_cselect_b32 s20, s19, s28
	s_cmpk_lt_i32 s62, 0xfe
	s_cselect_b32 s21, s11, s20
	s_cselect_b32 s20, s7, s13
	s_or_b32 s60, s8, 18
	s_ashr_i32 s61, s60, 31
	global_load_dword v36, v[2:3], off offset:512 nt
	global_load_dword v37, v[2:3], off offset:768 nt
	v_lshl_add_u64 v[2:3], s[18:19], 0, v[24:25]
	s_lshl_b64 s[18:19], s[60:61], 10
	s_add_u32 s18, s26, s18
	s_addc_u32 s19, s27, s19
	s_add_u32 s7, s18, 0x800
	s_addc_u32 s11, s19, 0
	global_load_dword v177, v[2:3], off nt
	global_load_dword v175, v[2:3], off offset:256 nt
	v_lshl_add_u64 v[2:3], s[20:21], 0, v[24:25]
	s_and_b64 s[20:21], s[14:15], exec
	s_cselect_b32 s13, s18, s16
	s_cselect_b32 s20, s19, s17
	s_cmpk_lt_i32 s60, 0xfe
	s_cselect_b32 s21, s11, s20
	s_cselect_b32 s20, s7, s13
	s_or_b32 s58, s8, 19
	s_ashr_i32 s59, s58, 31
	global_load_dword v178, v[2:3], off offset:512 nt
	global_load_dword v176, v[2:3], off offset:768 nt
	v_lshl_add_u64 v[2:3], s[18:19], 0, v[24:25]
	s_lshl_b64 s[18:19], s[58:59], 10
	s_add_u32 s18, s26, s18
	s_addc_u32 s19, s27, s19
	s_add_u32 s7, s18, 0x800
	s_addc_u32 s11, s19, 0
	global_load_dword v173, v[2:3], off nt
	global_load_dword v171, v[2:3], off offset:256 nt
	v_lshl_add_u64 v[2:3], s[20:21], 0, v[24:25]
	s_and_b64 s[20:21], s[14:15], exec
	s_cselect_b32 s13, s18, s9
	s_cselect_b32 s20, s19, s28
	s_cmpk_lt_i32 s58, 0xfe
	s_cselect_b32 s21, s11, s20
	s_cselect_b32 s20, s7, s13
	s_or_b32 s56, s8, 20
	s_ashr_i32 s57, s56, 31
	global_load_dword v174, v[2:3], off offset:512 nt
	global_load_dword v172, v[2:3], off offset:768 nt
	v_lshl_add_u64 v[2:3], s[18:19], 0, v[24:25]
	s_lshl_b64 s[18:19], s[56:57], 10
	s_add_u32 s18, s26, s18
	s_addc_u32 s19, s27, s19
	s_add_u32 s7, s18, 0x800
	s_addc_u32 s11, s19, 0
	global_load_dword v169, v[2:3], off nt
	global_load_dword v167, v[2:3], off offset:256 nt
	v_lshl_add_u64 v[2:3], s[20:21], 0, v[24:25]
	s_and_b64 s[20:21], s[14:15], exec
	s_cselect_b32 s13, s18, s16
	s_cselect_b32 s20, s19, s17
	s_cmpk_lt_i32 s56, 0xfe
	s_cselect_b32 s21, s11, s20
	s_cselect_b32 s20, s7, s13
	s_or_b32 s54, s8, 21
	s_ashr_i32 s55, s54, 31
	global_load_dword v170, v[2:3], off offset:512 nt
	global_load_dword v168, v[2:3], off offset:768 nt
	v_lshl_add_u64 v[2:3], s[18:19], 0, v[24:25]
	s_lshl_b64 s[18:19], s[54:55], 10
	s_add_u32 s18, s26, s18
	s_addc_u32 s19, s27, s19
	s_add_u32 s7, s18, 0x800
	s_addc_u32 s11, s19, 0
	global_load_dword v165, v[2:3], off nt
	global_load_dword v163, v[2:3], off offset:256 nt
	v_lshl_add_u64 v[2:3], s[20:21], 0, v[24:25]
	s_and_b64 s[20:21], s[14:15], exec
	s_cselect_b32 s13, s18, s9
	s_cselect_b32 s20, s19, s28
	s_cmpk_lt_i32 s54, 0xfe
	s_cselect_b32 s21, s11, s20
	s_cselect_b32 s20, s7, s13
	s_or_b32 s52, s8, 22
	s_ashr_i32 s53, s52, 31
	global_load_dword v166, v[2:3], off offset:512 nt
	global_load_dword v164, v[2:3], off offset:768 nt
	v_lshl_add_u64 v[2:3], s[18:19], 0, v[24:25]
	s_lshl_b64 s[18:19], s[52:53], 10
	s_add_u32 s18, s26, s18
	s_addc_u32 s19, s27, s19
	s_add_u32 s7, s18, 0x800
	s_addc_u32 s11, s19, 0
	global_load_dword v161, v[2:3], off nt
	global_load_dword v159, v[2:3], off offset:256 nt
	v_lshl_add_u64 v[2:3], s[20:21], 0, v[24:25]
	s_and_b64 s[20:21], s[14:15], exec
	s_cselect_b32 s13, s18, s16
	s_cselect_b32 s20, s19, s17
	s_cmpk_lt_i32 s52, 0xfe
	s_cselect_b32 s21, s11, s20
	s_cselect_b32 s20, s7, s13
	s_or_b32 s50, s8, 23
	s_ashr_i32 s51, s50, 31
	global_load_dword v162, v[2:3], off offset:512 nt
	global_load_dword v160, v[2:3], off offset:768 nt
	v_lshl_add_u64 v[2:3], s[18:19], 0, v[24:25]
	s_lshl_b64 s[18:19], s[50:51], 10
	s_add_u32 s18, s26, s18
	s_addc_u32 s19, s27, s19
	s_add_u32 s7, s18, 0x800
	s_addc_u32 s11, s19, 0
	global_load_dword v157, v[2:3], off nt
	global_load_dword v155, v[2:3], off offset:256 nt
	v_lshl_add_u64 v[2:3], s[20:21], 0, v[24:25]
	s_and_b64 s[20:21], s[14:15], exec
	s_cselect_b32 s13, s18, s9
	s_cselect_b32 s20, s19, s28
	s_cmpk_lt_i32 s50, 0xfe
	s_cselect_b32 s21, s11, s20
	s_cselect_b32 s20, s7, s13
	s_or_b32 s48, s8, 24
	s_ashr_i32 s49, s48, 31
	global_load_dword v158, v[2:3], off offset:512 nt
	global_load_dword v156, v[2:3], off offset:768 nt
	v_lshl_add_u64 v[2:3], s[18:19], 0, v[24:25]
	s_lshl_b64 s[18:19], s[48:49], 10
	s_add_u32 s18, s26, s18
	s_addc_u32 s19, s27, s19
	s_add_u32 s7, s18, 0x800
	s_addc_u32 s11, s19, 0
	global_load_dword v153, v[2:3], off nt
	global_load_dword v151, v[2:3], off offset:256 nt
	v_lshl_add_u64 v[2:3], s[20:21], 0, v[24:25]
	s_and_b64 s[20:21], s[14:15], exec
	s_cselect_b32 s13, s18, s16
	s_cselect_b32 s20, s19, s17
	s_cmpk_lt_i32 s48, 0xfe
	s_cselect_b32 s21, s11, s20
	s_cselect_b32 s20, s7, s13
	s_or_b32 s46, s8, 25
	s_ashr_i32 s47, s46, 31
	global_load_dword v154, v[2:3], off offset:512 nt
	global_load_dword v152, v[2:3], off offset:768 nt
	v_lshl_add_u64 v[2:3], s[18:19], 0, v[24:25]
	s_lshl_b64 s[18:19], s[46:47], 10
	s_add_u32 s18, s26, s18
	s_addc_u32 s19, s27, s19
	s_add_u32 s7, s18, 0x800
	s_addc_u32 s11, s19, 0
	global_load_dword v149, v[2:3], off nt
	global_load_dword v147, v[2:3], off offset:256 nt
	v_lshl_add_u64 v[2:3], s[20:21], 0, v[24:25]
	s_and_b64 s[20:21], s[14:15], exec
	s_cselect_b32 s13, s18, s9
	s_cselect_b32 s20, s19, s28
	s_cmpk_lt_i32 s46, 0xfe
	s_cselect_b32 s21, s11, s20
	s_cselect_b32 s20, s7, s13
	s_or_b32 s44, s8, 26
	s_ashr_i32 s45, s44, 31
	global_load_dword v150, v[2:3], off offset:512 nt
	global_load_dword v148, v[2:3], off offset:768 nt
	v_lshl_add_u64 v[2:3], s[18:19], 0, v[24:25]
	s_lshl_b64 s[18:19], s[44:45], 10
	s_add_u32 s18, s26, s18
	s_addc_u32 s19, s27, s19
	s_add_u32 s7, s18, 0x800
	s_addc_u32 s11, s19, 0
	global_load_dword v145, v[2:3], off nt
	global_load_dword v143, v[2:3], off offset:256 nt
	v_lshl_add_u64 v[2:3], s[20:21], 0, v[24:25]
	s_and_b64 s[20:21], s[14:15], exec
	s_cselect_b32 s13, s18, s16
	s_cselect_b32 s20, s19, s17
	s_cmpk_lt_i32 s44, 0xfe
	s_cselect_b32 s21, s11, s20
	s_cselect_b32 s20, s7, s13
	s_or_b32 s24, s8, 27
	s_ashr_i32 s25, s24, 31
	global_load_dword v146, v[2:3], off offset:512 nt
	global_load_dword v144, v[2:3], off offset:768 nt
	v_lshl_add_u64 v[2:3], s[18:19], 0, v[24:25]
	s_lshl_b64 s[18:19], s[24:25], 10
	s_add_u32 s18, s26, s18
	s_addc_u32 s19, s27, s19
	s_add_u32 s7, s18, 0x800
	s_addc_u32 s11, s19, 0
	global_load_dword v141, v[2:3], off nt
	global_load_dword v139, v[2:3], off offset:256 nt
	v_lshl_add_u64 v[2:3], s[20:21], 0, v[24:25]
	s_and_b64 s[20:21], s[14:15], exec
	s_cselect_b32 s13, s18, s9
	s_cselect_b32 s20, s19, s28
	s_cmpk_lt_i32 s24, 0xfe
	s_cselect_b32 s21, s11, s20
	s_cselect_b32 s20, s7, s13
	s_or_b32 s22, s8, 28
	s_ashr_i32 s23, s22, 31
	global_load_dword v142, v[2:3], off offset:512 nt
	global_load_dword v140, v[2:3], off offset:768 nt
	v_lshl_add_u64 v[2:3], s[18:19], 0, v[24:25]
	s_lshl_b64 s[18:19], s[22:23], 10
	s_add_u32 s18, s26, s18
	s_addc_u32 s19, s27, s19
	s_add_u32 s7, s18, 0x800
	s_addc_u32 s11, s19, 0
	global_load_dword v137, v[2:3], off nt
	global_load_dword v135, v[2:3], off offset:256 nt
	v_lshl_add_u64 v[2:3], s[20:21], 0, v[24:25]
	s_and_b64 s[20:21], s[14:15], exec
	s_cselect_b32 s13, s18, s16
	s_cselect_b32 s20, s19, s17
	s_cmpk_lt_i32 s22, 0xfe
	global_load_dword v138, v[2:3], off offset:512 nt
	global_load_dword v136, v[2:3], off offset:768 nt
	s_cselect_b32 s21, s11, s20
	s_cselect_b32 s20, s7, s13
	v_lshl_add_u64 v[2:3], s[18:19], 0, v[24:25]
	global_load_dword v129, v[2:3], off nt
	global_load_dword v127, v[2:3], off offset:256 nt
	v_lshl_add_u64 v[2:3], s[20:21], 0, v[24:25]
	s_or_b32 s20, s8, 29
	s_ashr_i32 s21, s20, 31
	s_lshl_b64 s[18:19], s[20:21], 10
	s_add_u32 s18, s26, s18
	s_addc_u32 s19, s27, s19
	s_add_u32 s7, s18, 0x800
	s_addc_u32 s11, s19, 0
	s_and_b64 s[30:31], s[14:15], exec
	s_cselect_b32 s13, s18, s9
	s_cselect_b32 s21, s19, s28
	s_cmpk_lt_i32 s20, 0xfe
	global_load_dword v134, v[2:3], off offset:512 nt
	global_load_dword v128, v[2:3], off offset:768 nt
	s_cselect_b32 s31, s11, s21
	s_cselect_b32 s30, s7, s13
	v_lshl_add_u64 v[2:3], s[18:19], 0, v[24:25]
	s_or_b32 s18, s8, 30
	s_ashr_i32 s19, s18, 31
	global_load_dword v125, v[2:3], off nt
	global_load_dword v123, v[2:3], off offset:256 nt
	v_lshl_add_u64 v[2:3], s[30:31], 0, v[24:25]
	s_lshl_b64 s[30:31], s[18:19], 10
	s_add_u32 s30, s26, s30
	s_addc_u32 s31, s27, s31
	s_add_u32 s7, s30, 0x800
	s_addc_u32 s11, s31, 0
	s_and_b64 s[34:35], s[14:15], exec
	s_cselect_b32 s13, s30, s16
	s_cselect_b32 s16, s31, s17
	s_cmpk_lt_i32 s18, 0xfe
	global_load_dword v126, v[2:3], off offset:512 nt
	global_load_dword v124, v[2:3], off offset:768 nt
	s_cselect_b32 s17, s11, s16
	s_cselect_b32 s16, s7, s13
	v_lshl_add_u64 v[2:3], s[30:31], 0, v[24:25]
	global_load_dword v121, v[2:3], off nt
	global_load_dword v119, v[2:3], off offset:256 nt
	v_lshl_add_u64 v[2:3], s[16:17], 0, v[24:25]
	s_or_b32 s16, s8, 31
	s_ashr_i32 s17, s16, 31
	s_lshl_b64 s[30:31], s[16:17], 10
	s_add_u32 s26, s26, s30
	s_addc_u32 s27, s27, s31
	s_add_u32 s7, s26, 0x800
	s_addc_u32 s11, s27, 0
	s_and_b64 s[14:15], s[14:15], exec
	s_cselect_b32 s9, s26, s9
	s_cselect_b32 s13, s27, s28
	s_cmpk_lt_i32 s16, 0xfe
	global_load_dword v122, v[2:3], off offset:512 nt
	global_load_dword v120, v[2:3], off offset:768 nt
	s_cselect_b32 s15, s11, s13
	s_cselect_b32 s14, s7, s9
	v_lshl_add_u64 v[2:3], s[26:27], 0, v[24:25]
	global_load_dword v117, v[2:3], off nt
	global_load_dword v115, v[2:3], off offset:256 nt
	v_lshl_add_u64 v[2:3], s[14:15], 0, v[24:25]
	global_load_dword v118, v[2:3], off offset:512 nt
	global_load_dword v116, v[2:3], off offset:768 nt
	s_movk_i32 s7, 0x2000
	s_mov_b64 s[14:15], 0x800
	v_cmp_gt_i32_e32 vcc, s7, v130
	v_lshl_add_u32 v4, v130, 2, s96
	s_waitcnt vmcnt(0) lgkmcnt(0)
	s_barrier
	s_and_saveexec_b64 s[68:69], vcc
	s_cbranch_execz .LBB0_1715
	s_lshl_b32 s7, s5, 15
	v_mov_b32_e32 v2, s7
	v_mov_b32_e32 v3, v133
	v_ashrrev_i32_e32 v131, 31, v130
	v_add_u32_e32 v5, 0xfffffe00, v130
	v_lshl_add_u64 v[2:3], v[130:131], 2, v[2:3]
	s_mov_b64 s[72:73], 0
	s_movk_i32 s7, 0x1dff
	v_mov_b32_e32 v6, v4
.LBB0_1714:
	v_mov_b64_e32 v[8:9], s[0:1]
	global_load_dwordx2 v[8:9], v[8:9], off offset:144 sc0 sc1
	s_waitcnt vmcnt(0)
	v_add_u32_e32 v5, 0x200, v5
	v_cmp_lt_i32_e32 vcc, s7, v5
	s_or_b64 s[72:73], vcc, s[72:73]
	s_waitcnt lgkmcnt(0)
	v_lshl_add_u64 v[8:9], v[8:9], 0, v[2:3]
	global_load_dword v7, v[8:9], off nt
	v_lshl_add_u64 v[2:3], v[2:3], 0, s[14:15]
	s_waitcnt vmcnt(0)
	ds_write_b32 v6, v7
	v_add_u32_e32 v6, 0x800, v6
	s_andn2_b64 exec, exec, s[72:73]
	s_cbranch_execnz .LBB0_1714
.LBB0_1715:
	s_or_b64 exec, exec, s[68:69]
	s_movk_i32 s7, 0x7f
	v_cmp_lt_i32_e32 vcc, s7, v130
	s_and_saveexec_b64 s[14:15], vcc
	s_xor_b64 s[14:15], exec, s[14:15]
	s_lshl_b32 s7, s5, 7
	s_or_saveexec_b64 s[14:15], s[14:15]
	v_mov_b32_e32 v58, s7
	s_xor_b64 exec, exec, s[14:15]
	s_cbranch_execz .LBB0_1721
	v_mov_b64_e32 v[2:3], s[0:1]
	global_load_dwordx2 v[6:7], v[2:3], off offset:136 sc0 sc1
	s_waitcnt vmcnt(0)
	s_lshl_b32 s7, s5, 7
	v_add_u32_e32 v2, s7, v130
	v_ashrrev_i32_e32 v3, 31, v2
	s_add_u32 s68, s38, 0x6200000
	s_addc_u32 s69, s39, 0
	s_mov_b32 s9, 0
	s_waitcnt lgkmcnt(0)
	v_lshl_add_u64 v[6:7], v[2:3], 2, v[6:7]
	global_load_dword v3, v[6:7], off nt
.LBB0_1719:
	v_add_u32_e32 v6, s9, v2
	v_add_u32_e32 v8, 0x200, v6
	v_add_u32_e32 v10, 0x400, v6
	v_add_u32_e32 v12, 0x600, v6
	v_ashrrev_i32_e32 v7, 31, v6
	v_add_u32_e32 v14, 0x800, v6
	v_add_u32_e32 v16, 0xa00, v6
	v_add_u32_e32 v18, 0xc00, v6
	v_add_u32_e32 v26, 0xe00, v6
	v_ashrrev_i32_e32 v9, 31, v8
	v_ashrrev_i32_e32 v11, 31, v10
	v_ashrrev_i32_e32 v13, 31, v12
	v_lshl_add_u64 v[6:7], v[6:7], 2, s[68:69]
	v_ashrrev_i32_e32 v15, 31, v14
	v_ashrrev_i32_e32 v17, 31, v16
	v_ashrrev_i32_e32 v19, 31, v18
	v_ashrrev_i32_e32 v27, 31, v26
	v_lshl_add_u64 v[8:9], v[8:9], 2, s[68:69]
	v_lshl_add_u64 v[10:11], v[10:11], 2, s[68:69]
	v_lshl_add_u64 v[12:13], v[12:13], 2, s[68:69]
	v_lshl_add_u64 v[14:15], v[14:15], 2, s[68:69]
	v_lshl_add_u64 v[16:17], v[16:17], 2, s[68:69]
	v_lshl_add_u64 v[18:19], v[18:19], 2, s[68:69]
	v_lshl_add_u64 v[26:27], v[26:27], 2, s[68:69]
	global_load_dword v5, v[6:7], off nt
	s_nop 0
	global_load_dword v6, v[8:9], off nt
	global_load_dword v7, v[10:11], off nt
	s_nop 0
	global_load_dword v8, v[12:13], off nt
	global_load_dword v9, v[14:15], off nt
	global_load_dword v10, v[16:17], off nt
	global_load_dword v11, v[18:19], off nt
	s_nop 0
	global_load_dword v12, v[26:27], off nt
	s_addk_i32 s9, 0x1000
	s_cmpk_eq_i32 s9, 0x4000
	s_waitcnt vmcnt(0) lgkmcnt(0)
	v_add_f32_e32 v3, v3, v5
	v_add_f32_e32 v3, v3, v6
	v_add_f32_e32 v3, v3, v7
	v_add_f32_e32 v3, v3, v8
	v_add_f32_e32 v3, v3, v9
	v_add_f32_e32 v3, v3, v10
	v_add_f32_e32 v3, v3, v11
	v_add_f32_e32 v3, v3, v12
	s_cbranch_scc0 .LBB0_1719
	v_mov_b32_e32 v58, s7
	ds_write_b32 v4, v3 offset:32768

.LBB0_2041:
	s_bfe_u32 s6, s40, 0x30001
	s_cmp_eq_u32 s6, s3
	s_cselect_b64 s[12:13], -1, 0
	s_cmp_lg_u32 s6, s3
	s_cbranch_scc1 .LBB0_2043
	s_ashr_i32 s6, s40, 4
	s_lshr_b32 s3, s40, 1
	s_and_b32 s7, s6, -2
	s_or_b32 s5, s7, s5
	s_lshl_b32 s3, s3, 4
	s_add_i32 s6, s5, 0x100
	s_and_b32 s8, s3, 0xf0
	s_cmpk_gt_i32 s7, 0xff0e
	s_cselect_b64 s[14:15], -1, 0
	s_and_b32 s3, s40, 0x60
	s_cmpk_eq_i32 s3, 0x60
	s_cselect_b64 s[16:17], -1, 0
	s_ashr_i32 s7, s6, 31
	s_or_b64 s[14:15], s[16:17], s[14:15]
	s_lshl_b64 s[16:17], s[6:7], 18
	s_add_u32 s2, s2, s16
	s_addc_u32 s3, s4, s17
	s_add_u32 s7, s2, 0x80000
	s_addc_u32 s18, s3, 0
	s_lshl_b32 s4, s8, 10
	s_add_u32 s16, s2, s4
	s_addc_u32 s17, s3, 0
	s_add_u32 s4, s2, 0x80400
	s_addc_u32 s5, s3, 0
	s_add_u32 s20, s16, 0x1000
	s_addc_u32 s21, s17, 0
	s_add_u32 s22, s16, 0x1400
	s_addc_u32 s23, s17, 0
	v_add_u32_e32 v2, 64, v132
	v_mov_b32_e32 v3, 0
	s_add_u32 s24, s16, 0x1800
	v_lshl_add_u64 v[4:5], s[16:17], 0, v[24:25]
	v_lshl_add_u64 v[6:7], s[20:21], 0, v[24:25]
	s_addc_u32 s25, s17, 0
	v_lshlrev_b64 v[2:3], 2, v[2:3]
	global_load_dword v20, v[4:5], off nt
	global_load_dword v21, v[4:5], off offset:256 nt
	global_load_dword v22, v[4:5], off offset:2560
	global_load_dword v23, v[4:5], off offset:2816
	global_load_dword v107, v[4:5], off offset:1024
	global_load_dword v105, v[4:5], off offset:1280
	global_load_dword v103, v[4:5], off offset:2048
	global_load_dword v100, v[4:5], off offset:2304
	v_lshl_add_u64 v[8:9], s[22:23], 0, v[24:25]
	global_load_dword v108, v[4:5], off offset:3584
	global_load_dword v106, v[4:5], off offset:3840
	global_load_dword v104, v[6:7], off offset:512 nt
	global_load_dword v102, v[6:7], off offset:768 nt
	global_load_dword v98, v[4:5], off offset:3072
	global_load_dword v90, v[8:9], off nt
	global_load_dword v94, v[6:7], off nt
	global_load_dword v97, v[4:5], off offset:3328
	v_lshl_add_u64 v[6:7], s[20:21], 0, v[2:3]
	s_add_u32 s20, s16, 0x1c00
	s_addc_u32 s21, s17, 0
	v_lshl_add_u64 v[12:13], s[22:23], 0, v[2:3]
	s_add_u32 s22, s16, 0x2000
	s_addc_u32 s23, s17, 0
	v_lshl_add_u64 v[10:11], s[24:25], 0, v[24:25]
	v_lshl_add_u64 v[14:15], s[20:21], 0, v[24:25]
	global_load_dword v101, v[8:9], off offset:512 nt
	global_load_dword v99, v[8:9], off offset:768 nt
	global_load_dword v93, v[6:7], off nt
	global_load_dword v96, v[10:11], off offset:512 nt
	global_load_dword v95, v[10:11], off offset:768 nt
	global_load_dword v89, v[12:13], off nt
	global_load_dword v82, v[14:15], off nt
	global_load_dword v87, v[10:11], off nt
	v_lshl_add_u64 v[6:7], s[24:25], 0, v[2:3]
	s_add_u32 s24, s16, 0x2400
	s_addc_u32 s25, s17, 0
	v_lshl_add_u64 v[10:11], s[20:21], 0, v[2:3]
	s_add_u32 s20, s16, 0x2800
	s_addc_u32 s21, s17, 0
	v_lshl_add_u64 v[8:9], s[22:23], 0, v[24:25]
	v_lshl_add_u64 v[12:13], s[24:25], 0, v[24:25]
	global_load_dword v92, v[14:15], off offset:512 nt
	global_load_dword v91, v[14:15], off offset:768 nt
	global_load_dword v85, v[6:7], off nt
	global_load_dword v88, v[8:9], off offset:512 nt
	global_load_dword v86, v[8:9], off offset:768 nt
	global_load_dword v81, v[10:11], off nt
	global_load_dword v73, v[12:13], off nt
	global_load_dword v79, v[8:9], off nt
	v_lshl_add_u64 v[6:7], s[22:23], 0, v[2:3]
	s_add_u32 s22, s16, 0x2c00
	s_addc_u32 s23, s17, 0
	v_lshl_add_u64 v[10:11], s[24:25], 0, v[2:3]
	s_add_u32 s24, s16, 0x3000
	s_addc_u32 s25, s17, 0
	v_lshl_add_u64 v[8:9], s[20:21], 0, v[24:25]
	v_lshl_add_u64 v[14:15], s[22:23], 0, v[24:25]
	global_load_dword v84, v[12:13], off offset:512 nt
	global_load_dword v83, v[12:13], off offset:768 nt
	global_load_dword v77, v[6:7], off nt
	global_load_dword v80, v[8:9], off offset:512 nt
	global_load_dword v78, v[8:9], off offset:768 nt
	global_load_dword v72, v[10:11], off nt
	global_load_dword v65, v[14:15], off nt
	global_load_dword v70, v[8:9], off nt
	v_lshl_add_u64 v[6:7], s[20:21], 0, v[2:3]
	s_add_u32 s20, s16, 0x3400
	s_addc_u32 s21, s17, 0
	v_lshl_add_u64 v[10:11], s[22:23], 0, v[2:3]
	s_add_u32 s22, s16, 0x3800
	s_addc_u32 s23, s17, 0
	v_lshl_add_u64 v[8:9], s[24:25], 0, v[24:25]
	v_lshl_add_u64 v[12:13], s[20:21], 0, v[24:25]
	global_load_dword v76, v[14:15], off offset:512 nt
	global_load_dword v74, v[14:15], off offset:768 nt
	global_load_dword v68, v[6:7], off nt
	global_load_dword v71, v[8:9], off offset:512 nt
	global_load_dword v69, v[8:9], off offset:768 nt
	global_load_dword v64, v[10:11], off nt
	global_load_dword v56, v[12:13], off nt
	global_load_dword v62, v[8:9], off nt
	v_lshl_add_u64 v[10:11], s[20:21], 0, v[2:3]
	s_mov_b64 s[20:21], 0x3c00
	s_add_u32 s19, s16, 0x4000
	v_lshl_add_u64 v[14:15], v[4:5], 0, s[20:21]
	s_addc_u32 s20, s17, 0
	s_and_b64 s[16:17], s[14:15], exec
	s_cselect_b32 s7, s22, s7
	s_cselect_b32 s16, s23, s18
	s_cmpk_eq_i32 s8, 0xf0
	v_lshl_add_u64 v[6:7], s[24:25], 0, v[2:3]
	s_cselect_b32 s17, s16, s20
	s_cselect_b32 s16, s7, s19
	v_lshl_add_u64 v[2:3], s[22:23], 0, v[2:3]
	s_or_b32 s7, s8, 15
	v_lshl_add_u64 v[8:9], s[22:23], 0, v[24:25]
	global_load_dword v67, v[12:13], off offset:512 nt
	global_load_dword v66, v[12:13], off offset:768 nt
	global_load_dword v60, v[6:7], off nt
	global_load_dword v63, v[8:9], off offset:512 nt
	global_load_dword v61, v[8:9], off offset:768 nt
	global_load_dword v55, v[10:11], off nt
	global_load_dword v59, v[14:15], off offset:512 nt
	global_load_dword v53, v[8:9], off nt
	global_load_dword v57, v[14:15], off offset:768 nt
	global_load_dword v51, v[2:3], off nt
	v_lshl_add_u64 v[2:3], s[16:17], 0, v[24:25]
	s_lshl_b32 s16, s7, 10
	s_add_u32 s2, s2, s16
	s_addc_u32 s3, s3, 0
	s_add_u32 s16, s2, 0x800
	s_addc_u32 s17, s3, 0
	s_and_b64 s[14:15], s[14:15], exec
	global_load_dword v54, v[2:3], off offset:512 nt
	global_load_dword v52, v[2:3], off offset:768 nt
	s_cselect_b32 s4, s2, s4
	s_cselect_b32 s5, s3, s5
	s_cmpk_lt_u32 s7, 0xfe
	v_add_co_u32_e32 v2, vcc, 0x3000, v4
	s_cselect_b32 s5, s17, s5
	s_cselect_b32 s4, s16, s4
	v_addc_co_u32_e32 v3, vcc, 0, v5, vcc
	v_lshl_add_u64 v[4:5], s[2:3], 0, v[24:25]
	global_load_dword v49, v[2:3], off offset:3072
	global_load_dword v1, v[4:5], off offset:256 nt
	v_lshl_add_u64 v[2:3], s[4:5], 0, v[24:25]
	global_load_dword v50, v[2:3], off offset:512 nt
	global_load_dword v48, v[2:3], off offset:768 nt
	s_andn2_b64 vcc, exec, s[12:13]
	s_cbranch_vccz .LBB0_2044
	s_branch .LBB0_2204

.LBB0_4318:
	s_cmp_lt_i32 s90, 22
	s_cselect_b64 s[2:3], -1, 0
	s_cmp_gt_i32 s91, 21
	s_cselect_b64 s[4:5], -1, 0
	s_and_b64 s[2:3], s[2:3], s[4:5]
	s_andn2_b64 vcc, exec, s[2:3]
	s_cbranch_vccnz .LBB0_4865
	s_add_u32 s2, s38, 0x31600000
	s_addc_u32 s3, s39, 0
	s_cmp_gt_i32 s40, 15
	s_cselect_b64 s[4:5], -1, 0
	s_and_b32 s6, s40, 6
	s_cmp_eq_u32 s6, 6
	s_cselect_b64 s[6:7], -1, 0
	s_ashr_i32 s41, s40, 31
	s_or_b64 s[14:15], s[4:5], s[6:7]
	s_lshl_b32 s8, s96, 5
	s_lshl_b64 s[4:5], s[40:41], 18
	s_add_u32 s4, s2, s4
	s_addc_u32 s5, s3, s5
	s_add_u32 s16, s4, 0x80000
	s_addc_u32 s17, s5, 0
	s_ashr_i32 s9, s8, 31
	s_lshl_b64 s[6:7], s[8:9], 10
	s_add_u32 s6, s4, s6
	s_addc_u32 s7, s5, s7
	s_add_u32 s9, s6, 0x800
	s_addc_u32 s12, s7, 0
	v_mov_b32_e32 v133, 0
	s_and_b64 s[10:11], s[14:15], exec
	s_cselect_b32 s10, s6, s16
	s_cselect_b32 s11, s7, s17
	s_cmp_lt_i32 s96, 8
	v_lshlrev_b64 v[24:25], 2, v[132:133]
	s_cselect_b32 s11, s12, s11
	s_cselect_b32 s10, s9, s10
	v_lshl_add_u64 v[2:3], s[6:7], 0, v[24:25]
	s_or_b32 s6, s8, 1
	s_ashr_i32 s7, s6, 31
	global_load_dword v20, v[2:3], off nt
	global_load_dword v21, v[2:3], off offset:256 nt
	v_lshl_add_u64 v[2:3], s[10:11], 0, v[24:25]
	s_lshl_b64 s[10:11], s[6:7], 10
	s_add_u32 s10, s4, s10
	s_addc_u32 s11, s5, s11
	s_add_u32 s18, s10, 0x800
	s_addc_u32 s7, s11, 0
	s_add_u32 s9, s4, 0x80400
	s_addc_u32 s26, s5, 0
	s_and_b64 s[12:13], s[14:15], exec
	s_cselect_b32 s12, s10, s9
	s_cselect_b32 s13, s11, s26
	s_cmpk_lt_i32 s6, 0xfe
	s_cselect_b32 s7, s7, s13
	s_cselect_b32 s6, s18, s12
	s_or_b32 s88, s8, 2
	global_load_dword v22, v[2:3], off offset:512 nt
	global_load_dword v23, v[2:3], off offset:768 nt
	v_lshl_add_u64 v[2:3], s[10:11], 0, v[24:25]
	s_ashr_i32 s89, s88, 31
	global_load_dword v107, v[2:3], off nt
	global_load_dword v105, v[2:3], off offset:256 nt
	v_lshl_add_u64 v[2:3], s[6:7], 0, v[24:25]
	s_lshl_b64 s[6:7], s[88:89], 10
	s_add_u32 s6, s4, s6
	s_addc_u32 s7, s5, s7
	s_add_u32 s12, s6, 0x800
	s_addc_u32 s13, s7, 0
	s_and_b64 s[10:11], s[14:15], exec
	s_cselect_b32 s10, s6, s16
	s_cselect_b32 s11, s7, s17
	s_cmpk_lt_i32 s88, 0xfe
	s_cselect_b32 s11, s13, s11
	s_cselect_b32 s10, s12, s10
	s_or_b32 s86, s8, 3
	s_ashr_i32 s87, s86, 31
	global_load_dword v108, v[2:3], off offset:512 nt
	global_load_dword v106, v[2:3], off offset:768 nt
	v_lshl_add_u64 v[2:3], s[6:7], 0, v[24:25]
	s_lshl_b64 s[6:7], s[86:87], 10
	s_add_u32 s6, s4, s6
	s_addc_u32 s7, s5, s7
	s_add_u32 s12, s6, 0x800
	s_addc_u32 s13, s7, 0
	global_load_dword v103, v[2:3], off nt
	global_load_dword v100, v[2:3], off offset:256 nt
	v_lshl_add_u64 v[2:3], s[10:11], 0, v[24:25]
	s_and_b64 s[10:11], s[14:15], exec
	s_cselect_b32 s10, s6, s9
	s_cselect_b32 s11, s7, s26
	s_cmpk_lt_i32 s86, 0xfe
	s_cselect_b32 s11, s13, s11
	s_cselect_b32 s10, s12, s10
	s_or_b32 s84, s8, 4
	s_ashr_i32 s85, s84, 31
	global_load_dword v104, v[2:3], off offset:512 nt
	global_load_dword v102, v[2:3], off offset:768 nt
	v_lshl_add_u64 v[2:3], s[6:7], 0, v[24:25]
	s_lshl_b64 s[6:7], s[84:85], 10
	s_add_u32 s6, s4, s6
	s_addc_u32 s7, s5, s7
	s_add_u32 s12, s6, 0x800
	s_addc_u32 s13, s7, 0
	global_load_dword v98, v[2:3], off nt
	global_load_dword v97, v[2:3], off offset:256 nt
	v_lshl_add_u64 v[2:3], s[10:11], 0, v[24:25]
	s_and_b64 s[10:11], s[14:15], exec
	s_cselect_b32 s10, s6, s16
	s_cselect_b32 s11, s7, s17
	s_cmpk_lt_i32 s84, 0xfe
	s_cselect_b32 s11, s13, s11
	s_cselect_b32 s10, s12, s10
	s_or_b32 s82, s8, 5
	s_ashr_i32 s83, s82, 31
	global_load_dword v101, v[2:3], off offset:512 nt
	global_load_dword v99, v[2:3], off offset:768 nt
	v_lshl_add_u64 v[2:3], s[6:7], 0, v[24:25]
	s_lshl_b64 s[6:7], s[82:83], 10
	s_add_u32 s6, s4, s6
	s_addc_u32 s7, s5, s7
	s_add_u32 s12, s6, 0x800
	s_addc_u32 s13, s7, 0
	global_load_dword v94, v[2:3], off nt
	global_load_dword v93, v[2:3], off offset:256 nt
	v_lshl_add_u64 v[2:3], s[10:11], 0, v[24:25]
	s_and_b64 s[10:11], s[14:15], exec
	s_cselect_b32 s10, s6, s9
	s_cselect_b32 s11, s7, s26
	s_cmpk_lt_i32 s82, 0xfe
	s_cselect_b32 s11, s13, s11
	s_cselect_b32 s10, s12, s10
	s_or_b32 s80, s8, 6
	s_ashr_i32 s81, s80, 31
	global_load_dword v96, v[2:3], off offset:512 nt
	global_load_dword v95, v[2:3], off offset:768 nt
	v_lshl_add_u64 v[2:3], s[6:7], 0, v[24:25]
	s_lshl_b64 s[6:7], s[80:81], 10
	s_add_u32 s6, s4, s6
	s_addc_u32 s7, s5, s7
	s_add_u32 s12, s6, 0x800
	s_addc_u32 s13, s7, 0
	global_load_dword v90, v[2:3], off nt
	global_load_dword v89, v[2:3], off offset:256 nt
	v_lshl_add_u64 v[2:3], s[10:11], 0, v[24:25]
	s_and_b64 s[10:11], s[14:15], exec
	s_cselect_b32 s10, s6, s16
	s_cselect_b32 s11, s7, s17
	s_cmpk_lt_i32 s80, 0xfe
	s_cselect_b32 s11, s13, s11
	s_cselect_b32 s10, s12, s10
	s_or_b32 s78, s8, 7
	s_ashr_i32 s79, s78, 31
	global_load_dword v92, v[2:3], off offset:512 nt
	global_load_dword v91, v[2:3], off offset:768 nt
	v_lshl_add_u64 v[2:3], s[6:7], 0, v[24:25]
	s_lshl_b64 s[6:7], s[78:79], 10
	s_add_u32 s6, s4, s6
	s_addc_u32 s7, s5, s7
	s_add_u32 s12, s6, 0x800
	s_addc_u32 s13, s7, 0
	global_load_dword v87, v[2:3], off nt
	global_load_dword v85, v[2:3], off offset:256 nt
	v_lshl_add_u64 v[2:3], s[10:11], 0, v[24:25]
	s_and_b64 s[10:11], s[14:15], exec
	s_cselect_b32 s10, s6, s9
	s_cselect_b32 s11, s7, s26
	s_cmpk_lt_i32 s78, 0xfe
	s_cselect_b32 s11, s13, s11
	s_cselect_b32 s10, s12, s10
	s_or_b32 s76, s8, 8
	s_ashr_i32 s77, s76, 31
	global_load_dword v88, v[2:3], off offset:512 nt
	global_load_dword v86, v[2:3], off offset:768 nt
	v_lshl_add_u64 v[2:3], s[6:7], 0, v[24:25]
	s_lshl_b64 s[6:7], s[76:77], 10
	s_add_u32 s6, s4, s6
	s_addc_u32 s7, s5, s7
	s_add_u32 s12, s6, 0x800
	s_addc_u32 s13, s7, 0
	global_load_dword v82, v[2:3], off nt
	global_load_dword v81, v[2:3], off offset:256 nt
	v_lshl_add_u64 v[2:3], s[10:11], 0, v[24:25]
	s_and_b64 s[10:11], s[14:15], exec
	s_cselect_b32 s10, s6, s16
	s_cselect_b32 s11, s7, s17
	s_cmpk_lt_i32 s76, 0xfe
	s_cselect_b32 s11, s13, s11
	s_cselect_b32 s10, s12, s10
	s_or_b32 s74, s8, 9
	s_ashr_i32 s75, s74, 31
	global_load_dword v84, v[2:3], off offset:512 nt
	global_load_dword v83, v[2:3], off offset:768 nt
	v_lshl_add_u64 v[2:3], s[6:7], 0, v[24:25]
	s_lshl_b64 s[6:7], s[74:75], 10
	s_add_u32 s6, s4, s6
	s_addc_u32 s7, s5, s7
	s_add_u32 s12, s6, 0x800
	s_addc_u32 s13, s7, 0
	global_load_dword v79, v[2:3], off nt
	global_load_dword v77, v[2:3], off offset:256 nt
	v_lshl_add_u64 v[2:3], s[10:11], 0, v[24:25]
	s_and_b64 s[10:11], s[14:15], exec
	s_cselect_b32 s10, s6, s9
	s_cselect_b32 s11, s7, s26
	s_cmpk_lt_i32 s74, 0xfe
	s_cselect_b32 s11, s13, s11
	s_cselect_b32 s10, s12, s10
	s_or_b32 s70, s8, 10
	s_ashr_i32 s71, s70, 31
	global_load_dword v80, v[2:3], off offset:512 nt
	global_load_dword v78, v[2:3], off offset:768 nt
	v_lshl_add_u64 v[2:3], s[6:7], 0, v[24:25]
	s_lshl_b64 s[6:7], s[70:71], 10
	s_add_u32 s6, s4, s6
	s_addc_u32 s7, s5, s7
	s_add_u32 s12, s6, 0x800
	s_addc_u32 s13, s7, 0
	global_load_dword v73, v[2:3], off nt
	global_load_dword v72, v[2:3], off offset:256 nt
	v_lshl_add_u64 v[2:3], s[10:11], 0, v[24:25]
	s_and_b64 s[10:11], s[14:15], exec
	s_cselect_b32 s10, s6, s16
	s_cselect_b32 s11, s7, s17
	s_cmpk_lt_i32 s70, 0xfe
	s_cselect_b32 s11, s13, s11
	s_cselect_b32 s10, s12, s10
	s_or_b32 s68, s8, 11
	s_ashr_i32 s69, s68, 31
	global_load_dword v75, v[2:3], off offset:512 nt
	global_load_dword v74, v[2:3], off offset:768 nt
	v_lshl_add_u64 v[2:3], s[6:7], 0, v[24:25]
	s_lshl_b64 s[6:7], s[68:69], 10
	s_add_u32 s6, s4, s6
	s_addc_u32 s7, s5, s7
	s_add_u32 s12, s6, 0x800
	s_addc_u32 s13, s7, 0
	global_load_dword v70, v[2:3], off nt
	global_load_dword v68, v[2:3], off offset:256 nt
	v_lshl_add_u64 v[2:3], s[10:11], 0, v[24:25]
	s_and_b64 s[10:11], s[14:15], exec
	s_cselect_b32 s10, s6, s9
	s_cselect_b32 s11, s7, s26
	s_cmpk_lt_i32 s68, 0xfe
	s_cselect_b32 s11, s13, s11
	s_cselect_b32 s10, s12, s10
	s_or_b32 s66, s8, 12
	s_ashr_i32 s67, s66, 31
	global_load_dword v71, v[2:3], off offset:512 nt
	global_load_dword v69, v[2:3], off offset:768 nt
	v_lshl_add_u64 v[2:3], s[6:7], 0, v[24:25]
	s_lshl_b64 s[6:7], s[66:67], 10
	s_add_u32 s6, s4, s6
	s_addc_u32 s7, s5, s7
	s_add_u32 s12, s6, 0x800
	s_addc_u32 s13, s7, 0
	global_load_dword v65, v[2:3], off nt
	global_load_dword v64, v[2:3], off offset:256 nt
	v_lshl_add_u64 v[2:3], s[10:11], 0, v[24:25]
	s_and_b64 s[10:11], s[14:15], exec
	s_cselect_b32 s10, s6, s16
	s_cselect_b32 s11, s7, s17
	s_cmpk_lt_i32 s66, 0xfe
	s_cselect_b32 s11, s13, s11
	s_cselect_b32 s10, s12, s10
	s_or_b32 s64, s8, 13
	s_ashr_i32 s65, s64, 31
	global_load_dword v67, v[2:3], off offset:512 nt
	global_load_dword v66, v[2:3], off offset:768 nt
	v_lshl_add_u64 v[2:3], s[6:7], 0, v[24:25]
	s_lshl_b64 s[6:7], s[64:65], 10
	s_add_u32 s6, s4, s6
	s_addc_u32 s7, s5, s7
	s_add_u32 s12, s6, 0x800
	s_addc_u32 s13, s7, 0
	global_load_dword v62, v[2:3], off nt
	global_load_dword v60, v[2:3], off offset:256 nt
	v_lshl_add_u64 v[2:3], s[10:11], 0, v[24:25]
	s_and_b64 s[10:11], s[14:15], exec
	s_cselect_b32 s10, s6, s9
	s_cselect_b32 s11, s7, s26
	s_cmpk_lt_i32 s64, 0xfe
	global_load_dword v63, v[2:3], off offset:512 nt
	global_load_dword v61, v[2:3], off offset:768 nt
	s_cselect_b32 s11, s13, s11
	s_cselect_b32 s10, s12, s10
	v_lshl_add_u64 v[2:3], s[6:7], 0, v[24:25]
	global_load_dword v56, v[2:3], off nt
	global_load_dword v55, v[2:3], off offset:256 nt
	v_lshl_add_u64 v[2:3], s[10:11], 0, v[24:25]
	s_or_b32 s10, s8, 14
	s_ashr_i32 s11, s10, 31
	s_lshl_b64 s[6:7], s[10:11], 10
	s_add_u32 s6, s4, s6
	s_addc_u32 s7, s5, s7
	s_add_u32 s11, s6, 0x800
	s_addc_u32 s18, s7, 0
	s_and_b64 s[12:13], s[14:15], exec
	s_cselect_b32 s12, s6, s16
	s_cselect_b32 s13, s7, s17
	s_cmpk_lt_i32 s10, 0xfe
	global_load_dword v58, v[2:3], off offset:512 nt
	global_load_dword v57, v[2:3], off offset:768 nt
	s_cselect_b32 s13, s18, s13
	s_cselect_b32 s12, s11, s12
	v_lshl_add_u64 v[2:3], s[6:7], 0, v[24:25]
	s_or_b32 s6, s8, 15
	s_ashr_i32 s7, s6, 31
	global_load_dword v53, v[2:3], off nt
	global_load_dword v51, v[2:3], off offset:256 nt
	v_lshl_add_u64 v[2:3], s[12:13], 0, v[24:25]
	s_lshl_b64 s[12:13], s[6:7], 10
	s_add_u32 s12, s4, s12
	s_addc_u32 s13, s5, s13
	s_add_u32 s7, s12, 0x800
	s_addc_u32 s11, s13, 0
	s_and_b64 s[18:19], s[14:15], exec
	s_cselect_b32 s18, s12, s9
	s_cselect_b32 s19, s13, s26
	s_cmpk_lt_i32 s6, 0xfe
	global_load_dword v54, v[2:3], off offset:512 nt
	global_load_dword v52, v[2:3], off offset:768 nt
	s_cselect_b32 s19, s11, s19
	s_cselect_b32 s18, s7, s18
	v_lshl_add_u64 v[2:3], s[12:13], 0, v[24:25]
	s_or_b32 s12, s8, 16
	s_ashr_i32 s13, s12, 31
	global_load_dword v49, v[2:3], off nt
	global_load_dword v1, v[2:3], off offset:256 nt
	v_lshl_add_u64 v[2:3], s[18:19], 0, v[24:25]
	s_lshl_b64 s[18:19], s[12:13], 10
	s_add_u32 s18, s4, s18
	s_addc_u32 s19, s5, s19
	s_add_u32 s7, s18, 0x800
	s_addc_u32 s11, s19, 0
	s_and_b64 s[20:21], s[14:15], exec
	s_cselect_b32 s13, s18, s16
	s_cselect_b32 s20, s19, s17
	s_cmpk_lt_i32 s12, 0xfe
	s_cselect_b32 s21, s11, s20
	s_cselect_b32 s20, s7, s13
	s_or_b32 s62, s8, 17
	s_ashr_i32 s63, s62, 31
	global_load_dword v50, v[2:3], off offset:512 nt
	global_load_dword v48, v[2:3], off offset:768 nt
	v_lshl_add_u64 v[2:3], s[18:19], 0, v[24:25]
	s_lshl_b64 s[18:19], s[62:63], 10
	s_add_u32 s18, s4, s18
	s_addc_u32 s19, s5, s19
	s_add_u32 s7, s18, 0x800
	s_addc_u32 s11, s19, 0
	global_load_dword v38, v[2:3], off nt
	global_load_dword v39, v[2:3], off offset:256 nt
	v_lshl_add_u64 v[2:3], s[20:21], 0, v[24:25]
	s_and_b64 s[20:21], s[14:15], exec
	s_cselect_b32 s13, s18, s9
	s_cselect_b32 s20, s19, s26
	s_cmpk_lt_i32 s62, 0xfe
	s_cselect_b32 s21, s11, s20
	s_cselect_b32 s20, s7, s13
	s_or_b32 s60, s8, 18
	s_ashr_i32 s61, s60, 31
	global_load_dword v36, v[2:3], off offset:512 nt
	global_load_dword v37, v[2:3], off offset:768 nt
	v_lshl_add_u64 v[2:3], s[18:19], 0, v[24:25]
	s_lshl_b64 s[18:19], s[60:61], 10
	s_add_u32 s18, s4, s18
	s_addc_u32 s19, s5, s19
	s_add_u32 s7, s18, 0x800
	s_addc_u32 s11, s19, 0
	global_load_dword v177, v[2:3], off nt
	global_load_dword v175, v[2:3], off offset:256 nt
	v_lshl_add_u64 v[2:3], s[20:21], 0, v[24:25]
	s_and_b64 s[20:21], s[14:15], exec
	s_cselect_b32 s13, s18, s16
	s_cselect_b32 s20, s19, s17
	s_cmpk_lt_i32 s60, 0xfe
	s_cselect_b32 s21, s11, s20
	s_cselect_b32 s20, s7, s13
	s_or_b32 s58, s8, 19
	s_ashr_i32 s59, s58, 31
	global_load_dword v178, v[2:3], off offset:512 nt
	global_load_dword v176, v[2:3], off offset:768 nt
	v_lshl_add_u64 v[2:3], s[18:19], 0, v[24:25]
	s_lshl_b64 s[18:19], s[58:59], 10
	s_add_u32 s18, s4, s18
	s_addc_u32 s19, s5, s19
	s_add_u32 s7, s18, 0x800
	s_addc_u32 s11, s19, 0
	global_load_dword v173, v[2:3], off nt
	global_load_dword v171, v[2:3], off offset:256 nt
	v_lshl_add_u64 v[2:3], s[20:21], 0, v[24:25]
	s_and_b64 s[20:21], s[14:15], exec
	s_cselect_b32 s13, s18, s9
	s_cselect_b32 s20, s19, s26
	s_cmpk_lt_i32 s58, 0xfe
	s_cselect_b32 s21, s11, s20
	s_cselect_b32 s20, s7, s13
	s_or_b32 s56, s8, 20
	s_ashr_i32 s57, s56, 31
	global_load_dword v174, v[2:3], off offset:512 nt
	global_load_dword v172, v[2:3], off offset:768 nt
	v_lshl_add_u64 v[2:3], s[18:19], 0, v[24:25]
	s_lshl_b64 s[18:19], s[56:57], 10
	s_add_u32 s18, s4, s18
	s_addc_u32 s19, s5, s19
	s_add_u32 s7, s18, 0x800
	s_addc_u32 s11, s19, 0
	global_load_dword v169, v[2:3], off nt
	global_load_dword v167, v[2:3], off offset:256 nt
	v_lshl_add_u64 v[2:3], s[20:21], 0, v[24:25]
	s_and_b64 s[20:21], s[14:15], exec
	s_cselect_b32 s13, s18, s16
	s_cselect_b32 s20, s19, s17
	s_cmpk_lt_i32 s56, 0xfe
	s_cselect_b32 s21, s11, s20
	s_cselect_b32 s20, s7, s13
	s_or_b32 s54, s8, 21
	s_ashr_i32 s55, s54, 31
	global_load_dword v170, v[2:3], off offset:512 nt
	global_load_dword v168, v[2:3], off offset:768 nt
	v_lshl_add_u64 v[2:3], s[18:19], 0, v[24:25]
	s_lshl_b64 s[18:19], s[54:55], 10
	s_add_u32 s18, s4, s18
	s_addc_u32 s19, s5, s19
	s_add_u32 s7, s18, 0x800
	s_addc_u32 s11, s19, 0
	global_load_dword v165, v[2:3], off nt
	global_load_dword v163, v[2:3], off offset:256 nt
	v_lshl_add_u64 v[2:3], s[20:21], 0, v[24:25]
	s_and_b64 s[20:21], s[14:15], exec
	s_cselect_b32 s13, s18, s9
	s_cselect_b32 s20, s19, s26
	s_cmpk_lt_i32 s54, 0xfe
	s_cselect_b32 s21, s11, s20
	s_cselect_b32 s20, s7, s13
	s_or_b32 s52, s8, 22
	s_ashr_i32 s53, s52, 31
	global_load_dword v166, v[2:3], off offset:512 nt
	global_load_dword v164, v[2:3], off offset:768 nt
	v_lshl_add_u64 v[2:3], s[18:19], 0, v[24:25]
	s_lshl_b64 s[18:19], s[52:53], 10
	s_add_u32 s18, s4, s18
	s_addc_u32 s19, s5, s19
	s_add_u32 s7, s18, 0x800
	s_addc_u32 s11, s19, 0
	global_load_dword v161, v[2:3], off nt
	global_load_dword v159, v[2:3], off offset:256 nt
	v_lshl_add_u64 v[2:3], s[20:21], 0, v[24:25]
	s_and_b64 s[20:21], s[14:15], exec
	s_cselect_b32 s13, s18, s16
	s_cselect_b32 s20, s19, s17
	s_cmpk_lt_i32 s52, 0xfe
	s_cselect_b32 s21, s11, s20
	s_cselect_b32 s20, s7, s13
	s_or_b32 s50, s8, 23
	s_ashr_i32 s51, s50, 31
	global_load_dword v162, v[2:3], off offset:512 nt
	global_load_dword v160, v[2:3], off offset:768 nt
	v_lshl_add_u64 v[2:3], s[18:19], 0, v[24:25]
	s_lshl_b64 s[18:19], s[50:51], 10
	s_add_u32 s18, s4, s18
	s_addc_u32 s19, s5, s19
	s_add_u32 s7, s18, 0x800
	s_addc_u32 s11, s19, 0
	global_load_dword v157, v[2:3], off nt
	global_load_dword v155, v[2:3], off offset:256 nt
	v_lshl_add_u64 v[2:3], s[20:21], 0, v[24:25]
	s_and_b64 s[20:21], s[14:15], exec
	s_cselect_b32 s13, s18, s9
	s_cselect_b32 s20, s19, s26
	s_cmpk_lt_i32 s50, 0xfe
	s_cselect_b32 s21, s11, s20
	s_cselect_b32 s20, s7, s13
	s_or_b32 s48, s8, 24
	s_ashr_i32 s49, s48, 31
	global_load_dword v158, v[2:3], off offset:512 nt
	global_load_dword v156, v[2:3], off offset:768 nt
	v_lshl_add_u64 v[2:3], s[18:19], 0, v[24:25]
	s_lshl_b64 s[18:19], s[48:49], 10
	s_add_u32 s18, s4, s18
	s_addc_u32 s19, s5, s19
	s_add_u32 s7, s18, 0x800
	s_addc_u32 s11, s19, 0
	global_load_dword v153, v[2:3], off nt
	global_load_dword v151, v[2:3], off offset:256 nt
	v_lshl_add_u64 v[2:3], s[20:21], 0, v[24:25]
	s_and_b64 s[20:21], s[14:15], exec
	s_cselect_b32 s13, s18, s16
	s_cselect_b32 s20, s19, s17
	s_cmpk_lt_i32 s48, 0xfe
	s_cselect_b32 s21, s11, s20
	s_cselect_b32 s20, s7, s13
	s_or_b32 s46, s8, 25
	s_ashr_i32 s47, s46, 31
	global_load_dword v154, v[2:3], off offset:512 nt
	global_load_dword v152, v[2:3], off offset:768 nt
	v_lshl_add_u64 v[2:3], s[18:19], 0, v[24:25]
	s_lshl_b64 s[18:19], s[46:47], 10
	s_add_u32 s18, s4, s18
	s_addc_u32 s19, s5, s19
	s_add_u32 s7, s18, 0x800
	s_addc_u32 s11, s19, 0
	global_load_dword v149, v[2:3], off nt
	global_load_dword v147, v[2:3], off offset:256 nt
	v_lshl_add_u64 v[2:3], s[20:21], 0, v[24:25]
	s_and_b64 s[20:21], s[14:15], exec
	s_cselect_b32 s13, s18, s9
	s_cselect_b32 s20, s19, s26
	s_cmpk_lt_i32 s46, 0xfe
	s_cselect_b32 s21, s11, s20
	s_cselect_b32 s20, s7, s13
	s_or_b32 s44, s8, 26
	s_ashr_i32 s45, s44, 31
	global_load_dword v150, v[2:3], off offset:512 nt
	global_load_dword v148, v[2:3], off offset:768 nt
	v_lshl_add_u64 v[2:3], s[18:19], 0, v[24:25]
	s_lshl_b64 s[18:19], s[44:45], 10
	s_add_u32 s18, s4, s18
	s_addc_u32 s19, s5, s19
	s_add_u32 s7, s18, 0x800
	s_addc_u32 s11, s19, 0
	global_load_dword v145, v[2:3], off nt
	global_load_dword v143, v[2:3], off offset:256 nt
	v_lshl_add_u64 v[2:3], s[20:21], 0, v[24:25]
	s_and_b64 s[20:21], s[14:15], exec
	s_cselect_b32 s13, s18, s16
	s_cselect_b32 s20, s19, s17
	s_cmpk_lt_i32 s44, 0xfe
	s_cselect_b32 s21, s11, s20
	s_cselect_b32 s20, s7, s13
	s_or_b32 s24, s8, 27
	s_ashr_i32 s25, s24, 31
	global_load_dword v146, v[2:3], off offset:512 nt
	global_load_dword v144, v[2:3], off offset:768 nt
	v_lshl_add_u64 v[2:3], s[18:19], 0, v[24:25]
	s_lshl_b64 s[18:19], s[24:25], 10
	s_add_u32 s18, s4, s18
	s_addc_u32 s19, s5, s19
	s_add_u32 s7, s18, 0x800
	s_addc_u32 s11, s19, 0
	global_load_dword v141, v[2:3], off nt
	global_load_dword v139, v[2:3], off offset:256 nt
	v_lshl_add_u64 v[2:3], s[20:21], 0, v[24:25]
	s_and_b64 s[20:21], s[14:15], exec
	s_cselect_b32 s13, s18, s9
	s_cselect_b32 s20, s19, s26
	s_cmpk_lt_i32 s24, 0xfe
	s_cselect_b32 s21, s11, s20
	s_cselect_b32 s20, s7, s13
	s_or_b32 s22, s8, 28
	s_ashr_i32 s23, s22, 31
	global_load_dword v142, v[2:3], off offset:512 nt
	global_load_dword v140, v[2:3], off offset:768 nt
	v_lshl_add_u64 v[2:3], s[18:19], 0, v[24:25]
	s_lshl_b64 s[18:19], s[22:23], 10
	s_add_u32 s18, s4, s18
	s_addc_u32 s19, s5, s19
	s_add_u32 s7, s18, 0x800
	s_addc_u32 s11, s19, 0
	global_load_dword v137, v[2:3], off nt
	global_load_dword v135, v[2:3], off offset:256 nt
	v_lshl_add_u64 v[2:3], s[20:21], 0, v[24:25]
	s_and_b64 s[20:21], s[14:15], exec
	s_cselect_b32 s13, s18, s16
	s_cselect_b32 s20, s19, s17
	s_cmpk_lt_i32 s22, 0xfe
	global_load_dword v138, v[2:3], off offset:512 nt
	global_load_dword v136, v[2:3], off offset:768 nt
	s_cselect_b32 s21, s11, s20
	s_cselect_b32 s20, s7, s13
	v_lshl_add_u64 v[2:3], s[18:19], 0, v[24:25]
	global_load_dword v129, v[2:3], off nt
	global_load_dword v127, v[2:3], off offset:256 nt
	v_lshl_add_u64 v[2:3], s[20:21], 0, v[24:25]
	s_or_b32 s20, s8, 29
	s_ashr_i32 s21, s20, 31
	s_lshl_b64 s[18:19], s[20:21], 10
	s_add_u32 s18, s4, s18
	s_addc_u32 s19, s5, s19
	s_add_u32 s7, s18, 0x800
	s_addc_u32 s11, s19, 0
	s_and_b64 s[28:29], s[14:15], exec
	s_cselect_b32 s13, s18, s9
	s_cselect_b32 s21, s19, s26
	s_cmpk_lt_i32 s20, 0xfe
	global_load_dword v134, v[2:3], off offset:512 nt
	global_load_dword v128, v[2:3], off offset:768 nt
	s_cselect_b32 s29, s11, s21
	s_cselect_b32 s28, s7, s13
	v_lshl_add_u64 v[2:3], s[18:19], 0, v[24:25]
	s_or_b32 s18, s8, 30
	s_ashr_i32 s19, s18, 31
	global_load_dword v125, v[2:3], off nt
	global_load_dword v123, v[2:3], off offset:256 nt
	v_lshl_add_u64 v[2:3], s[28:29], 0, v[24:25]
	s_lshl_b64 s[28:29], s[18:19], 10
	s_add_u32 s28, s4, s28
	s_addc_u32 s29, s5, s29
	s_add_u32 s7, s28, 0x800
	s_addc_u32 s11, s29, 0
	s_and_b64 s[30:31], s[14:15], exec
	s_cselect_b32 s13, s28, s16
	s_cselect_b32 s16, s29, s17
	s_cmpk_lt_i32 s18, 0xfe
	global_load_dword v126, v[2:3], off offset:512 nt
	global_load_dword v124, v[2:3], off offset:768 nt
	s_cselect_b32 s17, s11, s16
	s_cselect_b32 s16, s7, s13
	v_lshl_add_u64 v[2:3], s[28:29], 0, v[24:25]
	global_load_dword v121, v[2:3], off nt
	global_load_dword v119, v[2:3], off offset:256 nt
	v_lshl_add_u64 v[2:3], s[16:17], 0, v[24:25]
	s_or_b32 s16, s8, 31
	s_ashr_i32 s17, s16, 31
	s_lshl_b64 s[28:29], s[16:17], 10
	s_add_u32 s4, s4, s28
	s_addc_u32 s5, s5, s29
	s_add_u32 s7, s4, 0x800
	s_addc_u32 s11, s5, 0
	s_and_b64 s[14:15], s[14:15], exec
	s_cselect_b32 s9, s4, s9
	s_cselect_b32 s13, s5, s26
	s_cmpk_lt_i32 s16, 0xfe
	global_load_dword v122, v[2:3], off offset:512 nt
	global_load_dword v120, v[2:3], off offset:768 nt
	s_cselect_b32 s15, s11, s13
	s_cselect_b32 s14, s7, s9
	v_lshl_add_u64 v[2:3], s[4:5], 0, v[24:25]
	global_load_dword v117, v[2:3], off nt
	global_load_dword v115, v[2:3], off offset:256 nt
	v_lshl_add_u64 v[2:3], s[14:15], 0, v[24:25]
	global_load_dword v118, v[2:3], off offset:512 nt
	global_load_dword v116, v[2:3], off offset:768 nt
	s_movk_i32 s4, 0x2000
	s_mov_b64 s[14:15], 0x800
	v_cmp_gt_i32_e32 vcc, s4, v130
	v_lshl_add_u32 v4, v130, 2, s94
	s_waitcnt vmcnt(0) lgkmcnt(0)
	s_barrier
	s_and_saveexec_b64 s[72:73], vcc
	s_cbranch_execz .LBB0_4322
	s_and_b32 s4, s40, 1
	s_lshl_b32 s4, s4, 15
	v_mov_b32_e32 v2, s4
	v_mov_b32_e32 v3, v133
	v_ashrrev_i32_e32 v131, 31, v130
	v_lshl_add_u64 v[2:3], v[130:131], 2, v[2:3]
	s_mov_b64 s[4:5], 0x10000
	v_add_u32_e32 v5, 0xfffffe00, v130
	v_lshl_add_u64 v[2:3], v[2:3], 0, s[4:5]
	s_mov_b64 s[90:91], 0
	s_movk_i32 s4, 0x1dff
	v_mov_b32_e32 v6, v4
.LBB0_4321:
	v_mov_b64_e32 v[8:9], s[0:1]
	global_load_dwordx2 v[8:9], v[8:9], off offset:144 sc0 sc1
	s_waitcnt vmcnt(0)
	v_add_u32_e32 v5, 0x200, v5
	v_cmp_lt_i32_e32 vcc, s4, v5
	s_or_b64 s[90:91], vcc, s[90:91]
	s_waitcnt lgkmcnt(0)
	v_lshl_add_u64 v[8:9], v[8:9], 0, v[2:3]
	global_load_dword v7, v[8:9], off nt
	v_lshl_add_u64 v[2:3], v[2:3], 0, s[14:15]
	s_waitcnt vmcnt(0)
	ds_write_b32 v6, v7
	v_add_u32_e32 v6, 0x800, v6
	s_andn2_b64 exec, exec, s[90:91]
	s_cbranch_execnz .LBB0_4321
.LBB0_4322:
	s_or_b64 exec, exec, s[72:73]
	s_movk_i32 s4, 0x7f
	s_and_b32 s26, s40, 1
	v_cmp_lt_i32_e32 vcc, s4, v130
	s_and_saveexec_b64 s[14:15], vcc
	s_xor_b64 s[14:15], exec, s[14:15]
	s_lshl_b32 s4, s26, 7
	s_or_saveexec_b64 s[14:15], s[14:15]
	v_mov_b32_e32 v59, s4
	s_xor_b64 exec, exec, s[14:15]
	s_cbranch_execz .LBB0_4328
	v_mov_b64_e32 v[2:3], s[0:1]
	global_load_dwordx2 v[6:7], v[2:3], off offset:136 sc0 sc1
	s_waitcnt vmcnt(0)
	s_lshl_b32 s4, s26, 7
	v_add_u32_e32 v2, s4, v130
	v_add_u32_e32 v8, 0x100, v2
	v_ashrrev_i32_e32 v9, 31, v8
	s_add_u32 s72, s38, 0x6200000
	s_addc_u32 s73, s39, 0
	s_mov_b32 s5, 0
	s_waitcnt lgkmcnt(0)
	v_lshl_add_u64 v[6:7], v[8:9], 2, v[6:7]
	global_load_dword v3, v[6:7], off nt
.LBB0_4326:
	v_add_u32_e32 v5, s5, v2
	v_add_u32_e32 v6, 0x100, v5
	v_add_u32_e32 v8, 0x300, v5
	v_add_u32_e32 v10, 0x500, v5
	v_add_u32_e32 v12, 0x700, v5
	v_add_u32_e32 v14, 0x900, v5
	v_add_u32_e32 v16, 0xb00, v5
	v_add_u32_e32 v18, 0xd00, v5
	v_add_u32_e32 v26, 0xf00, v5
	v_ashrrev_i32_e32 v7, 31, v6
	v_ashrrev_i32_e32 v9, 31, v8
	v_ashrrev_i32_e32 v11, 31, v10
	v_ashrrev_i32_e32 v13, 31, v12
	v_ashrrev_i32_e32 v15, 31, v14
	v_ashrrev_i32_e32 v17, 31, v16
	v_ashrrev_i32_e32 v19, 31, v18
	v_ashrrev_i32_e32 v27, 31, v26
	v_lshl_add_u64 v[6:7], v[6:7], 2, s[72:73]
	v_lshl_add_u64 v[8:9], v[8:9], 2, s[72:73]
	v_lshl_add_u64 v[10:11], v[10:11], 2, s[72:73]
	v_lshl_add_u64 v[12:13], v[12:13], 2, s[72:73]
	v_lshl_add_u64 v[14:15], v[14:15], 2, s[72:73]
	v_lshl_add_u64 v[16:17], v[16:17], 2, s[72:73]
	v_lshl_add_u64 v[18:19], v[18:19], 2, s[72:73]
	v_lshl_add_u64 v[26:27], v[26:27], 2, s[72:73]
	global_load_dword v5, v[6:7], off nt
	s_nop 0
	global_load_dword v6, v[8:9], off nt
	global_load_dword v7, v[10:11], off nt
	s_nop 0
	global_load_dword v8, v[12:13], off nt
	global_load_dword v9, v[14:15], off nt
	global_load_dword v10, v[16:17], off nt
	global_load_dword v11, v[18:19], off nt
	s_nop 0
	global_load_dword v12, v[26:27], off nt
	s_addk_i32 s5, 0x1000
	s_cmpk_lg_i32 s5, 0x4000
	s_waitcnt vmcnt(0) lgkmcnt(0)
	v_add_f32_e32 v3, v3, v5
	v_add_f32_e32 v3, v3, v6
	v_add_f32_e32 v3, v3, v7
	v_add_f32_e32 v3, v3, v8
	v_add_f32_e32 v3, v3, v9
	v_add_f32_e32 v3, v3, v10
	v_add_f32_e32 v3, v3, v11
	v_add_f32_e32 v3, v3, v12
	s_cbranch_scc1 .LBB0_4326
	v_mov_b32_e32 v59, s4
	ds_write_b32 v4, v3 offset:32768

.LBB0_4648:
	s_bfe_u32 s6, s40, 0x30001
	s_cmp_eq_u32 s6, s96
	s_cselect_b64 s[12:13], -1, 0
	s_cmp_lg_u32 s6, s96
	s_cbranch_scc1 .LBB0_4650
	s_ashr_i32 s6, s40, 4
	s_lshr_b32 s7, s40, 1
	s_and_b32 s14, s6, -2
	s_or_b32 s6, s14, s26
	s_lshl_b32 s7, s7, 4
	s_addk_i32 s6, 0x100
	s_and_b32 s8, s7, 0xf0
	s_cmpk_gt_i32 s14, 0xff0e
	s_cselect_b64 s[14:15], -1, 0
	s_and_b32 s7, s40, 0x60
	s_cmpk_eq_i32 s7, 0x60
	s_cselect_b64 s[16:17], -1, 0
	s_ashr_i32 s7, s6, 31
	s_or_b64 s[14:15], s[16:17], s[14:15]
	s_lshl_b64 s[16:17], s[6:7], 18
	s_add_u32 s2, s2, s16
	s_addc_u32 s3, s3, s17
	s_add_u32 s19, s2, 0x80000
	s_addc_u32 s20, s3, 0
	s_lshl_b32 s7, s8, 10
	s_add_u32 s16, s2, s7
	s_addc_u32 s17, s3, 0
	s_add_u32 s7, s2, 0x80400
	s_addc_u32 s18, s3, 0
	s_add_u32 s22, s16, 0x1000
	s_addc_u32 s23, s17, 0
	s_add_u32 s24, s16, 0x1400
	s_addc_u32 s25, s17, 0
	v_add_u32_e32 v2, 64, v132
	v_mov_b32_e32 v3, 0
	s_add_u32 s26, s16, 0x1800
	v_lshl_add_u64 v[4:5], s[16:17], 0, v[24:25]
	v_lshl_add_u64 v[6:7], s[22:23], 0, v[24:25]
	s_addc_u32 s27, s17, 0
	v_lshlrev_b64 v[2:3], 2, v[2:3]
	global_load_dword v20, v[4:5], off nt
	global_load_dword v21, v[4:5], off offset:256 nt
	global_load_dword v22, v[4:5], off offset:2560
	global_load_dword v23, v[4:5], off offset:2816
	global_load_dword v107, v[4:5], off offset:1024
	global_load_dword v105, v[4:5], off offset:1280
	global_load_dword v103, v[4:5], off offset:2048
	global_load_dword v100, v[4:5], off offset:2304
	v_lshl_add_u64 v[8:9], s[24:25], 0, v[24:25]
	global_load_dword v108, v[4:5], off offset:3584
	global_load_dword v106, v[4:5], off offset:3840
	global_load_dword v104, v[6:7], off offset:512 nt
	global_load_dword v102, v[6:7], off offset:768 nt
	global_load_dword v98, v[4:5], off offset:3072
	global_load_dword v90, v[8:9], off nt
	global_load_dword v94, v[6:7], off nt
	global_load_dword v97, v[4:5], off offset:3328
	v_lshl_add_u64 v[6:7], s[22:23], 0, v[2:3]
	s_add_u32 s22, s16, 0x1c00
	s_addc_u32 s23, s17, 0
	v_lshl_add_u64 v[12:13], s[24:25], 0, v[2:3]
	s_add_u32 s24, s16, 0x2000
	s_addc_u32 s25, s17, 0
	v_lshl_add_u64 v[10:11], s[26:27], 0, v[24:25]
	v_lshl_add_u64 v[14:15], s[22:23], 0, v[24:25]
	global_load_dword v101, v[8:9], off offset:512 nt
	global_load_dword v99, v[8:9], off offset:768 nt
	global_load_dword v93, v[6:7], off nt
	global_load_dword v96, v[10:11], off offset:512 nt
	global_load_dword v95, v[10:11], off offset:768 nt
	global_load_dword v89, v[12:13], off nt
	global_load_dword v82, v[14:15], off nt
	global_load_dword v87, v[10:11], off nt
	v_lshl_add_u64 v[6:7], s[26:27], 0, v[2:3]
	s_add_u32 s26, s16, 0x2400
	s_addc_u32 s27, s17, 0
	v_lshl_add_u64 v[10:11], s[22:23], 0, v[2:3]
	s_add_u32 s22, s16, 0x2800
	s_addc_u32 s23, s17, 0
	v_lshl_add_u64 v[8:9], s[24:25], 0, v[24:25]
	v_lshl_add_u64 v[12:13], s[26:27], 0, v[24:25]
	global_load_dword v92, v[14:15], off offset:512 nt
	global_load_dword v91, v[14:15], off offset:768 nt
	global_load_dword v85, v[6:7], off nt
	global_load_dword v88, v[8:9], off offset:512 nt
	global_load_dword v86, v[8:9], off offset:768 nt
	global_load_dword v81, v[10:11], off nt
	global_load_dword v73, v[12:13], off nt
	global_load_dword v79, v[8:9], off nt
	v_lshl_add_u64 v[6:7], s[24:25], 0, v[2:3]
	s_add_u32 s24, s16, 0x2c00
	s_addc_u32 s25, s17, 0
	v_lshl_add_u64 v[10:11], s[26:27], 0, v[2:3]
	s_add_u32 s26, s16, 0x3000
	s_addc_u32 s27, s17, 0
	v_lshl_add_u64 v[8:9], s[22:23], 0, v[24:25]
	v_lshl_add_u64 v[14:15], s[24:25], 0, v[24:25]
	global_load_dword v84, v[12:13], off offset:512 nt
	global_load_dword v83, v[12:13], off offset:768 nt
	global_load_dword v77, v[6:7], off nt
	global_load_dword v80, v[8:9], off offset:512 nt
	global_load_dword v78, v[8:9], off offset:768 nt
	global_load_dword v72, v[10:11], off nt
	global_load_dword v65, v[14:15], off nt
	global_load_dword v70, v[8:9], off nt
	v_lshl_add_u64 v[6:7], s[22:23], 0, v[2:3]
	s_add_u32 s22, s16, 0x3400
	s_addc_u32 s23, s17, 0
	v_lshl_add_u64 v[10:11], s[24:25], 0, v[2:3]
	s_add_u32 s24, s16, 0x3800
	s_addc_u32 s25, s17, 0
	v_lshl_add_u64 v[8:9], s[26:27], 0, v[24:25]
	v_lshl_add_u64 v[12:13], s[22:23], 0, v[24:25]
	global_load_dword v75, v[14:15], off offset:512 nt
	global_load_dword v74, v[14:15], off offset:768 nt
	global_load_dword v68, v[6:7], off nt
	global_load_dword v71, v[8:9], off offset:512 nt
	global_load_dword v69, v[8:9], off offset:768 nt
	global_load_dword v64, v[10:11], off nt
	global_load_dword v56, v[12:13], off nt
	global_load_dword v62, v[8:9], off nt
	v_lshl_add_u64 v[10:11], s[22:23], 0, v[2:3]
	s_mov_b64 s[22:23], 0x3c00
	s_add_u32 s21, s16, 0x4000
	v_lshl_add_u64 v[14:15], v[4:5], 0, s[22:23]
	s_addc_u32 s22, s17, 0
	s_and_b64 s[16:17], s[14:15], exec
	s_cselect_b32 s16, s24, s19
	s_cselect_b32 s17, s25, s20
	s_cmpk_eq_i32 s8, 0xf0
	v_lshl_add_u64 v[6:7], s[26:27], 0, v[2:3]
	s_cselect_b32 s17, s17, s22
	s_cselect_b32 s16, s16, s21
	v_lshl_add_u64 v[2:3], s[24:25], 0, v[2:3]
	v_lshl_add_u64 v[8:9], s[24:25], 0, v[24:25]
	global_load_dword v67, v[12:13], off offset:512 nt
	global_load_dword v66, v[12:13], off offset:768 nt
	global_load_dword v60, v[6:7], off nt
	global_load_dword v63, v[8:9], off offset:512 nt
	global_load_dword v61, v[8:9], off offset:768 nt
	global_load_dword v55, v[10:11], off nt
	global_load_dword v58, v[14:15], off offset:512 nt
	global_load_dword v53, v[8:9], off nt
	global_load_dword v57, v[14:15], off offset:768 nt
	global_load_dword v51, v[2:3], off nt
	v_lshl_add_u64 v[2:3], s[16:17], 0, v[24:25]
	s_or_b32 s16, s8, 15
	s_lshl_b32 s17, s16, 10
	s_add_u32 s2, s2, s17
	s_addc_u32 s3, s3, 0
	s_add_u32 s17, s2, 0x800
	s_addc_u32 s19, s3, 0
	s_and_b64 s[14:15], s[14:15], exec
	global_load_dword v54, v[2:3], off offset:512 nt
	global_load_dword v52, v[2:3], off offset:768 nt
	s_cselect_b32 s7, s2, s7
	s_cselect_b32 s14, s3, s18
	s_cmpk_lt_u32 s16, 0xfe
	v_add_co_u32_e32 v2, vcc, 0x3000, v4
	s_cselect_b32 s15, s19, s14
	s_cselect_b32 s14, s17, s7
	v_addc_co_u32_e32 v3, vcc, 0, v5, vcc
	v_lshl_add_u64 v[4:5], s[2:3], 0, v[24:25]
	global_load_dword v49, v[2:3], off offset:3072
	global_load_dword v1, v[4:5], off offset:256 nt
	v_lshl_add_u64 v[2:3], s[14:15], 0, v[24:25]
	global_load_dword v50, v[2:3], off offset:512 nt
	global_load_dword v48, v[2:3], off offset:768 nt
	s_andn2_b64 vcc, exec, s[12:13]
	s_cbranch_vccz .LBB0_4651
	s_branch .LBB0_4811
